# k24 + two more s_setprio 0/1 windows per M phase (after MFMA 8 and 24) so the load half gets more issue opportunities
# baseline (speedup 1.0000x reference)
.LBB0_444:
	s_add_u32 s48, s46, 0x20080
	s_addc_u32 s49, s47, 0
	s_add_u32 s25, s50, 0x100
	s_addc_u32 s64, s51, 0
	s_mov_b32 s65, -2
	s_add_u32 s46, s48, 0xfffe0080
	s_addc_u32 s47, s49, -1
	s_add_i32 s84, 0, 0x10000
	s_cmp_eq_u32 s65, 4
	s_cselect_b32 s47, s15, s47
	s_cselect_b32 s46, s14, s46
	v_add_u32_e32 v0, s84, v147
	s_cselect_b32 s51, s17, s64
	s_cselect_b32 s50, s16, s25
	s_add_i32 s86, 0, 0x14000
	ds_read_b128 v[150:153], v0
	ds_read_b128 v[154:157], v0 offset:1024
	ds_read_b128 v[158:161], v0 offset:2048
	ds_read_b128 v[162:165], v0 offset:3072
	ds_read_b128 v[166:169], v0 offset:16384
	ds_read_b128 v[170:173], v0 offset:17408
	ds_read_b128 v[174:177], v0 offset:18432
	ds_read_b128 v[178:181], v0 offset:19456
	ds_read_b128 v[182:185], v148
	ds_read_b128 v[186:189], v148 offset:1024
	ds_read_b128 v[190:193], v148 offset:2048
	ds_read_b128 v[194:197], v148 offset:3072
	ds_read_b128 v[198:201], v148 offset:4096
	ds_read_b128 v[202:205], v148 offset:5120
	ds_read_b128 v[206:209], v148 offset:6144
	ds_read_b128 v[210:213], v148 offset:7168
	s_add_i32 m0, s59, 0xc000
	s_nop 0
	global_load_lds_dwordx4 v132, s[48:49]
	s_add_i32 m0, s59, 0xe000
	s_nop 0
	global_load_lds_dwordx4 v133, s[48:49]
	s_waitcnt vmcnt(8)
	s_waitcnt lgkmcnt(0)
	s_barrier
	s_setprio 1
	s_waitcnt lgkmcnt(0)
	v_mfma_i32_16x16x64_i8 v[126:129], v[150:153], v[182:185], 0
	v_mfma_i32_16x16x64_i8 v[122:125], v[158:161], v[182:185], 0
	v_mfma_i32_16x16x64_i8 v[110:113], v[150:153], v[190:193], 0
	v_mfma_i32_16x16x64_i8 v[106:109], v[158:161], v[190:193], 0
	v_mfma_i32_16x16x64_i8 v[94:97], v[150:153], v[198:201], 0
	v_mfma_i32_16x16x64_i8 v[90:93], v[158:161], v[198:201], 0
	v_mfma_i32_16x16x64_i8 v[78:81], v[150:153], v[206:209], 0
	v_mfma_i32_16x16x64_i8 v[74:77], v[158:161], v[206:209], 0
	s_setprio 0
	s_setprio 1
	v_mfma_i32_16x16x64_i8 v[126:129], v[154:157], v[186:189], v[126:129]
	v_mfma_i32_16x16x64_i8 v[122:125], v[162:165], v[186:189], v[122:125]
	v_mfma_i32_16x16x64_i8 v[110:113], v[154:157], v[194:197], v[110:113]
	v_mfma_i32_16x16x64_i8 v[106:109], v[162:165], v[194:197], v[106:109]
	v_mfma_i32_16x16x64_i8 v[94:97], v[154:157], v[202:205], v[94:97]
	v_mfma_i32_16x16x64_i8 v[90:93], v[162:165], v[202:205], v[90:93]
	v_mfma_i32_16x16x64_i8 v[78:81], v[154:157], v[210:213], v[78:81]
	v_mfma_i32_16x16x64_i8 v[74:77], v[162:165], v[210:213], v[74:77]
	s_setprio 0
	s_setprio 1
	v_mfma_i32_16x16x64_i8 v[118:121], v[166:169], v[182:185], 0
	v_mfma_i32_16x16x64_i8 v[114:117], v[174:177], v[182:185], 0
	v_mfma_i32_16x16x64_i8 v[102:105], v[166:169], v[190:193], 0
	v_mfma_i32_16x16x64_i8 v[98:101], v[174:177], v[190:193], 0
	v_mfma_i32_16x16x64_i8 v[86:89], v[166:169], v[198:201], 0
	v_mfma_i32_16x16x64_i8 v[82:85], v[174:177], v[198:201], 0
	v_mfma_i32_16x16x64_i8 v[70:73], v[166:169], v[206:209], 0
	v_mfma_i32_16x16x64_i8 v[66:69], v[174:177], v[206:209], 0
	s_setprio 0
	s_setprio 1
	v_mfma_i32_16x16x64_i8 v[118:121], v[170:173], v[186:189], v[118:121]
	v_mfma_i32_16x16x64_i8 v[114:117], v[178:181], v[186:189], v[114:117]
	v_mfma_i32_16x16x64_i8 v[102:105], v[170:173], v[194:197], v[102:105]
	v_mfma_i32_16x16x64_i8 v[98:101], v[178:181], v[194:197], v[98:101]
	v_mfma_i32_16x16x64_i8 v[86:89], v[170:173], v[202:205], v[86:89]
	v_mfma_i32_16x16x64_i8 v[82:85], v[178:181], v[202:205], v[82:85]
	v_mfma_i32_16x16x64_i8 v[70:73], v[170:173], v[210:213], v[70:73]
	v_mfma_i32_16x16x64_i8 v[66:69], v[178:181], v[210:213], v[66:69]
	s_setprio 0
	s_barrier
	s_add_i32 s84, s84, s40
	ds_read_b128 v[182:185], v148 offset:16384
	ds_read_b128 v[186:189], v148 offset:17408
	ds_read_b128 v[190:193], v148 offset:18432
	ds_read_b128 v[194:197], v148 offset:19456
	ds_read_b128 v[198:201], v148 offset:20480
	ds_read_b128 v[202:205], v148 offset:21504
	ds_read_b128 v[206:209], v148 offset:22528
	ds_read_b128 v[210:213], v148 offset:23552
	s_mov_b32 m0, s84
	s_nop 0
	global_load_lds_dwordx4 v143, s[50:51]
	s_add_i32 m0, s84, 0x2000
	s_add_u32 s84, s50, 0x20000
	global_load_lds_dwordx4 v144, s[50:51]
	s_addc_u32 s85, s51, 0
	s_add_i32 s86, s86, s40
	s_mov_b32 m0, s86
	s_nop 0
	global_load_lds_dwordx4 v143, s[84:85]
	s_add_i32 m0, s86, 0x2000
	s_nop 0
	global_load_lds_dwordx4 v144, s[84:85]
	s_mov_b32 m0, s59
	s_nop 0
	global_load_lds_dwordx4 v132, s[46:47]
	s_mov_b32 m0, s60
	s_nop 0
	global_load_lds_dwordx4 v133, s[46:47]
	s_waitcnt vmcnt(8)
	s_waitcnt lgkmcnt(0)
	s_barrier
	s_setprio 1
	s_waitcnt lgkmcnt(0)
	v_mfma_i32_16x16x64_i8 v[62:65], v[150:153], v[182:185], 0
	v_mfma_i32_16x16x64_i8 v[58:61], v[158:161], v[182:185], 0
	v_mfma_i32_16x16x64_i8 v[46:49], v[150:153], v[190:193], 0
	v_mfma_i32_16x16x64_i8 v[42:45], v[158:161], v[190:193], 0
	v_mfma_i32_16x16x64_i8 v[30:33], v[150:153], v[198:201], 0
	v_mfma_i32_16x16x64_i8 v[26:29], v[158:161], v[198:201], 0
	v_mfma_i32_16x16x64_i8 v[14:17], v[150:153], v[206:209], 0
	v_mfma_i32_16x16x64_i8 v[10:13], v[158:161], v[206:209], 0
	s_setprio 0
	s_setprio 1
	v_mfma_i32_16x16x64_i8 v[62:65], v[154:157], v[186:189], v[62:65]
	v_mfma_i32_16x16x64_i8 v[58:61], v[162:165], v[186:189], v[58:61]
	v_mfma_i32_16x16x64_i8 v[46:49], v[154:157], v[194:197], v[46:49]
	v_mfma_i32_16x16x64_i8 v[42:45], v[162:165], v[194:197], v[42:45]
	v_mfma_i32_16x16x64_i8 v[30:33], v[154:157], v[202:205], v[30:33]
	v_mfma_i32_16x16x64_i8 v[26:29], v[162:165], v[202:205], v[26:29]
	v_mfma_i32_16x16x64_i8 v[14:17], v[154:157], v[210:213], v[14:17]
	v_mfma_i32_16x16x64_i8 v[10:13], v[162:165], v[210:213], v[10:13]
	s_setprio 0
	s_setprio 1
	v_mfma_i32_16x16x64_i8 v[54:57], v[166:169], v[182:185], 0
	v_mfma_i32_16x16x64_i8 v[50:53], v[174:177], v[182:185], 0
	v_mfma_i32_16x16x64_i8 v[38:41], v[166:169], v[190:193], 0
	v_mfma_i32_16x16x64_i8 v[34:37], v[174:177], v[190:193], 0
	v_mfma_i32_16x16x64_i8 v[22:25], v[166:169], v[198:201], 0
	v_mfma_i32_16x16x64_i8 v[18:21], v[174:177], v[198:201], 0
	v_mfma_i32_16x16x64_i8 v[6:9], v[166:169], v[206:209], 0
	v_mfma_i32_16x16x64_i8 v[2:5], v[174:177], v[206:209], 0
	s_setprio 0
	s_setprio 1
	v_mfma_i32_16x16x64_i8 v[54:57], v[170:173], v[186:189], v[54:57]
	v_mfma_i32_16x16x64_i8 v[50:53], v[178:181], v[186:189], v[50:53]
	v_mfma_i32_16x16x64_i8 v[38:41], v[170:173], v[194:197], v[38:41]
	v_mfma_i32_16x16x64_i8 v[34:37], v[178:181], v[194:197], v[34:37]
	v_mfma_i32_16x16x64_i8 v[22:25], v[170:173], v[202:205], v[22:25]
	v_mfma_i32_16x16x64_i8 v[18:21], v[178:181], v[202:205], v[18:21]
	v_mfma_i32_16x16x64_i8 v[6:9], v[170:173], v[210:213], v[6:9]
	v_mfma_i32_16x16x64_i8 v[2:5], v[178:181], v[210:213], v[2:5]
	s_setprio 0
	s_barrier
	s_add_i32 s86, 0, 0x18000
	s_add_i32 s87, 0, 0x1c000
	ds_read_b128 v[150:153], v0 offset:32768
	ds_read_b128 v[154:157], v0 offset:33792
	ds_read_b128 v[158:161], v0 offset:34816
	ds_read_b128 v[162:165], v0 offset:35840
	ds_read_b128 v[166:169], v0 offset:49152
	ds_read_b128 v[170:173], v0 offset:50176
	ds_read_b128 v[174:177], v0 offset:51200
	ds_read_b128 v[178:181], v0 offset:52224
	s_add_u32 s84, s46, 0x20000
	s_mov_b32 m0, s61
	ds_read_b128 v[182:185], v148 offset:32768
	ds_read_b128 v[186:189], v148 offset:33792
	ds_read_b128 v[190:193], v148 offset:34816
	ds_read_b128 v[194:197], v148 offset:35840
	ds_read_b128 v[198:201], v148 offset:36864
	ds_read_b128 v[202:205], v148 offset:37888
	ds_read_b128 v[206:209], v148 offset:38912
	ds_read_b128 v[210:213], v148 offset:39936
	s_addc_u32 s85, s47, 0
	s_nop 0
	global_load_lds_dwordx4 v132, s[84:85]
	s_mov_b32 m0, s66
	s_nop 0
	global_load_lds_dwordx4 v133, s[84:85]
	s_waitcnt vmcnt(8)
	s_waitcnt lgkmcnt(0)
	s_barrier
	s_setprio 1
	s_waitcnt lgkmcnt(0)
	v_mfma_i32_16x16x64_i8 v[126:129], v[150:153], v[182:185], v[126:129]
	v_mfma_i32_16x16x64_i8 v[122:125], v[158:161], v[182:185], v[122:125]
	v_mfma_i32_16x16x64_i8 v[110:113], v[150:153], v[190:193], v[110:113]
	v_mfma_i32_16x16x64_i8 v[106:109], v[158:161], v[190:193], v[106:109]
	v_mfma_i32_16x16x64_i8 v[94:97], v[150:153], v[198:201], v[94:97]
	v_mfma_i32_16x16x64_i8 v[90:93], v[158:161], v[198:201], v[90:93]
	v_mfma_i32_16x16x64_i8 v[78:81], v[150:153], v[206:209], v[78:81]
	v_mfma_i32_16x16x64_i8 v[74:77], v[158:161], v[206:209], v[74:77]
	s_setprio 0
	s_setprio 1
	v_mfma_i32_16x16x64_i8 v[126:129], v[154:157], v[186:189], v[126:129]
	v_mfma_i32_16x16x64_i8 v[122:125], v[162:165], v[186:189], v[122:125]
	v_mfma_i32_16x16x64_i8 v[110:113], v[154:157], v[194:197], v[110:113]
	v_mfma_i32_16x16x64_i8 v[106:109], v[162:165], v[194:197], v[106:109]
	v_mfma_i32_16x16x64_i8 v[94:97], v[154:157], v[202:205], v[94:97]
	v_mfma_i32_16x16x64_i8 v[90:93], v[162:165], v[202:205], v[90:93]
	v_mfma_i32_16x16x64_i8 v[78:81], v[154:157], v[210:213], v[78:81]
	v_mfma_i32_16x16x64_i8 v[74:77], v[162:165], v[210:213], v[74:77]
	s_setprio 0
	s_setprio 1
	v_mfma_i32_16x16x64_i8 v[118:121], v[166:169], v[182:185], v[118:121]
	v_mfma_i32_16x16x64_i8 v[114:117], v[174:177], v[182:185], v[114:117]
	v_mfma_i32_16x16x64_i8 v[102:105], v[166:169], v[190:193], v[102:105]
	v_mfma_i32_16x16x64_i8 v[98:101], v[174:177], v[190:193], v[98:101]
	v_mfma_i32_16x16x64_i8 v[86:89], v[166:169], v[198:201], v[86:89]
	v_mfma_i32_16x16x64_i8 v[82:85], v[174:177], v[198:201], v[82:85]
	v_mfma_i32_16x16x64_i8 v[70:73], v[166:169], v[206:209], v[70:73]
	v_mfma_i32_16x16x64_i8 v[66:69], v[174:177], v[206:209], v[66:69]
	s_setprio 0
	s_setprio 1
	v_mfma_i32_16x16x64_i8 v[118:121], v[170:173], v[186:189], v[118:121]
	v_mfma_i32_16x16x64_i8 v[114:117], v[178:181], v[186:189], v[114:117]
	v_mfma_i32_16x16x64_i8 v[102:105], v[170:173], v[194:197], v[102:105]
	v_mfma_i32_16x16x64_i8 v[98:101], v[178:181], v[194:197], v[98:101]
	v_mfma_i32_16x16x64_i8 v[86:89], v[170:173], v[202:205], v[86:89]
	v_mfma_i32_16x16x64_i8 v[82:85], v[178:181], v[202:205], v[82:85]
	v_mfma_i32_16x16x64_i8 v[70:73], v[170:173], v[210:213], v[70:73]
	v_mfma_i32_16x16x64_i8 v[66:69], v[178:181], v[210:213], v[66:69]
	s_setprio 0
	s_barrier
	ds_read_b128 v[182:185], v148 offset:49152
	ds_read_b128 v[186:189], v148 offset:50176
	ds_read_b128 v[190:193], v148 offset:51200
	ds_read_b128 v[194:197], v148 offset:52224
	ds_read_b128 v[198:201], v148 offset:53248
	ds_read_b128 v[202:205], v148 offset:54272
	ds_read_b128 v[206:209], v148 offset:55296
	ds_read_b128 v[210:213], v148 offset:56320
	s_add_i32 s84, s86, s40
	s_add_u32 s100, s50, s38
	s_addc_u32 s101, s51, s39
	s_mov_b32 m0, s84
	s_nop 0
	global_load_lds_dwordx4 v143, s[100:101]
	s_add_i32 m0, s84, 0x2000
	s_nop 0
	s_add_u32 s50, s50, 0x20080
	s_addc_u32 s51, s51, 0
	s_add_i32 s84, s87, s40
	global_load_lds_dwordx4 v144, s[100:101]
	s_mov_b32 m0, s84
	s_nop 0
	global_load_lds_dwordx4 v143, s[50:51]
	s_add_i32 m0, s84, 0x2000
	s_nop 0
	global_load_lds_dwordx4 v144, s[50:51]
	s_mov_b32 m0, s75
	s_add_u32 s100, s46, s38
	s_addc_u32 s101, s47, s39
	v_mov_b32_e32 v0, v133
	global_load_lds_dwordx4 v132, s[100:101]
	s_mov_b32 m0, s78
	s_nop 0
	global_load_lds_dwordx4 v133, s[100:101]
	s_waitcnt vmcnt(8)
	s_waitcnt lgkmcnt(0)
	s_barrier
	s_setprio 1
	s_waitcnt lgkmcnt(0)
	v_mfma_i32_16x16x64_i8 v[62:65], v[150:153], v[182:185], v[62:65]
	v_mfma_i32_16x16x64_i8 v[58:61], v[158:161], v[182:185], v[58:61]
	v_mfma_i32_16x16x64_i8 v[46:49], v[150:153], v[190:193], v[46:49]
	v_mfma_i32_16x16x64_i8 v[42:45], v[158:161], v[190:193], v[42:45]
	v_mfma_i32_16x16x64_i8 v[30:33], v[150:153], v[198:201], v[30:33]
	v_mfma_i32_16x16x64_i8 v[26:29], v[158:161], v[198:201], v[26:29]
	v_mfma_i32_16x16x64_i8 v[14:17], v[150:153], v[206:209], v[14:17]
	v_mfma_i32_16x16x64_i8 v[10:13], v[158:161], v[206:209], v[10:13]
	s_setprio 0
	s_setprio 1
	v_mfma_i32_16x16x64_i8 v[62:65], v[154:157], v[186:189], v[62:65]
	v_mfma_i32_16x16x64_i8 v[58:61], v[162:165], v[186:189], v[58:61]
	v_mfma_i32_16x16x64_i8 v[46:49], v[154:157], v[194:197], v[46:49]
	v_mfma_i32_16x16x64_i8 v[42:45], v[162:165], v[194:197], v[42:45]
	v_mfma_i32_16x16x64_i8 v[30:33], v[154:157], v[202:205], v[30:33]
	v_mfma_i32_16x16x64_i8 v[26:29], v[162:165], v[202:205], v[26:29]
	v_mfma_i32_16x16x64_i8 v[14:17], v[154:157], v[210:213], v[14:17]
	v_mfma_i32_16x16x64_i8 v[10:13], v[162:165], v[210:213], v[10:13]
	s_setprio 0
	s_setprio 1
	v_mfma_i32_16x16x64_i8 v[54:57], v[166:169], v[182:185], v[54:57]
	v_mfma_i32_16x16x64_i8 v[50:53], v[174:177], v[182:185], v[50:53]
	v_mfma_i32_16x16x64_i8 v[38:41], v[166:169], v[190:193], v[38:41]
	v_mfma_i32_16x16x64_i8 v[34:37], v[174:177], v[190:193], v[34:37]
	v_mfma_i32_16x16x64_i8 v[22:25], v[166:169], v[198:201], v[22:25]
	v_mfma_i32_16x16x64_i8 v[18:21], v[174:177], v[198:201], v[18:21]
	v_mfma_i32_16x16x64_i8 v[6:9], v[166:169], v[206:209], v[6:9]
	v_mfma_i32_16x16x64_i8 v[2:5], v[174:177], v[206:209], v[2:5]
	s_setprio 0
	s_setprio 1
	v_mfma_i32_16x16x64_i8 v[54:57], v[170:173], v[186:189], v[54:57]
	v_mfma_i32_16x16x64_i8 v[50:53], v[178:181], v[186:189], v[50:53]
	v_mfma_i32_16x16x64_i8 v[38:41], v[170:173], v[194:197], v[38:41]
	v_mfma_i32_16x16x64_i8 v[34:37], v[178:181], v[194:197], v[34:37]
	v_mfma_i32_16x16x64_i8 v[22:25], v[170:173], v[202:205], v[22:25]
	v_mfma_i32_16x16x64_i8 v[18:21], v[178:181], v[202:205], v[18:21]
	v_mfma_i32_16x16x64_i8 v[6:9], v[170:173], v[210:213], v[6:9]
	v_mfma_i32_16x16x64_i8 v[2:5], v[178:181], v[210:213], v[2:5]
	s_setprio 0
	s_barrier
	s_add_i32 s65, s65, 2
	s_add_u32 s48, s48, 0x100
	s_addc_u32 s49, s49, 0
	s_add_u32 s25, s25, 0x100
	s_addc_u32 s64, s64, 0
	s_cmp_gt_u32 s65, 5
	s_cbranch_scc0 .LBB0_445
	s_branch .Lpeel_exit_445
.LBB0_445:
	s_add_u32 s46, s48, 0xfffe0080
	s_addc_u32 s47, s49, -1
	s_add_i32 s84, 0, 0x10000
	s_cmp_eq_u32 s65, 4
	s_cselect_b32 s47, s15, s47
	s_cselect_b32 s46, s14, s46
	v_add_u32_e32 v0, s84, v147
	s_cselect_b32 s51, s17, s64
	s_cselect_b32 s50, s16, s25
	s_add_i32 s86, 0, 0x14000
	ds_read_b128 v[150:153], v0
	ds_read_b128 v[154:157], v0 offset:1024
	ds_read_b128 v[158:161], v0 offset:2048
	ds_read_b128 v[162:165], v0 offset:3072
	ds_read_b128 v[166:169], v0 offset:16384
	ds_read_b128 v[170:173], v0 offset:17408
	ds_read_b128 v[174:177], v0 offset:18432
	ds_read_b128 v[178:181], v0 offset:19456
	ds_read_b128 v[182:185], v148
	ds_read_b128 v[186:189], v148 offset:1024
	ds_read_b128 v[190:193], v148 offset:2048
	ds_read_b128 v[194:197], v148 offset:3072
	ds_read_b128 v[198:201], v148 offset:4096
	ds_read_b128 v[202:205], v148 offset:5120
	ds_read_b128 v[206:209], v148 offset:6144
	ds_read_b128 v[210:213], v148 offset:7168
	s_add_i32 m0, s59, 0xc000
	s_nop 0
	global_load_lds_dwordx4 v132, s[48:49]
	s_add_i32 m0, s59, 0xe000
	s_nop 0
	global_load_lds_dwordx4 v133, s[48:49]
	s_waitcnt vmcnt(8)
	s_waitcnt lgkmcnt(0)
	s_barrier
	s_setprio 1
	s_waitcnt lgkmcnt(0)
	v_mfma_i32_16x16x64_i8 v[126:129], v[150:153], v[182:185], v[126:129]
	v_mfma_i32_16x16x64_i8 v[122:125], v[158:161], v[182:185], v[122:125]
	v_mfma_i32_16x16x64_i8 v[110:113], v[150:153], v[190:193], v[110:113]
	v_mfma_i32_16x16x64_i8 v[106:109], v[158:161], v[190:193], v[106:109]
	v_mfma_i32_16x16x64_i8 v[94:97], v[150:153], v[198:201], v[94:97]
	v_mfma_i32_16x16x64_i8 v[90:93], v[158:161], v[198:201], v[90:93]
	v_mfma_i32_16x16x64_i8 v[78:81], v[150:153], v[206:209], v[78:81]
	v_mfma_i32_16x16x64_i8 v[74:77], v[158:161], v[206:209], v[74:77]
	s_setprio 0
	s_setprio 1
	v_mfma_i32_16x16x64_i8 v[126:129], v[154:157], v[186:189], v[126:129]
	v_mfma_i32_16x16x64_i8 v[122:125], v[162:165], v[186:189], v[122:125]
	v_mfma_i32_16x16x64_i8 v[110:113], v[154:157], v[194:197], v[110:113]
	v_mfma_i32_16x16x64_i8 v[106:109], v[162:165], v[194:197], v[106:109]
	v_mfma_i32_16x16x64_i8 v[94:97], v[154:157], v[202:205], v[94:97]
	v_mfma_i32_16x16x64_i8 v[90:93], v[162:165], v[202:205], v[90:93]
	v_mfma_i32_16x16x64_i8 v[78:81], v[154:157], v[210:213], v[78:81]
	v_mfma_i32_16x16x64_i8 v[74:77], v[162:165], v[210:213], v[74:77]
	s_setprio 0
	s_setprio 1
	v_mfma_i32_16x16x64_i8 v[118:121], v[166:169], v[182:185], v[118:121]
	v_mfma_i32_16x16x64_i8 v[114:117], v[174:177], v[182:185], v[114:117]
	v_mfma_i32_16x16x64_i8 v[102:105], v[166:169], v[190:193], v[102:105]
	v_mfma_i32_16x16x64_i8 v[98:101], v[174:177], v[190:193], v[98:101]
	v_mfma_i32_16x16x64_i8 v[86:89], v[166:169], v[198:201], v[86:89]
	v_mfma_i32_16x16x64_i8 v[82:85], v[174:177], v[198:201], v[82:85]
	v_mfma_i32_16x16x64_i8 v[70:73], v[166:169], v[206:209], v[70:73]
	v_mfma_i32_16x16x64_i8 v[66:69], v[174:177], v[206:209], v[66:69]
	s_setprio 0
	s_setprio 1
	v_mfma_i32_16x16x64_i8 v[118:121], v[170:173], v[186:189], v[118:121]
	v_mfma_i32_16x16x64_i8 v[114:117], v[178:181], v[186:189], v[114:117]
	v_mfma_i32_16x16x64_i8 v[102:105], v[170:173], v[194:197], v[102:105]
	v_mfma_i32_16x16x64_i8 v[98:101], v[178:181], v[194:197], v[98:101]
	v_mfma_i32_16x16x64_i8 v[86:89], v[170:173], v[202:205], v[86:89]
	v_mfma_i32_16x16x64_i8 v[82:85], v[178:181], v[202:205], v[82:85]
	v_mfma_i32_16x16x64_i8 v[70:73], v[170:173], v[210:213], v[70:73]
	v_mfma_i32_16x16x64_i8 v[66:69], v[178:181], v[210:213], v[66:69]
	s_setprio 0
	s_barrier
	s_add_i32 s84, s84, s40
	ds_read_b128 v[182:185], v148 offset:16384
	ds_read_b128 v[186:189], v148 offset:17408
	ds_read_b128 v[190:193], v148 offset:18432
	ds_read_b128 v[194:197], v148 offset:19456
	ds_read_b128 v[198:201], v148 offset:20480
	ds_read_b128 v[202:205], v148 offset:21504
	ds_read_b128 v[206:209], v148 offset:22528
	ds_read_b128 v[210:213], v148 offset:23552
	s_mov_b32 m0, s84
	s_nop 0
	global_load_lds_dwordx4 v143, s[50:51]
	s_add_i32 m0, s84, 0x2000
	s_add_u32 s84, s50, 0x20000
	global_load_lds_dwordx4 v144, s[50:51]
	s_addc_u32 s85, s51, 0
	s_add_i32 s86, s86, s40
	s_mov_b32 m0, s86
	s_nop 0
	global_load_lds_dwordx4 v143, s[84:85]
	s_add_i32 m0, s86, 0x2000
	s_nop 0
	global_load_lds_dwordx4 v144, s[84:85]
	s_mov_b32 m0, s59
	s_nop 0
	global_load_lds_dwordx4 v132, s[46:47]
	s_mov_b32 m0, s60
	s_nop 0
	global_load_lds_dwordx4 v133, s[46:47]
	s_waitcnt vmcnt(8)
	s_waitcnt lgkmcnt(0)
	s_barrier
	s_setprio 1
	s_waitcnt lgkmcnt(0)
	v_mfma_i32_16x16x64_i8 v[62:65], v[150:153], v[182:185], v[62:65]
	v_mfma_i32_16x16x64_i8 v[58:61], v[158:161], v[182:185], v[58:61]
	v_mfma_i32_16x16x64_i8 v[46:49], v[150:153], v[190:193], v[46:49]
	v_mfma_i32_16x16x64_i8 v[42:45], v[158:161], v[190:193], v[42:45]
	v_mfma_i32_16x16x64_i8 v[30:33], v[150:153], v[198:201], v[30:33]
	v_mfma_i32_16x16x64_i8 v[26:29], v[158:161], v[198:201], v[26:29]
	v_mfma_i32_16x16x64_i8 v[14:17], v[150:153], v[206:209], v[14:17]
	v_mfma_i32_16x16x64_i8 v[10:13], v[158:161], v[206:209], v[10:13]
	s_setprio 0
	s_setprio 1
	v_mfma_i32_16x16x64_i8 v[62:65], v[154:157], v[186:189], v[62:65]
	v_mfma_i32_16x16x64_i8 v[58:61], v[162:165], v[186:189], v[58:61]
	v_mfma_i32_16x16x64_i8 v[46:49], v[154:157], v[194:197], v[46:49]
	v_mfma_i32_16x16x64_i8 v[42:45], v[162:165], v[194:197], v[42:45]
	v_mfma_i32_16x16x64_i8 v[30:33], v[154:157], v[202:205], v[30:33]
	v_mfma_i32_16x16x64_i8 v[26:29], v[162:165], v[202:205], v[26:29]
	v_mfma_i32_16x16x64_i8 v[14:17], v[154:157], v[210:213], v[14:17]
	v_mfma_i32_16x16x64_i8 v[10:13], v[162:165], v[210:213], v[10:13]
	s_setprio 0
	s_setprio 1
	v_mfma_i32_16x16x64_i8 v[54:57], v[166:169], v[182:185], v[54:57]
	v_mfma_i32_16x16x64_i8 v[50:53], v[174:177], v[182:185], v[50:53]
	v_mfma_i32_16x16x64_i8 v[38:41], v[166:169], v[190:193], v[38:41]
	v_mfma_i32_16x16x64_i8 v[34:37], v[174:177], v[190:193], v[34:37]
	v_mfma_i32_16x16x64_i8 v[22:25], v[166:169], v[198:201], v[22:25]
	v_mfma_i32_16x16x64_i8 v[18:21], v[174:177], v[198:201], v[18:21]
	v_mfma_i32_16x16x64_i8 v[6:9], v[166:169], v[206:209], v[6:9]
	v_mfma_i32_16x16x64_i8 v[2:5], v[174:177], v[206:209], v[2:5]
	s_setprio 0
	s_setprio 1
	v_mfma_i32_16x16x64_i8 v[54:57], v[170:173], v[186:189], v[54:57]
	v_mfma_i32_16x16x64_i8 v[50:53], v[178:181], v[186:189], v[50:53]
	v_mfma_i32_16x16x64_i8 v[38:41], v[170:173], v[194:197], v[38:41]
	v_mfma_i32_16x16x64_i8 v[34:37], v[178:181], v[194:197], v[34:37]
	v_mfma_i32_16x16x64_i8 v[22:25], v[170:173], v[202:205], v[22:25]
	v_mfma_i32_16x16x64_i8 v[18:21], v[178:181], v[202:205], v[18:21]
	v_mfma_i32_16x16x64_i8 v[6:9], v[170:173], v[210:213], v[6:9]
	v_mfma_i32_16x16x64_i8 v[2:5], v[178:181], v[210:213], v[2:5]
	s_setprio 0
	s_barrier
	s_add_i32 s86, 0, 0x18000
	s_add_i32 s87, 0, 0x1c000
	ds_read_b128 v[150:153], v0 offset:32768
	ds_read_b128 v[154:157], v0 offset:33792
	ds_read_b128 v[158:161], v0 offset:34816
	ds_read_b128 v[162:165], v0 offset:35840
	ds_read_b128 v[166:169], v0 offset:49152
	ds_read_b128 v[170:173], v0 offset:50176
	ds_read_b128 v[174:177], v0 offset:51200
	ds_read_b128 v[178:181], v0 offset:52224
	s_add_u32 s84, s46, 0x20000
	s_mov_b32 m0, s61
	ds_read_b128 v[182:185], v148 offset:32768
	ds_read_b128 v[186:189], v148 offset:33792
	ds_read_b128 v[190:193], v148 offset:34816
	ds_read_b128 v[194:197], v148 offset:35840
	ds_read_b128 v[198:201], v148 offset:36864
	ds_read_b128 v[202:205], v148 offset:37888
	ds_read_b128 v[206:209], v148 offset:38912
	ds_read_b128 v[210:213], v148 offset:39936
	s_addc_u32 s85, s47, 0
	s_nop 0
	global_load_lds_dwordx4 v132, s[84:85]
	s_mov_b32 m0, s66
	s_nop 0
	global_load_lds_dwordx4 v133, s[84:85]
	s_waitcnt vmcnt(8)
	s_waitcnt lgkmcnt(0)
	s_barrier
	s_setprio 1
	s_waitcnt lgkmcnt(0)
	v_mfma_i32_16x16x64_i8 v[126:129], v[150:153], v[182:185], v[126:129]
	v_mfma_i32_16x16x64_i8 v[122:125], v[158:161], v[182:185], v[122:125]
	v_mfma_i32_16x16x64_i8 v[110:113], v[150:153], v[190:193], v[110:113]
	v_mfma_i32_16x16x64_i8 v[106:109], v[158:161], v[190:193], v[106:109]
	v_mfma_i32_16x16x64_i8 v[94:97], v[150:153], v[198:201], v[94:97]
	v_mfma_i32_16x16x64_i8 v[90:93], v[158:161], v[198:201], v[90:93]
	v_mfma_i32_16x16x64_i8 v[78:81], v[150:153], v[206:209], v[78:81]
	v_mfma_i32_16x16x64_i8 v[74:77], v[158:161], v[206:209], v[74:77]
	s_setprio 0
	s_setprio 1
	v_mfma_i32_16x16x64_i8 v[126:129], v[154:157], v[186:189], v[126:129]
	v_mfma_i32_16x16x64_i8 v[122:125], v[162:165], v[186:189], v[122:125]
	v_mfma_i32_16x16x64_i8 v[110:113], v[154:157], v[194:197], v[110:113]
	v_mfma_i32_16x16x64_i8 v[106:109], v[162:165], v[194:197], v[106:109]
	v_mfma_i32_16x16x64_i8 v[94:97], v[154:157], v[202:205], v[94:97]
	v_mfma_i32_16x16x64_i8 v[90:93], v[162:165], v[202:205], v[90:93]
	v_mfma_i32_16x16x64_i8 v[78:81], v[154:157], v[210:213], v[78:81]
	v_mfma_i32_16x16x64_i8 v[74:77], v[162:165], v[210:213], v[74:77]
	s_setprio 0
	s_setprio 1
	v_mfma_i32_16x16x64_i8 v[118:121], v[166:169], v[182:185], v[118:121]
	v_mfma_i32_16x16x64_i8 v[114:117], v[174:177], v[182:185], v[114:117]
	v_mfma_i32_16x16x64_i8 v[102:105], v[166:169], v[190:193], v[102:105]
	v_mfma_i32_16x16x64_i8 v[98:101], v[174:177], v[190:193], v[98:101]
	v_mfma_i32_16x16x64_i8 v[86:89], v[166:169], v[198:201], v[86:89]
	v_mfma_i32_16x16x64_i8 v[82:85], v[174:177], v[198:201], v[82:85]
	v_mfma_i32_16x16x64_i8 v[70:73], v[166:169], v[206:209], v[70:73]
	v_mfma_i32_16x16x64_i8 v[66:69], v[174:177], v[206:209], v[66:69]
	s_setprio 0
	s_setprio 1
	v_mfma_i32_16x16x64_i8 v[118:121], v[170:173], v[186:189], v[118:121]
	v_mfma_i32_16x16x64_i8 v[114:117], v[178:181], v[186:189], v[114:117]
	v_mfma_i32_16x16x64_i8 v[102:105], v[170:173], v[194:197], v[102:105]
	v_mfma_i32_16x16x64_i8 v[98:101], v[178:181], v[194:197], v[98:101]
	v_mfma_i32_16x16x64_i8 v[86:89], v[170:173], v[202:205], v[86:89]
	v_mfma_i32_16x16x64_i8 v[82:85], v[178:181], v[202:205], v[82:85]
	v_mfma_i32_16x16x64_i8 v[70:73], v[170:173], v[210:213], v[70:73]
	v_mfma_i32_16x16x64_i8 v[66:69], v[178:181], v[210:213], v[66:69]
	s_setprio 0
	s_barrier
	ds_read_b128 v[182:185], v148 offset:49152
	ds_read_b128 v[186:189], v148 offset:50176
	ds_read_b128 v[190:193], v148 offset:51200
	ds_read_b128 v[194:197], v148 offset:52224
	ds_read_b128 v[198:201], v148 offset:53248
	ds_read_b128 v[202:205], v148 offset:54272
	ds_read_b128 v[206:209], v148 offset:55296
	ds_read_b128 v[210:213], v148 offset:56320
	s_add_i32 s84, s86, s40
	s_add_u32 s100, s50, s38
	s_addc_u32 s101, s51, s39
	s_mov_b32 m0, s84
	s_nop 0
	global_load_lds_dwordx4 v143, s[100:101]
	s_add_i32 m0, s84, 0x2000
	s_nop 0
	s_add_u32 s50, s50, 0x20080
	s_addc_u32 s51, s51, 0
	s_add_i32 s84, s87, s40
	global_load_lds_dwordx4 v144, s[100:101]
	s_mov_b32 m0, s84
	s_nop 0
	global_load_lds_dwordx4 v143, s[50:51]
	s_add_i32 m0, s84, 0x2000
	s_nop 0
	global_load_lds_dwordx4 v144, s[50:51]
	s_mov_b32 m0, s75
	s_add_u32 s100, s46, s38
	s_addc_u32 s101, s47, s39
	v_mov_b32_e32 v0, v133
	global_load_lds_dwordx4 v132, s[100:101]
	s_mov_b32 m0, s78
	s_nop 0
	global_load_lds_dwordx4 v133, s[100:101]
	s_waitcnt vmcnt(8)
	s_waitcnt lgkmcnt(0)
	s_barrier
	s_setprio 1
	s_waitcnt lgkmcnt(0)
	v_mfma_i32_16x16x64_i8 v[62:65], v[150:153], v[182:185], v[62:65]
	v_mfma_i32_16x16x64_i8 v[58:61], v[158:161], v[182:185], v[58:61]
	v_mfma_i32_16x16x64_i8 v[46:49], v[150:153], v[190:193], v[46:49]
	v_mfma_i32_16x16x64_i8 v[42:45], v[158:161], v[190:193], v[42:45]
	v_mfma_i32_16x16x64_i8 v[30:33], v[150:153], v[198:201], v[30:33]
	v_mfma_i32_16x16x64_i8 v[26:29], v[158:161], v[198:201], v[26:29]
	v_mfma_i32_16x16x64_i8 v[14:17], v[150:153], v[206:209], v[14:17]
	v_mfma_i32_16x16x64_i8 v[10:13], v[158:161], v[206:209], v[10:13]
	s_setprio 0
	s_setprio 1
	v_mfma_i32_16x16x64_i8 v[62:65], v[154:157], v[186:189], v[62:65]
	v_mfma_i32_16x16x64_i8 v[58:61], v[162:165], v[186:189], v[58:61]
	v_mfma_i32_16x16x64_i8 v[46:49], v[154:157], v[194:197], v[46:49]
	v_mfma_i32_16x16x64_i8 v[42:45], v[162:165], v[194:197], v[42:45]
	v_mfma_i32_16x16x64_i8 v[30:33], v[154:157], v[202:205], v[30:33]
	v_mfma_i32_16x16x64_i8 v[26:29], v[162:165], v[202:205], v[26:29]
	v_mfma_i32_16x16x64_i8 v[14:17], v[154:157], v[210:213], v[14:17]
	v_mfma_i32_16x16x64_i8 v[10:13], v[162:165], v[210:213], v[10:13]
	s_setprio 0
	s_setprio 1
	v_mfma_i32_16x16x64_i8 v[54:57], v[166:169], v[182:185], v[54:57]
	v_mfma_i32_16x16x64_i8 v[50:53], v[174:177], v[182:185], v[50:53]
	v_mfma_i32_16x16x64_i8 v[38:41], v[166:169], v[190:193], v[38:41]
	v_mfma_i32_16x16x64_i8 v[34:37], v[174:177], v[190:193], v[34:37]
	v_mfma_i32_16x16x64_i8 v[22:25], v[166:169], v[198:201], v[22:25]
	v_mfma_i32_16x16x64_i8 v[18:21], v[174:177], v[198:201], v[18:21]
	v_mfma_i32_16x16x64_i8 v[6:9], v[166:169], v[206:209], v[6:9]
	v_mfma_i32_16x16x64_i8 v[2:5], v[174:177], v[206:209], v[2:5]
	s_setprio 0
	s_setprio 1
	v_mfma_i32_16x16x64_i8 v[54:57], v[170:173], v[186:189], v[54:57]
	v_mfma_i32_16x16x64_i8 v[50:53], v[178:181], v[186:189], v[50:53]
	v_mfma_i32_16x16x64_i8 v[38:41], v[170:173], v[194:197], v[38:41]
	v_mfma_i32_16x16x64_i8 v[34:37], v[178:181], v[194:197], v[34:37]
	v_mfma_i32_16x16x64_i8 v[22:25], v[170:173], v[202:205], v[22:25]
	v_mfma_i32_16x16x64_i8 v[18:21], v[178:181], v[202:205], v[18:21]
	v_mfma_i32_16x16x64_i8 v[6:9], v[170:173], v[210:213], v[6:9]
	v_mfma_i32_16x16x64_i8 v[2:5], v[178:181], v[210:213], v[2:5]
	s_setprio 0
	s_barrier
	s_add_i32 s65, s65, 2
	s_add_u32 s48, s48, 0x100
	s_addc_u32 s49, s49, 0
	s_add_u32 s25, s25, 0x100
	s_addc_u32 s64, s64, 0
	s_cmp_gt_u32 s65, 5
	s_cbranch_scc0 .LBB0_445

.LBB0_626:
	s_add_u32 s58, s14, s50
	s_addc_u32 s59, s15, s51
	s_add_u32 s46, s58, 0x100
	s_addc_u32 s47, s59, 0
	s_and_b64 s[4:5], s[48:49], exec
	s_cselect_b32 s47, s15, s47
	s_cselect_b32 s46, s14, s46
	s_add_u32 s4, s16, s50
	s_addc_u32 s5, s17, s51
	s_add_u32 s50, s4, 0x100
	s_addc_u32 s51, s5, 0
	s_add_i32 s78, 0, 0x10000
	s_and_b64 s[4:5], s[48:49], exec
	s_cselect_b32 s49, s17, s51
	s_cselect_b32 s48, s16, s50
	s_add_i32 s4, 0, 0x14000
	s_add_u32 s96, s58, 0x80080
	s_addc_u32 s97, s59, 0
	s_add_i32 s82, s78, s42
	s_add_i32 m0, s43, 0xc000
	s_add_i32 s5, s43, 0xe000
	s_add_i32 s76, s82, 0x2000
	v_add_u32_e32 v0, s78, v136
	s_add_u32 s94, s48, 0x40000
	ds_read_b128 v[138:141], v0
	ds_read_b128 v[142:145], v0 offset:1024
	ds_read_b128 v[146:149], v0 offset:2048
	ds_read_b128 v[150:153], v0 offset:3072
	s_addc_u32 s95, s49, 0
	s_add_i32 s77, s4, s42
	ds_read_b128 v[154:157], v0 offset:16384
	ds_read_b128 v[158:161], v0 offset:17408
	ds_read_b128 v[162:165], v0 offset:18432
	ds_read_b128 v[166:169], v0 offset:19456
	s_add_i32 s75, s77, 0x2000
	s_add_i32 s74, 0, 0x18000
	s_add_i32 s71, 0, 0x1c000
	s_add_u32 s58, s46, 0x80000
	s_addc_u32 s59, s47, 0
	s_add_i32 s70, s74, s42
	s_add_i32 s69, s70, 0x2000
	s_add_u32 s50, s48, 0x40080
	s_addc_u32 s51, s49, 0
	s_add_i32 s79, s71, s42
	s_add_i32 s78, s79, 0x2000
	ds_read_b128 v[170:173], v137
	ds_read_b128 v[174:177], v137 offset:1024
	ds_read_b128 v[178:181], v137 offset:2048
	ds_read_b128 v[182:185], v137 offset:3072
	ds_read_b128 v[186:189], v137 offset:4096
	ds_read_b128 v[190:193], v137 offset:5120
	ds_read_b128 v[194:197], v137 offset:6144
	ds_read_b128 v[198:201], v137 offset:7168
	s_nop 0
	global_load_lds_dwordx4 v130, s[96:97]
	s_mov_b32 m0, s5
	s_nop 0
	global_load_lds_dwordx4 v132, s[96:97]
	s_waitcnt vmcnt(8)
	s_waitcnt lgkmcnt(0)
	s_barrier
	s_setprio 1
	s_waitcnt lgkmcnt(0)
	v_mfma_f32_16x16x32_bf16 v[126:129], v[138:141], v[170:173], v[126:129]
	v_mfma_f32_16x16x32_bf16 v[122:125], v[146:149], v[170:173], v[122:125]
	v_mfma_f32_16x16x32_bf16 v[118:121], v[138:141], v[178:181], v[118:121]
	v_mfma_f32_16x16x32_bf16 v[110:113], v[146:149], v[178:181], v[110:113]
	v_mfma_f32_16x16x32_bf16 v[102:105], v[138:141], v[186:189], v[102:105]
	v_mfma_f32_16x16x32_bf16 v[94:97], v[146:149], v[186:189], v[94:97]
	v_mfma_f32_16x16x32_bf16 v[86:89], v[138:141], v[194:197], v[86:89]
	v_mfma_f32_16x16x32_bf16 v[78:81], v[146:149], v[194:197], v[78:81]
	s_setprio 0
	s_setprio 1
	v_mfma_f32_16x16x32_bf16 v[126:129], v[142:145], v[174:177], v[126:129]
	v_mfma_f32_16x16x32_bf16 v[122:125], v[150:153], v[174:177], v[122:125]
	v_mfma_f32_16x16x32_bf16 v[118:121], v[142:145], v[182:185], v[118:121]
	v_mfma_f32_16x16x32_bf16 v[110:113], v[150:153], v[182:185], v[110:113]
	v_mfma_f32_16x16x32_bf16 v[102:105], v[142:145], v[190:193], v[102:105]
	v_mfma_f32_16x16x32_bf16 v[94:97], v[150:153], v[190:193], v[94:97]
	v_mfma_f32_16x16x32_bf16 v[86:89], v[142:145], v[198:201], v[86:89]
	v_mfma_f32_16x16x32_bf16 v[78:81], v[150:153], v[198:201], v[78:81]
	s_setprio 0
	s_setprio 1
	v_mfma_f32_16x16x32_bf16 v[114:117], v[154:157], v[170:173], v[114:117]
	v_mfma_f32_16x16x32_bf16 v[106:109], v[162:165], v[170:173], v[106:109]
	v_mfma_f32_16x16x32_bf16 v[98:101], v[154:157], v[178:181], v[98:101]
	v_mfma_f32_16x16x32_bf16 v[90:93], v[162:165], v[178:181], v[90:93]
	v_mfma_f32_16x16x32_bf16 v[82:85], v[154:157], v[186:189], v[82:85]
	v_mfma_f32_16x16x32_bf16 v[74:77], v[162:165], v[186:189], v[74:77]
	v_mfma_f32_16x16x32_bf16 v[70:73], v[154:157], v[194:197], v[70:73]
	v_mfma_f32_16x16x32_bf16 v[62:65], v[162:165], v[194:197], v[62:65]
	s_setprio 0
	s_setprio 1
	v_mfma_f32_16x16x32_bf16 v[114:117], v[158:161], v[174:177], v[114:117]
	v_mfma_f32_16x16x32_bf16 v[106:109], v[166:169], v[174:177], v[106:109]
	v_mfma_f32_16x16x32_bf16 v[98:101], v[158:161], v[182:185], v[98:101]
	v_mfma_f32_16x16x32_bf16 v[90:93], v[166:169], v[182:185], v[90:93]
	v_mfma_f32_16x16x32_bf16 v[82:85], v[158:161], v[190:193], v[82:85]
	v_mfma_f32_16x16x32_bf16 v[74:77], v[166:169], v[190:193], v[74:77]
	v_mfma_f32_16x16x32_bf16 v[70:73], v[158:161], v[198:201], v[70:73]
	v_mfma_f32_16x16x32_bf16 v[62:65], v[166:169], v[198:201], v[62:65]
	s_setprio 0
	s_barrier
	s_mov_b32 m0, s82
	ds_read_b128 v[170:173], v137 offset:16384
	ds_read_b128 v[174:177], v137 offset:17408
	ds_read_b128 v[178:181], v137 offset:18432
	ds_read_b128 v[182:185], v137 offset:19456
	ds_read_b128 v[186:189], v137 offset:20480
	ds_read_b128 v[190:193], v137 offset:21504
	ds_read_b128 v[194:197], v137 offset:22528
	ds_read_b128 v[198:201], v137 offset:23552
	s_nop 0
	global_load_lds_dwordx4 v131, s[48:49]
	s_mov_b32 m0, s76
	s_nop 0
	global_load_lds_dwordx4 v133, s[48:49]
	s_mov_b32 m0, s77
	s_nop 0
	global_load_lds_dwordx4 v131, s[94:95]
	s_mov_b32 m0, s75
	s_nop 0
	global_load_lds_dwordx4 v133, s[94:95]
	s_mov_b32 m0, s43
	s_nop 0
	global_load_lds_dwordx4 v130, s[46:47]
	s_mov_b32 m0, s60
	s_nop 0
	global_load_lds_dwordx4 v132, s[46:47]
	s_waitcnt vmcnt(8)
	s_waitcnt lgkmcnt(0)
	s_barrier
	s_setprio 1
	s_waitcnt lgkmcnt(0)
	v_mfma_f32_16x16x32_bf16 v[66:69], v[138:141], v[170:173], v[66:69]
	v_mfma_f32_16x16x32_bf16 v[58:61], v[146:149], v[170:173], v[58:61]
	v_mfma_f32_16x16x32_bf16 v[54:57], v[138:141], v[178:181], v[54:57]
	v_mfma_f32_16x16x32_bf16 v[46:49], v[146:149], v[178:181], v[46:49]
	v_mfma_f32_16x16x32_bf16 v[38:41], v[138:141], v[186:189], v[38:41]
	v_mfma_f32_16x16x32_bf16 v[30:33], v[146:149], v[186:189], v[30:33]
	v_mfma_f32_16x16x32_bf16 v[22:25], v[138:141], v[194:197], v[22:25]
	v_mfma_f32_16x16x32_bf16 v[14:17], v[146:149], v[194:197], v[14:17]
	s_setprio 0
	s_setprio 1
	v_mfma_f32_16x16x32_bf16 v[66:69], v[142:145], v[174:177], v[66:69]
	v_mfma_f32_16x16x32_bf16 v[58:61], v[150:153], v[174:177], v[58:61]
	v_mfma_f32_16x16x32_bf16 v[54:57], v[142:145], v[182:185], v[54:57]
	v_mfma_f32_16x16x32_bf16 v[46:49], v[150:153], v[182:185], v[46:49]
	v_mfma_f32_16x16x32_bf16 v[38:41], v[142:145], v[190:193], v[38:41]
	v_mfma_f32_16x16x32_bf16 v[30:33], v[150:153], v[190:193], v[30:33]
	v_mfma_f32_16x16x32_bf16 v[22:25], v[142:145], v[198:201], v[22:25]
	v_mfma_f32_16x16x32_bf16 v[14:17], v[150:153], v[198:201], v[14:17]
	s_setprio 0
	s_setprio 1
	v_mfma_f32_16x16x32_bf16 v[50:53], v[154:157], v[170:173], v[50:53]
	v_mfma_f32_16x16x32_bf16 v[42:45], v[162:165], v[170:173], v[42:45]
	v_mfma_f32_16x16x32_bf16 v[34:37], v[154:157], v[178:181], v[34:37]
	v_mfma_f32_16x16x32_bf16 v[26:29], v[162:165], v[178:181], v[26:29]
	v_mfma_f32_16x16x32_bf16 v[18:21], v[154:157], v[186:189], v[18:21]
	v_mfma_f32_16x16x32_bf16 v[10:13], v[162:165], v[186:189], v[10:13]
	v_mfma_f32_16x16x32_bf16 v[6:9], v[154:157], v[194:197], v[6:9]
	v_mfma_f32_16x16x32_bf16 v[2:5], v[162:165], v[194:197], v[2:5]
	s_setprio 0
	s_setprio 1
	v_mfma_f32_16x16x32_bf16 v[50:53], v[158:161], v[174:177], v[50:53]
	v_mfma_f32_16x16x32_bf16 v[42:45], v[166:169], v[174:177], v[42:45]
	v_mfma_f32_16x16x32_bf16 v[34:37], v[158:161], v[182:185], v[34:37]
	v_mfma_f32_16x16x32_bf16 v[26:29], v[166:169], v[182:185], v[26:29]
	v_mfma_f32_16x16x32_bf16 v[18:21], v[158:161], v[190:193], v[18:21]
	v_mfma_f32_16x16x32_bf16 v[10:13], v[166:169], v[190:193], v[10:13]
	v_mfma_f32_16x16x32_bf16 v[6:9], v[158:161], v[198:201], v[6:9]
	v_mfma_f32_16x16x32_bf16 v[2:5], v[166:169], v[198:201], v[2:5]
	s_setprio 0
	s_barrier
	ds_read_b128 v[138:141], v0 offset:32768
	ds_read_b128 v[142:145], v0 offset:33792
	ds_read_b128 v[146:149], v0 offset:34816
	ds_read_b128 v[150:153], v0 offset:35840
	ds_read_b128 v[154:157], v0 offset:49152
	ds_read_b128 v[158:161], v0 offset:50176
	ds_read_b128 v[162:165], v0 offset:51200
	ds_read_b128 v[166:169], v0 offset:52224
	s_mov_b32 m0, s65
	ds_read_b128 v[170:173], v137 offset:32768
	ds_read_b128 v[174:177], v137 offset:33792
	ds_read_b128 v[178:181], v137 offset:34816
	ds_read_b128 v[182:185], v137 offset:35840
	ds_read_b128 v[186:189], v137 offset:36864
	ds_read_b128 v[190:193], v137 offset:37888
	ds_read_b128 v[194:197], v137 offset:38912
	ds_read_b128 v[198:201], v137 offset:39936
	s_nop 0
	global_load_lds_dwordx4 v130, s[58:59]
	s_mov_b32 m0, s66
	s_nop 0
	global_load_lds_dwordx4 v132, s[58:59]
	s_waitcnt vmcnt(8)
	s_waitcnt lgkmcnt(0)
	s_barrier
	s_setprio 1
	s_waitcnt lgkmcnt(0)
	v_mfma_f32_16x16x32_bf16 v[126:129], v[138:141], v[170:173], v[126:129]
	v_mfma_f32_16x16x32_bf16 v[122:125], v[146:149], v[170:173], v[122:125]
	v_mfma_f32_16x16x32_bf16 v[118:121], v[138:141], v[178:181], v[118:121]
	v_mfma_f32_16x16x32_bf16 v[110:113], v[146:149], v[178:181], v[110:113]
	v_mfma_f32_16x16x32_bf16 v[102:105], v[138:141], v[186:189], v[102:105]
	v_mfma_f32_16x16x32_bf16 v[94:97], v[146:149], v[186:189], v[94:97]
	v_mfma_f32_16x16x32_bf16 v[86:89], v[138:141], v[194:197], v[86:89]
	v_mfma_f32_16x16x32_bf16 v[78:81], v[146:149], v[194:197], v[78:81]
	s_setprio 0
	s_setprio 1
	v_mfma_f32_16x16x32_bf16 v[126:129], v[142:145], v[174:177], v[126:129]
	v_mfma_f32_16x16x32_bf16 v[122:125], v[150:153], v[174:177], v[122:125]
	v_mfma_f32_16x16x32_bf16 v[118:121], v[142:145], v[182:185], v[118:121]
	v_mfma_f32_16x16x32_bf16 v[110:113], v[150:153], v[182:185], v[110:113]
	v_mfma_f32_16x16x32_bf16 v[102:105], v[142:145], v[190:193], v[102:105]
	v_mfma_f32_16x16x32_bf16 v[94:97], v[150:153], v[190:193], v[94:97]
	v_mfma_f32_16x16x32_bf16 v[86:89], v[142:145], v[198:201], v[86:89]
	v_mfma_f32_16x16x32_bf16 v[78:81], v[150:153], v[198:201], v[78:81]
	s_setprio 0
	s_setprio 1
	v_mfma_f32_16x16x32_bf16 v[114:117], v[154:157], v[170:173], v[114:117]
	v_mfma_f32_16x16x32_bf16 v[106:109], v[162:165], v[170:173], v[106:109]
	v_mfma_f32_16x16x32_bf16 v[98:101], v[154:157], v[178:181], v[98:101]
	v_mfma_f32_16x16x32_bf16 v[90:93], v[162:165], v[178:181], v[90:93]
	v_mfma_f32_16x16x32_bf16 v[82:85], v[154:157], v[186:189], v[82:85]
	v_mfma_f32_16x16x32_bf16 v[74:77], v[162:165], v[186:189], v[74:77]
	v_mfma_f32_16x16x32_bf16 v[70:73], v[154:157], v[194:197], v[70:73]
	v_mfma_f32_16x16x32_bf16 v[62:65], v[162:165], v[194:197], v[62:65]
	s_setprio 0
	s_setprio 1
	v_mfma_f32_16x16x32_bf16 v[114:117], v[158:161], v[174:177], v[114:117]
	v_mfma_f32_16x16x32_bf16 v[106:109], v[166:169], v[174:177], v[106:109]
	v_mfma_f32_16x16x32_bf16 v[98:101], v[158:161], v[182:185], v[98:101]
	v_mfma_f32_16x16x32_bf16 v[90:93], v[166:169], v[182:185], v[90:93]
	v_mfma_f32_16x16x32_bf16 v[82:85], v[158:161], v[190:193], v[82:85]
	v_mfma_f32_16x16x32_bf16 v[74:77], v[166:169], v[190:193], v[74:77]
	v_mfma_f32_16x16x32_bf16 v[70:73], v[158:161], v[198:201], v[70:73]
	v_mfma_f32_16x16x32_bf16 v[62:65], v[166:169], v[198:201], v[62:65]
	s_setprio 0
	s_barrier
	ds_read_b128 v[170:173], v137 offset:49152
	ds_read_b128 v[174:177], v137 offset:50176
	ds_read_b128 v[178:181], v137 offset:51200
	ds_read_b128 v[182:185], v137 offset:52224
	ds_read_b128 v[186:189], v137 offset:53248
	ds_read_b128 v[190:193], v137 offset:54272
	ds_read_b128 v[194:197], v137 offset:55296
	ds_read_b128 v[198:201], v137 offset:56320
	s_mov_b32 m0, s70
	s_add_u32 s100, s48, s38
	s_addc_u32 s101, s49, s39
	global_load_lds_dwordx4 v131, s[100:101]
	s_mov_b32 m0, s69
	s_nop 0
	global_load_lds_dwordx4 v133, s[100:101]
	s_mov_b32 m0, s79
	s_nop 0
	global_load_lds_dwordx4 v131, s[50:51]
	s_mov_b32 m0, s78
	s_nop 0
	global_load_lds_dwordx4 v133, s[50:51]
	s_mov_b32 m0, s67
	s_add_u32 s100, s46, s38
	s_addc_u32 s101, s47, s39
	v_mov_b32_e32 v0, v132
	global_load_lds_dwordx4 v130, s[100:101]
	s_mov_b32 m0, s68
	s_nop 0
	global_load_lds_dwordx4 v132, s[100:101]
	s_waitcnt vmcnt(8)
	s_waitcnt lgkmcnt(0)
	s_barrier
	s_setprio 1
	s_waitcnt lgkmcnt(0)
	v_mfma_f32_16x16x32_bf16 v[66:69], v[138:141], v[170:173], v[66:69]
	v_mfma_f32_16x16x32_bf16 v[58:61], v[146:149], v[170:173], v[58:61]
	v_mfma_f32_16x16x32_bf16 v[54:57], v[138:141], v[178:181], v[54:57]
	v_mfma_f32_16x16x32_bf16 v[46:49], v[146:149], v[178:181], v[46:49]
	v_mfma_f32_16x16x32_bf16 v[38:41], v[138:141], v[186:189], v[38:41]
	v_mfma_f32_16x16x32_bf16 v[30:33], v[146:149], v[186:189], v[30:33]
	v_mfma_f32_16x16x32_bf16 v[22:25], v[138:141], v[194:197], v[22:25]
	v_mfma_f32_16x16x32_bf16 v[14:17], v[146:149], v[194:197], v[14:17]
	s_setprio 0
	s_setprio 1
	v_mfma_f32_16x16x32_bf16 v[66:69], v[142:145], v[174:177], v[66:69]
	v_mfma_f32_16x16x32_bf16 v[58:61], v[150:153], v[174:177], v[58:61]
	v_mfma_f32_16x16x32_bf16 v[54:57], v[142:145], v[182:185], v[54:57]
	v_mfma_f32_16x16x32_bf16 v[46:49], v[150:153], v[182:185], v[46:49]
	v_mfma_f32_16x16x32_bf16 v[38:41], v[142:145], v[190:193], v[38:41]
	v_mfma_f32_16x16x32_bf16 v[30:33], v[150:153], v[190:193], v[30:33]
	v_mfma_f32_16x16x32_bf16 v[22:25], v[142:145], v[198:201], v[22:25]
	v_mfma_f32_16x16x32_bf16 v[14:17], v[150:153], v[198:201], v[14:17]
	s_setprio 0
	s_setprio 1
	v_mfma_f32_16x16x32_bf16 v[50:53], v[154:157], v[170:173], v[50:53]
	v_mfma_f32_16x16x32_bf16 v[42:45], v[162:165], v[170:173], v[42:45]
	v_mfma_f32_16x16x32_bf16 v[34:37], v[154:157], v[178:181], v[34:37]
	v_mfma_f32_16x16x32_bf16 v[26:29], v[162:165], v[178:181], v[26:29]
	v_mfma_f32_16x16x32_bf16 v[18:21], v[154:157], v[186:189], v[18:21]
	v_mfma_f32_16x16x32_bf16 v[10:13], v[162:165], v[186:189], v[10:13]
	v_mfma_f32_16x16x32_bf16 v[6:9], v[154:157], v[194:197], v[6:9]
	v_mfma_f32_16x16x32_bf16 v[2:5], v[162:165], v[194:197], v[2:5]
	s_setprio 0
	s_setprio 1
	v_mfma_f32_16x16x32_bf16 v[50:53], v[158:161], v[174:177], v[50:53]
	v_mfma_f32_16x16x32_bf16 v[42:45], v[166:169], v[174:177], v[42:45]
	v_mfma_f32_16x16x32_bf16 v[34:37], v[158:161], v[182:185], v[34:37]
	v_mfma_f32_16x16x32_bf16 v[26:29], v[166:169], v[182:185], v[26:29]
	v_mfma_f32_16x16x32_bf16 v[18:21], v[158:161], v[190:193], v[18:21]
	v_mfma_f32_16x16x32_bf16 v[10:13], v[166:169], v[190:193], v[10:13]
	v_mfma_f32_16x16x32_bf16 v[6:9], v[158:161], v[198:201], v[6:9]
	v_mfma_f32_16x16x32_bf16 v[2:5], v[166:169], v[198:201], v[2:5]
	s_setprio 0
	s_barrier
	s_andn2_b64 vcc, exec, s[22:23]
	s_mov_b64 s[48:49], -1
	s_mov_b64 s[22:23], 0
	s_mov_b64 s[50:51], 0x100
	s_cbranch_vccz .LBB0_626
	s_cmpk_lt_u32 s25, 0x100
	s_cbranch_scc0 .LBB0_629
	s_barrier

.LBB0_634:
	s_add_u32 s50, s2, s48
	s_addc_u32 s51, s3, s49
	s_add_u32 s22, s50, 0x100
	s_addc_u32 s23, s51, 0
	s_and_b64 s[4:5], s[46:47], exec
	s_cselect_b32 s23, s3, s23
	s_cselect_b32 s22, s2, s22
	s_add_u32 s4, s14, s48
	s_addc_u32 s5, s15, s49
	s_add_u32 s48, s4, 0x900
	s_addc_u32 s49, s5, 0
	s_add_i32 s78, 0, 0x10000
	s_and_b64 s[4:5], s[46:47], exec
	s_cselect_b32 s47, s66, s49
	s_cselect_b32 s46, s65, s48
	s_add_i32 s4, 0, 0x14000
	s_add_u32 s94, s50, 0x40080
	s_addc_u32 s95, s51, 0
	s_add_i32 s82, s78, s40
	s_add_i32 m0, s41, 0xc000
	s_add_i32 s5, s41, 0xe000
	s_add_i32 s76, s82, 0x2000
	v_add_u32_e32 v0, s78, v136
	s_add_u32 s58, s46, 0x80000
	ds_read_b128 v[138:141], v0
	ds_read_b128 v[142:145], v0 offset:1024
	ds_read_b128 v[146:149], v0 offset:2048
	ds_read_b128 v[150:153], v0 offset:3072
	s_addc_u32 s59, s47, 0
	s_add_i32 s77, s4, s40
	ds_read_b128 v[154:157], v0 offset:16384
	ds_read_b128 v[158:161], v0 offset:17408
	ds_read_b128 v[162:165], v0 offset:18432
	ds_read_b128 v[166:169], v0 offset:19456
	s_add_i32 s75, s77, 0x2000
	s_add_i32 s74, 0, 0x18000
	s_add_i32 s71, 0, 0x1c000
	s_add_u32 s50, s22, 0x40000
	s_addc_u32 s51, s23, 0
	s_add_i32 s70, s74, s40
	s_add_i32 s69, s70, 0x2000
	s_add_u32 s48, s46, 0x80080
	s_addc_u32 s49, s47, 0
	s_add_i32 s79, s71, s40
	s_add_i32 s78, s79, 0x2000
	ds_read_b128 v[170:173], v137
	ds_read_b128 v[174:177], v137 offset:1024
	ds_read_b128 v[178:181], v137 offset:2048
	ds_read_b128 v[182:185], v137 offset:3072
	ds_read_b128 v[186:189], v137 offset:4096
	ds_read_b128 v[190:193], v137 offset:5120
	ds_read_b128 v[194:197], v137 offset:6144
	ds_read_b128 v[198:201], v137 offset:7168
	s_nop 0
	global_load_lds_dwordx4 v130, s[94:95]
	s_mov_b32 m0, s5
	s_nop 0
	global_load_lds_dwordx4 v132, s[94:95]
	s_waitcnt vmcnt(8)
	s_waitcnt lgkmcnt(0)
	s_barrier
	s_setprio 1
	s_waitcnt lgkmcnt(0)
	v_mfma_f32_16x16x32_bf16 v[126:129], v[138:141], v[170:173], v[126:129]
	v_mfma_f32_16x16x32_bf16 v[122:125], v[146:149], v[170:173], v[122:125]
	v_mfma_f32_16x16x32_bf16 v[118:121], v[138:141], v[178:181], v[118:121]
	v_mfma_f32_16x16x32_bf16 v[110:113], v[146:149], v[178:181], v[110:113]
	v_mfma_f32_16x16x32_bf16 v[102:105], v[138:141], v[186:189], v[102:105]
	v_mfma_f32_16x16x32_bf16 v[94:97], v[146:149], v[186:189], v[94:97]
	v_mfma_f32_16x16x32_bf16 v[86:89], v[138:141], v[194:197], v[86:89]
	v_mfma_f32_16x16x32_bf16 v[78:81], v[146:149], v[194:197], v[78:81]
	s_setprio 0
	s_setprio 1
	v_mfma_f32_16x16x32_bf16 v[126:129], v[142:145], v[174:177], v[126:129]
	v_mfma_f32_16x16x32_bf16 v[122:125], v[150:153], v[174:177], v[122:125]
	v_mfma_f32_16x16x32_bf16 v[118:121], v[142:145], v[182:185], v[118:121]
	v_mfma_f32_16x16x32_bf16 v[110:113], v[150:153], v[182:185], v[110:113]
	v_mfma_f32_16x16x32_bf16 v[102:105], v[142:145], v[190:193], v[102:105]
	v_mfma_f32_16x16x32_bf16 v[94:97], v[150:153], v[190:193], v[94:97]
	v_mfma_f32_16x16x32_bf16 v[86:89], v[142:145], v[198:201], v[86:89]
	v_mfma_f32_16x16x32_bf16 v[78:81], v[150:153], v[198:201], v[78:81]
	s_setprio 0
	s_setprio 1
	v_mfma_f32_16x16x32_bf16 v[114:117], v[154:157], v[170:173], v[114:117]
	v_mfma_f32_16x16x32_bf16 v[106:109], v[162:165], v[170:173], v[106:109]
	v_mfma_f32_16x16x32_bf16 v[98:101], v[154:157], v[178:181], v[98:101]
	v_mfma_f32_16x16x32_bf16 v[90:93], v[162:165], v[178:181], v[90:93]
	v_mfma_f32_16x16x32_bf16 v[82:85], v[154:157], v[186:189], v[82:85]
	v_mfma_f32_16x16x32_bf16 v[74:77], v[162:165], v[186:189], v[74:77]
	v_mfma_f32_16x16x32_bf16 v[70:73], v[154:157], v[194:197], v[70:73]
	v_mfma_f32_16x16x32_bf16 v[62:65], v[162:165], v[194:197], v[62:65]
	s_setprio 0
	s_setprio 1
	v_mfma_f32_16x16x32_bf16 v[114:117], v[158:161], v[174:177], v[114:117]
	v_mfma_f32_16x16x32_bf16 v[106:109], v[166:169], v[174:177], v[106:109]
	v_mfma_f32_16x16x32_bf16 v[98:101], v[158:161], v[182:185], v[98:101]
	v_mfma_f32_16x16x32_bf16 v[90:93], v[166:169], v[182:185], v[90:93]
	v_mfma_f32_16x16x32_bf16 v[82:85], v[158:161], v[190:193], v[82:85]
	v_mfma_f32_16x16x32_bf16 v[74:77], v[166:169], v[190:193], v[74:77]
	v_mfma_f32_16x16x32_bf16 v[70:73], v[158:161], v[198:201], v[70:73]
	v_mfma_f32_16x16x32_bf16 v[62:65], v[166:169], v[198:201], v[62:65]
	s_setprio 0
	s_barrier
	s_mov_b32 m0, s82
	ds_read_b128 v[170:173], v137 offset:16384
	ds_read_b128 v[174:177], v137 offset:17408
	ds_read_b128 v[178:181], v137 offset:18432
	ds_read_b128 v[182:185], v137 offset:19456
	ds_read_b128 v[186:189], v137 offset:20480
	ds_read_b128 v[190:193], v137 offset:21504
	ds_read_b128 v[194:197], v137 offset:22528
	ds_read_b128 v[198:201], v137 offset:23552
	s_nop 0
	global_load_lds_dwordx4 v131, s[46:47]
	s_mov_b32 m0, s76
	s_nop 0
	global_load_lds_dwordx4 v133, s[46:47]
	s_mov_b32 m0, s77
	s_nop 0
	global_load_lds_dwordx4 v131, s[58:59]
	s_mov_b32 m0, s75
	s_nop 0
	global_load_lds_dwordx4 v133, s[58:59]
	s_mov_b32 m0, s41
	s_nop 0
	global_load_lds_dwordx4 v130, s[22:23]
	s_mov_b32 m0, s42
	s_nop 0
	global_load_lds_dwordx4 v132, s[22:23]
	s_waitcnt vmcnt(8)
	s_waitcnt lgkmcnt(0)
	s_barrier
	s_setprio 1
	s_waitcnt lgkmcnt(0)
	v_mfma_f32_16x16x32_bf16 v[66:69], v[138:141], v[170:173], v[66:69]
	v_mfma_f32_16x16x32_bf16 v[58:61], v[146:149], v[170:173], v[58:61]
	v_mfma_f32_16x16x32_bf16 v[54:57], v[138:141], v[178:181], v[54:57]
	v_mfma_f32_16x16x32_bf16 v[46:49], v[146:149], v[178:181], v[46:49]
	v_mfma_f32_16x16x32_bf16 v[38:41], v[138:141], v[186:189], v[38:41]
	v_mfma_f32_16x16x32_bf16 v[30:33], v[146:149], v[186:189], v[30:33]
	v_mfma_f32_16x16x32_bf16 v[22:25], v[138:141], v[194:197], v[22:25]
	v_mfma_f32_16x16x32_bf16 v[14:17], v[146:149], v[194:197], v[14:17]
	s_setprio 0
	s_setprio 1
	v_mfma_f32_16x16x32_bf16 v[66:69], v[142:145], v[174:177], v[66:69]
	v_mfma_f32_16x16x32_bf16 v[58:61], v[150:153], v[174:177], v[58:61]
	v_mfma_f32_16x16x32_bf16 v[54:57], v[142:145], v[182:185], v[54:57]
	v_mfma_f32_16x16x32_bf16 v[46:49], v[150:153], v[182:185], v[46:49]
	v_mfma_f32_16x16x32_bf16 v[38:41], v[142:145], v[190:193], v[38:41]
	v_mfma_f32_16x16x32_bf16 v[30:33], v[150:153], v[190:193], v[30:33]
	v_mfma_f32_16x16x32_bf16 v[22:25], v[142:145], v[198:201], v[22:25]
	v_mfma_f32_16x16x32_bf16 v[14:17], v[150:153], v[198:201], v[14:17]
	s_setprio 0
	s_setprio 1
	v_mfma_f32_16x16x32_bf16 v[50:53], v[154:157], v[170:173], v[50:53]
	v_mfma_f32_16x16x32_bf16 v[42:45], v[162:165], v[170:173], v[42:45]
	v_mfma_f32_16x16x32_bf16 v[34:37], v[154:157], v[178:181], v[34:37]
	v_mfma_f32_16x16x32_bf16 v[26:29], v[162:165], v[178:181], v[26:29]
	v_mfma_f32_16x16x32_bf16 v[18:21], v[154:157], v[186:189], v[18:21]
	v_mfma_f32_16x16x32_bf16 v[10:13], v[162:165], v[186:189], v[10:13]
	v_mfma_f32_16x16x32_bf16 v[6:9], v[154:157], v[194:197], v[6:9]
	v_mfma_f32_16x16x32_bf16 v[2:5], v[162:165], v[194:197], v[2:5]
	s_setprio 0
	s_setprio 1
	v_mfma_f32_16x16x32_bf16 v[50:53], v[158:161], v[174:177], v[50:53]
	v_mfma_f32_16x16x32_bf16 v[42:45], v[166:169], v[174:177], v[42:45]
	v_mfma_f32_16x16x32_bf16 v[34:37], v[158:161], v[182:185], v[34:37]
	v_mfma_f32_16x16x32_bf16 v[26:29], v[166:169], v[182:185], v[26:29]
	v_mfma_f32_16x16x32_bf16 v[18:21], v[158:161], v[190:193], v[18:21]
	v_mfma_f32_16x16x32_bf16 v[10:13], v[166:169], v[190:193], v[10:13]
	v_mfma_f32_16x16x32_bf16 v[6:9], v[158:161], v[198:201], v[6:9]
	v_mfma_f32_16x16x32_bf16 v[2:5], v[166:169], v[198:201], v[2:5]
	s_setprio 0
	s_barrier
	ds_read_b128 v[138:141], v0 offset:32768
	ds_read_b128 v[142:145], v0 offset:33792
	ds_read_b128 v[146:149], v0 offset:34816
	ds_read_b128 v[150:153], v0 offset:35840
	ds_read_b128 v[154:157], v0 offset:49152
	ds_read_b128 v[158:161], v0 offset:50176
	ds_read_b128 v[162:165], v0 offset:51200
	ds_read_b128 v[166:169], v0 offset:52224
	s_mov_b32 m0, s43
	ds_read_b128 v[170:173], v137 offset:32768
	ds_read_b128 v[174:177], v137 offset:33792
	ds_read_b128 v[178:181], v137 offset:34816
	ds_read_b128 v[182:185], v137 offset:35840
	ds_read_b128 v[186:189], v137 offset:36864
	ds_read_b128 v[190:193], v137 offset:37888
	ds_read_b128 v[194:197], v137 offset:38912
	ds_read_b128 v[198:201], v137 offset:39936
	s_nop 0
	global_load_lds_dwordx4 v130, s[50:51]
	s_mov_b32 m0, s64
	s_nop 0
	global_load_lds_dwordx4 v132, s[50:51]
	s_waitcnt vmcnt(8)
	s_waitcnt lgkmcnt(0)
	s_barrier
	s_setprio 1
	s_waitcnt lgkmcnt(0)
	v_mfma_f32_16x16x32_bf16 v[126:129], v[138:141], v[170:173], v[126:129]
	v_mfma_f32_16x16x32_bf16 v[122:125], v[146:149], v[170:173], v[122:125]
	v_mfma_f32_16x16x32_bf16 v[118:121], v[138:141], v[178:181], v[118:121]
	v_mfma_f32_16x16x32_bf16 v[110:113], v[146:149], v[178:181], v[110:113]
	v_mfma_f32_16x16x32_bf16 v[102:105], v[138:141], v[186:189], v[102:105]
	v_mfma_f32_16x16x32_bf16 v[94:97], v[146:149], v[186:189], v[94:97]
	v_mfma_f32_16x16x32_bf16 v[86:89], v[138:141], v[194:197], v[86:89]
	v_mfma_f32_16x16x32_bf16 v[78:81], v[146:149], v[194:197], v[78:81]
	s_setprio 0
	s_setprio 1
	v_mfma_f32_16x16x32_bf16 v[126:129], v[142:145], v[174:177], v[126:129]
	v_mfma_f32_16x16x32_bf16 v[122:125], v[150:153], v[174:177], v[122:125]
	v_mfma_f32_16x16x32_bf16 v[118:121], v[142:145], v[182:185], v[118:121]
	v_mfma_f32_16x16x32_bf16 v[110:113], v[150:153], v[182:185], v[110:113]
	v_mfma_f32_16x16x32_bf16 v[102:105], v[142:145], v[190:193], v[102:105]
	v_mfma_f32_16x16x32_bf16 v[94:97], v[150:153], v[190:193], v[94:97]
	v_mfma_f32_16x16x32_bf16 v[86:89], v[142:145], v[198:201], v[86:89]
	v_mfma_f32_16x16x32_bf16 v[78:81], v[150:153], v[198:201], v[78:81]
	s_setprio 0
	s_setprio 1
	v_mfma_f32_16x16x32_bf16 v[114:117], v[154:157], v[170:173], v[114:117]
	v_mfma_f32_16x16x32_bf16 v[106:109], v[162:165], v[170:173], v[106:109]
	v_mfma_f32_16x16x32_bf16 v[98:101], v[154:157], v[178:181], v[98:101]
	v_mfma_f32_16x16x32_bf16 v[90:93], v[162:165], v[178:181], v[90:93]
	v_mfma_f32_16x16x32_bf16 v[82:85], v[154:157], v[186:189], v[82:85]
	v_mfma_f32_16x16x32_bf16 v[74:77], v[162:165], v[186:189], v[74:77]
	v_mfma_f32_16x16x32_bf16 v[70:73], v[154:157], v[194:197], v[70:73]
	v_mfma_f32_16x16x32_bf16 v[62:65], v[162:165], v[194:197], v[62:65]
	s_setprio 0
	s_setprio 1
	v_mfma_f32_16x16x32_bf16 v[114:117], v[158:161], v[174:177], v[114:117]
	v_mfma_f32_16x16x32_bf16 v[106:109], v[166:169], v[174:177], v[106:109]
	v_mfma_f32_16x16x32_bf16 v[98:101], v[158:161], v[182:185], v[98:101]
	v_mfma_f32_16x16x32_bf16 v[90:93], v[166:169], v[182:185], v[90:93]
	v_mfma_f32_16x16x32_bf16 v[82:85], v[158:161], v[190:193], v[82:85]
	v_mfma_f32_16x16x32_bf16 v[74:77], v[166:169], v[190:193], v[74:77]
	v_mfma_f32_16x16x32_bf16 v[70:73], v[158:161], v[198:201], v[70:73]
	v_mfma_f32_16x16x32_bf16 v[62:65], v[166:169], v[198:201], v[62:65]
	s_setprio 0
	s_barrier
	ds_read_b128 v[170:173], v137 offset:49152
	ds_read_b128 v[174:177], v137 offset:50176
	ds_read_b128 v[178:181], v137 offset:51200
	ds_read_b128 v[182:185], v137 offset:52224
	ds_read_b128 v[186:189], v137 offset:53248
	ds_read_b128 v[190:193], v137 offset:54272
	ds_read_b128 v[194:197], v137 offset:55296
	ds_read_b128 v[198:201], v137 offset:56320
	s_mov_b32 m0, s70
	s_add_u32 s100, s46, s38
	s_addc_u32 s101, s47, s39
	global_load_lds_dwordx4 v131, s[100:101]
	s_mov_b32 m0, s69
	s_nop 0
	global_load_lds_dwordx4 v133, s[100:101]
	s_mov_b32 m0, s79
	s_nop 0
	global_load_lds_dwordx4 v131, s[48:49]
	s_mov_b32 m0, s78
	s_nop 0
	global_load_lds_dwordx4 v133, s[48:49]
	s_mov_b32 m0, s67
	s_add_u32 s100, s22, s38
	s_addc_u32 s101, s23, s39
	v_mov_b32_e32 v0, v132
	global_load_lds_dwordx4 v130, s[100:101]
	s_mov_b32 m0, s68
	s_nop 0
	global_load_lds_dwordx4 v132, s[100:101]
	s_waitcnt vmcnt(8)
	s_waitcnt lgkmcnt(0)
	s_barrier
	s_setprio 1
	s_waitcnt lgkmcnt(0)
	v_mfma_f32_16x16x32_bf16 v[66:69], v[138:141], v[170:173], v[66:69]
	v_mfma_f32_16x16x32_bf16 v[58:61], v[146:149], v[170:173], v[58:61]
	v_mfma_f32_16x16x32_bf16 v[54:57], v[138:141], v[178:181], v[54:57]
	v_mfma_f32_16x16x32_bf16 v[46:49], v[146:149], v[178:181], v[46:49]
	v_mfma_f32_16x16x32_bf16 v[38:41], v[138:141], v[186:189], v[38:41]
	v_mfma_f32_16x16x32_bf16 v[30:33], v[146:149], v[186:189], v[30:33]
	v_mfma_f32_16x16x32_bf16 v[22:25], v[138:141], v[194:197], v[22:25]
	v_mfma_f32_16x16x32_bf16 v[14:17], v[146:149], v[194:197], v[14:17]
	s_setprio 0
	s_setprio 1
	v_mfma_f32_16x16x32_bf16 v[66:69], v[142:145], v[174:177], v[66:69]
	v_mfma_f32_16x16x32_bf16 v[58:61], v[150:153], v[174:177], v[58:61]
	v_mfma_f32_16x16x32_bf16 v[54:57], v[142:145], v[182:185], v[54:57]
	v_mfma_f32_16x16x32_bf16 v[46:49], v[150:153], v[182:185], v[46:49]
	v_mfma_f32_16x16x32_bf16 v[38:41], v[142:145], v[190:193], v[38:41]
	v_mfma_f32_16x16x32_bf16 v[30:33], v[150:153], v[190:193], v[30:33]
	v_mfma_f32_16x16x32_bf16 v[22:25], v[142:145], v[198:201], v[22:25]
	v_mfma_f32_16x16x32_bf16 v[14:17], v[150:153], v[198:201], v[14:17]
	s_setprio 0
	s_setprio 1
	v_mfma_f32_16x16x32_bf16 v[50:53], v[154:157], v[170:173], v[50:53]
	v_mfma_f32_16x16x32_bf16 v[42:45], v[162:165], v[170:173], v[42:45]
	v_mfma_f32_16x16x32_bf16 v[34:37], v[154:157], v[178:181], v[34:37]
	v_mfma_f32_16x16x32_bf16 v[26:29], v[162:165], v[178:181], v[26:29]
	v_mfma_f32_16x16x32_bf16 v[18:21], v[154:157], v[186:189], v[18:21]
	v_mfma_f32_16x16x32_bf16 v[10:13], v[162:165], v[186:189], v[10:13]
	v_mfma_f32_16x16x32_bf16 v[6:9], v[154:157], v[194:197], v[6:9]
	v_mfma_f32_16x16x32_bf16 v[2:5], v[162:165], v[194:197], v[2:5]
	s_setprio 0
	s_setprio 1
	v_mfma_f32_16x16x32_bf16 v[50:53], v[158:161], v[174:177], v[50:53]
	v_mfma_f32_16x16x32_bf16 v[42:45], v[166:169], v[174:177], v[42:45]
	v_mfma_f32_16x16x32_bf16 v[34:37], v[158:161], v[182:185], v[34:37]
	v_mfma_f32_16x16x32_bf16 v[26:29], v[166:169], v[182:185], v[26:29]
	v_mfma_f32_16x16x32_bf16 v[18:21], v[158:161], v[190:193], v[18:21]
	v_mfma_f32_16x16x32_bf16 v[10:13], v[166:169], v[190:193], v[10:13]
	v_mfma_f32_16x16x32_bf16 v[6:9], v[158:161], v[198:201], v[6:9]
	v_mfma_f32_16x16x32_bf16 v[2:5], v[166:169], v[198:201], v[2:5]
	s_setprio 0
	s_barrier
	s_andn2_b64 vcc, exec, s[16:17]
	s_mov_b64 s[46:47], -1
	s_mov_b64 s[16:17], 0
	s_mov_b64 s[48:49], 0x100
	s_cbranch_vccz .LBB0_634
	s_cmpk_lt_u32 s25, 0x100
	s_cbranch_scc0 .LBB0_637
	s_barrier

.LBB0_667:
	s_add_u32 s4, s70, s50
	s_addc_u32 s5, s71, s51
	s_add_u32 s46, s4, 0x9400100
	s_addc_u32 s47, s5, 0
	s_add_u32 s58, s74, s50
	s_addc_u32 s59, s75, s51
	s_add_i32 s77, 0, 0x10000
	s_cmpk_eq_i32 s50, 0x300
	s_cselect_b32 s47, s23, s47
	s_cselect_b32 s46, s22, s46
	v_add_u32_e32 v0, s77, v144
	s_cselect_b32 s59, s49, s59
	s_cselect_b32 s58, s48, s58
	s_add_i32 s78, 0, 0x14000
	ds_read_b128 v[146:149], v0
	ds_read_b128 v[150:153], v0 offset:1024
	ds_read_b128 v[154:157], v0 offset:2048
	ds_read_b128 v[158:161], v0 offset:3072
	ds_read_b128 v[162:165], v0 offset:16384
	ds_read_b128 v[166:169], v0 offset:17408
	ds_read_b128 v[170:173], v0 offset:18432
	ds_read_b128 v[174:177], v0 offset:19456
	ds_read_b128 v[178:181], v145
	ds_read_b128 v[182:185], v145 offset:1024
	ds_read_b128 v[186:189], v145 offset:2048
	ds_read_b128 v[190:193], v145 offset:3072
	ds_read_b128 v[194:197], v145 offset:4096
	ds_read_b128 v[198:201], v145 offset:5120
	ds_read_b128 v[202:205], v145 offset:6144
	ds_read_b128 v[206:209], v145 offset:7168
	s_add_i32 m0, s61, 0xc000
	s_add_u32 s100, s4, s54
	s_addc_u32 s101, s5, s55
	global_load_lds_dwordx4 v130, s[100:101]
	s_add_i32 m0, s61, 0xe000
	s_nop 0
	global_load_lds_dwordx4 v141, s[100:101]
	s_waitcnt vmcnt(8)
	s_waitcnt lgkmcnt(0)
	s_barrier
	s_setprio 1
	s_waitcnt lgkmcnt(0)
	v_mfma_i32_16x16x64_i8 v[126:129], v[146:149], v[178:181], v[126:129]
	v_mfma_i32_16x16x64_i8 v[122:125], v[154:157], v[178:181], v[122:125]
	v_mfma_i32_16x16x64_i8 v[110:113], v[146:149], v[186:189], v[110:113]
	v_mfma_i32_16x16x64_i8 v[106:109], v[154:157], v[186:189], v[106:109]
	v_mfma_i32_16x16x64_i8 v[94:97], v[146:149], v[194:197], v[94:97]
	v_mfma_i32_16x16x64_i8 v[90:93], v[154:157], v[194:197], v[90:93]
	v_mfma_i32_16x16x64_i8 v[78:81], v[146:149], v[202:205], v[78:81]
	v_mfma_i32_16x16x64_i8 v[74:77], v[154:157], v[202:205], v[74:77]
	s_setprio 0
	s_setprio 1
	v_mfma_i32_16x16x64_i8 v[126:129], v[150:153], v[182:185], v[126:129]
	v_mfma_i32_16x16x64_i8 v[122:125], v[158:161], v[182:185], v[122:125]
	v_mfma_i32_16x16x64_i8 v[110:113], v[150:153], v[190:193], v[110:113]
	v_mfma_i32_16x16x64_i8 v[106:109], v[158:161], v[190:193], v[106:109]
	v_mfma_i32_16x16x64_i8 v[94:97], v[150:153], v[198:201], v[94:97]
	v_mfma_i32_16x16x64_i8 v[90:93], v[158:161], v[198:201], v[90:93]
	v_mfma_i32_16x16x64_i8 v[78:81], v[150:153], v[206:209], v[78:81]
	v_mfma_i32_16x16x64_i8 v[74:77], v[158:161], v[206:209], v[74:77]
	s_setprio 0
	s_setprio 1
	v_mfma_i32_16x16x64_i8 v[118:121], v[162:165], v[178:181], v[118:121]
	v_mfma_i32_16x16x64_i8 v[114:117], v[170:173], v[178:181], v[114:117]
	v_mfma_i32_16x16x64_i8 v[102:105], v[162:165], v[186:189], v[102:105]
	v_mfma_i32_16x16x64_i8 v[98:101], v[170:173], v[186:189], v[98:101]
	v_mfma_i32_16x16x64_i8 v[86:89], v[162:165], v[194:197], v[86:89]
	v_mfma_i32_16x16x64_i8 v[82:85], v[170:173], v[194:197], v[82:85]
	v_mfma_i32_16x16x64_i8 v[70:73], v[162:165], v[202:205], v[70:73]
	v_mfma_i32_16x16x64_i8 v[66:69], v[170:173], v[202:205], v[66:69]
	s_setprio 0
	s_setprio 1
	v_mfma_i32_16x16x64_i8 v[118:121], v[166:169], v[182:185], v[118:121]
	v_mfma_i32_16x16x64_i8 v[114:117], v[174:177], v[182:185], v[114:117]
	v_mfma_i32_16x16x64_i8 v[102:105], v[166:169], v[190:193], v[102:105]
	v_mfma_i32_16x16x64_i8 v[98:101], v[174:177], v[190:193], v[98:101]
	v_mfma_i32_16x16x64_i8 v[86:89], v[166:169], v[198:201], v[86:89]
	v_mfma_i32_16x16x64_i8 v[82:85], v[174:177], v[198:201], v[82:85]
	v_mfma_i32_16x16x64_i8 v[70:73], v[166:169], v[206:209], v[70:73]
	v_mfma_i32_16x16x64_i8 v[66:69], v[174:177], v[206:209], v[66:69]
	s_setprio 0
	s_barrier
	s_add_i32 s4, s77, s60
	ds_read_b128 v[178:181], v145 offset:16384
	ds_read_b128 v[182:185], v145 offset:17408
	ds_read_b128 v[186:189], v145 offset:18432
	ds_read_b128 v[190:193], v145 offset:19456
	ds_read_b128 v[194:197], v145 offset:20480
	ds_read_b128 v[198:201], v145 offset:21504
	ds_read_b128 v[202:205], v145 offset:22528
	ds_read_b128 v[206:209], v145 offset:23552
	s_mov_b32 m0, s4
	s_nop 0
	global_load_lds_dwordx4 v131, s[58:59]
	s_add_i32 m0, s4, 0x2000
	s_add_u32 s4, s58, 0x20000
	global_load_lds_dwordx4 v142, s[58:59]
	s_addc_u32 s5, s59, 0
	s_add_i32 s77, s78, s60
	s_mov_b32 m0, s77
	s_nop 0
	global_load_lds_dwordx4 v131, s[4:5]
	s_add_i32 m0, s77, 0x2000
	s_nop 0
	global_load_lds_dwordx4 v142, s[4:5]
	s_mov_b32 m0, s61
	s_nop 0
	global_load_lds_dwordx4 v130, s[46:47]
	s_mov_b32 m0, s65
	s_nop 0
	global_load_lds_dwordx4 v141, s[46:47]
	s_waitcnt vmcnt(8)
	s_waitcnt lgkmcnt(0)
	s_barrier
	s_setprio 1
	s_waitcnt lgkmcnt(0)
	v_mfma_i32_16x16x64_i8 v[62:65], v[146:149], v[178:181], v[62:65]
	v_mfma_i32_16x16x64_i8 v[58:61], v[154:157], v[178:181], v[58:61]
	v_mfma_i32_16x16x64_i8 v[46:49], v[146:149], v[186:189], v[46:49]
	v_mfma_i32_16x16x64_i8 v[42:45], v[154:157], v[186:189], v[42:45]
	v_mfma_i32_16x16x64_i8 v[30:33], v[146:149], v[194:197], v[30:33]
	v_mfma_i32_16x16x64_i8 v[26:29], v[154:157], v[194:197], v[26:29]
	v_mfma_i32_16x16x64_i8 v[14:17], v[146:149], v[202:205], v[14:17]
	v_mfma_i32_16x16x64_i8 v[10:13], v[154:157], v[202:205], v[10:13]
	s_setprio 0
	s_setprio 1
	v_mfma_i32_16x16x64_i8 v[62:65], v[150:153], v[182:185], v[62:65]
	v_mfma_i32_16x16x64_i8 v[58:61], v[158:161], v[182:185], v[58:61]
	v_mfma_i32_16x16x64_i8 v[46:49], v[150:153], v[190:193], v[46:49]
	v_mfma_i32_16x16x64_i8 v[42:45], v[158:161], v[190:193], v[42:45]
	v_mfma_i32_16x16x64_i8 v[30:33], v[150:153], v[198:201], v[30:33]
	v_mfma_i32_16x16x64_i8 v[26:29], v[158:161], v[198:201], v[26:29]
	v_mfma_i32_16x16x64_i8 v[14:17], v[150:153], v[206:209], v[14:17]
	v_mfma_i32_16x16x64_i8 v[10:13], v[158:161], v[206:209], v[10:13]
	s_setprio 0
	s_setprio 1
	v_mfma_i32_16x16x64_i8 v[54:57], v[162:165], v[178:181], v[54:57]
	v_mfma_i32_16x16x64_i8 v[50:53], v[170:173], v[178:181], v[50:53]
	v_mfma_i32_16x16x64_i8 v[38:41], v[162:165], v[186:189], v[38:41]
	v_mfma_i32_16x16x64_i8 v[34:37], v[170:173], v[186:189], v[34:37]
	v_mfma_i32_16x16x64_i8 v[22:25], v[162:165], v[194:197], v[22:25]
	v_mfma_i32_16x16x64_i8 v[18:21], v[170:173], v[194:197], v[18:21]
	v_mfma_i32_16x16x64_i8 v[6:9], v[162:165], v[202:205], v[6:9]
	v_mfma_i32_16x16x64_i8 v[2:5], v[170:173], v[202:205], v[2:5]
	s_setprio 0
	s_setprio 1
	v_mfma_i32_16x16x64_i8 v[54:57], v[166:169], v[182:185], v[54:57]
	v_mfma_i32_16x16x64_i8 v[50:53], v[174:177], v[182:185], v[50:53]
	v_mfma_i32_16x16x64_i8 v[38:41], v[166:169], v[190:193], v[38:41]
	v_mfma_i32_16x16x64_i8 v[34:37], v[174:177], v[190:193], v[34:37]
	v_mfma_i32_16x16x64_i8 v[22:25], v[166:169], v[198:201], v[22:25]
	v_mfma_i32_16x16x64_i8 v[18:21], v[174:177], v[198:201], v[18:21]
	v_mfma_i32_16x16x64_i8 v[6:9], v[166:169], v[206:209], v[6:9]
	v_mfma_i32_16x16x64_i8 v[2:5], v[174:177], v[206:209], v[2:5]
	s_setprio 0
	s_barrier
	s_add_i32 s77, 0, 0x18000
	s_add_i32 s78, 0, 0x1c000
	ds_read_b128 v[146:149], v0 offset:32768
	ds_read_b128 v[150:153], v0 offset:33792
	ds_read_b128 v[154:157], v0 offset:34816
	ds_read_b128 v[158:161], v0 offset:35840
	ds_read_b128 v[162:165], v0 offset:49152
	ds_read_b128 v[166:169], v0 offset:50176
	ds_read_b128 v[170:173], v0 offset:51200
	ds_read_b128 v[174:177], v0 offset:52224
	s_add_u32 s4, s46, 0x20000
	s_mov_b32 m0, s66
	ds_read_b128 v[178:181], v145 offset:32768
	ds_read_b128 v[182:185], v145 offset:33792
	ds_read_b128 v[186:189], v145 offset:34816
	ds_read_b128 v[190:193], v145 offset:35840
	ds_read_b128 v[194:197], v145 offset:36864
	ds_read_b128 v[198:201], v145 offset:37888
	ds_read_b128 v[202:205], v145 offset:38912
	ds_read_b128 v[206:209], v145 offset:39936
	s_addc_u32 s5, s47, 0
	s_nop 0
	global_load_lds_dwordx4 v130, s[4:5]
	s_mov_b32 m0, s67
	s_nop 0
	global_load_lds_dwordx4 v141, s[4:5]
	s_waitcnt vmcnt(8)
	s_waitcnt lgkmcnt(0)
	s_barrier
	s_setprio 1
	s_waitcnt lgkmcnt(0)
	v_mfma_i32_16x16x64_i8 v[126:129], v[146:149], v[178:181], v[126:129]
	v_mfma_i32_16x16x64_i8 v[122:125], v[154:157], v[178:181], v[122:125]
	v_mfma_i32_16x16x64_i8 v[110:113], v[146:149], v[186:189], v[110:113]
	v_mfma_i32_16x16x64_i8 v[106:109], v[154:157], v[186:189], v[106:109]
	v_mfma_i32_16x16x64_i8 v[94:97], v[146:149], v[194:197], v[94:97]
	v_mfma_i32_16x16x64_i8 v[90:93], v[154:157], v[194:197], v[90:93]
	v_mfma_i32_16x16x64_i8 v[78:81], v[146:149], v[202:205], v[78:81]
	v_mfma_i32_16x16x64_i8 v[74:77], v[154:157], v[202:205], v[74:77]
	s_setprio 0
	s_setprio 1
	v_mfma_i32_16x16x64_i8 v[126:129], v[150:153], v[182:185], v[126:129]
	v_mfma_i32_16x16x64_i8 v[122:125], v[158:161], v[182:185], v[122:125]
	v_mfma_i32_16x16x64_i8 v[110:113], v[150:153], v[190:193], v[110:113]
	v_mfma_i32_16x16x64_i8 v[106:109], v[158:161], v[190:193], v[106:109]
	v_mfma_i32_16x16x64_i8 v[94:97], v[150:153], v[198:201], v[94:97]
	v_mfma_i32_16x16x64_i8 v[90:93], v[158:161], v[198:201], v[90:93]
	v_mfma_i32_16x16x64_i8 v[78:81], v[150:153], v[206:209], v[78:81]
	v_mfma_i32_16x16x64_i8 v[74:77], v[158:161], v[206:209], v[74:77]
	s_setprio 0
	s_setprio 1
	v_mfma_i32_16x16x64_i8 v[118:121], v[162:165], v[178:181], v[118:121]
	v_mfma_i32_16x16x64_i8 v[114:117], v[170:173], v[178:181], v[114:117]
	v_mfma_i32_16x16x64_i8 v[102:105], v[162:165], v[186:189], v[102:105]
	v_mfma_i32_16x16x64_i8 v[98:101], v[170:173], v[186:189], v[98:101]
	v_mfma_i32_16x16x64_i8 v[86:89], v[162:165], v[194:197], v[86:89]
	v_mfma_i32_16x16x64_i8 v[82:85], v[170:173], v[194:197], v[82:85]
	v_mfma_i32_16x16x64_i8 v[70:73], v[162:165], v[202:205], v[70:73]
	v_mfma_i32_16x16x64_i8 v[66:69], v[170:173], v[202:205], v[66:69]
	s_setprio 0
	s_setprio 1
	v_mfma_i32_16x16x64_i8 v[118:121], v[166:169], v[182:185], v[118:121]
	v_mfma_i32_16x16x64_i8 v[114:117], v[174:177], v[182:185], v[114:117]
	v_mfma_i32_16x16x64_i8 v[102:105], v[166:169], v[190:193], v[102:105]
	v_mfma_i32_16x16x64_i8 v[98:101], v[174:177], v[190:193], v[98:101]
	v_mfma_i32_16x16x64_i8 v[86:89], v[166:169], v[198:201], v[86:89]
	v_mfma_i32_16x16x64_i8 v[82:85], v[174:177], v[198:201], v[82:85]
	v_mfma_i32_16x16x64_i8 v[70:73], v[166:169], v[206:209], v[70:73]
	v_mfma_i32_16x16x64_i8 v[66:69], v[174:177], v[206:209], v[66:69]
	s_setprio 0
	s_barrier
	ds_read_b128 v[178:181], v145 offset:49152
	ds_read_b128 v[182:185], v145 offset:50176
	ds_read_b128 v[186:189], v145 offset:51200
	ds_read_b128 v[190:193], v145 offset:52224
	ds_read_b128 v[194:197], v145 offset:53248
	ds_read_b128 v[198:201], v145 offset:54272
	ds_read_b128 v[202:205], v145 offset:55296
	ds_read_b128 v[206:209], v145 offset:56320
	s_add_i32 s4, s77, s60
	s_add_u32 s100, s58, s38
	s_addc_u32 s101, s59, s39
	s_mov_b32 m0, s4
	s_nop 0
	global_load_lds_dwordx4 v131, s[100:101]
	s_add_i32 m0, s4, 0x2000
	s_add_u32 s4, s58, 0x20080
	s_addc_u32 s5, s59, 0
	s_add_i32 s58, s78, s60
	global_load_lds_dwordx4 v142, s[100:101]
	s_mov_b32 m0, s58
	s_nop 0
	global_load_lds_dwordx4 v131, s[4:5]
	s_add_i32 m0, s58, 0x2000
	s_nop 0
	global_load_lds_dwordx4 v142, s[4:5]
	s_mov_b32 m0, s68
	s_add_u32 s100, s46, s38
	s_addc_u32 s101, s47, s39
	v_mov_b32_e32 v0, v141
	global_load_lds_dwordx4 v130, s[100:101]
	s_mov_b32 m0, s69
	s_nop 0
	global_load_lds_dwordx4 v141, s[100:101]
	s_waitcnt vmcnt(8)
	s_waitcnt lgkmcnt(0)
	s_barrier
	s_setprio 1
	s_waitcnt lgkmcnt(0)
	v_mfma_i32_16x16x64_i8 v[62:65], v[146:149], v[178:181], v[62:65]
	v_mfma_i32_16x16x64_i8 v[58:61], v[154:157], v[178:181], v[58:61]
	v_mfma_i32_16x16x64_i8 v[46:49], v[146:149], v[186:189], v[46:49]
	v_mfma_i32_16x16x64_i8 v[42:45], v[154:157], v[186:189], v[42:45]
	v_mfma_i32_16x16x64_i8 v[30:33], v[146:149], v[194:197], v[30:33]
	v_mfma_i32_16x16x64_i8 v[26:29], v[154:157], v[194:197], v[26:29]
	v_mfma_i32_16x16x64_i8 v[14:17], v[146:149], v[202:205], v[14:17]
	v_mfma_i32_16x16x64_i8 v[10:13], v[154:157], v[202:205], v[10:13]
	s_setprio 0
	s_setprio 1
	v_mfma_i32_16x16x64_i8 v[62:65], v[150:153], v[182:185], v[62:65]
	v_mfma_i32_16x16x64_i8 v[58:61], v[158:161], v[182:185], v[58:61]
	v_mfma_i32_16x16x64_i8 v[46:49], v[150:153], v[190:193], v[46:49]
	v_mfma_i32_16x16x64_i8 v[42:45], v[158:161], v[190:193], v[42:45]
	v_mfma_i32_16x16x64_i8 v[30:33], v[150:153], v[198:201], v[30:33]
	v_mfma_i32_16x16x64_i8 v[26:29], v[158:161], v[198:201], v[26:29]
	v_mfma_i32_16x16x64_i8 v[14:17], v[150:153], v[206:209], v[14:17]
	v_mfma_i32_16x16x64_i8 v[10:13], v[158:161], v[206:209], v[10:13]
	s_setprio 0
	s_setprio 1
	v_mfma_i32_16x16x64_i8 v[54:57], v[162:165], v[178:181], v[54:57]
	v_mfma_i32_16x16x64_i8 v[50:53], v[170:173], v[178:181], v[50:53]
	v_mfma_i32_16x16x64_i8 v[38:41], v[162:165], v[186:189], v[38:41]
	v_mfma_i32_16x16x64_i8 v[34:37], v[170:173], v[186:189], v[34:37]
	v_mfma_i32_16x16x64_i8 v[22:25], v[162:165], v[194:197], v[22:25]
	v_mfma_i32_16x16x64_i8 v[18:21], v[170:173], v[194:197], v[18:21]
	v_mfma_i32_16x16x64_i8 v[6:9], v[162:165], v[202:205], v[6:9]
	v_mfma_i32_16x16x64_i8 v[2:5], v[170:173], v[202:205], v[2:5]
	s_setprio 0
	s_setprio 1
	v_mfma_i32_16x16x64_i8 v[54:57], v[166:169], v[182:185], v[54:57]
	v_mfma_i32_16x16x64_i8 v[50:53], v[174:177], v[182:185], v[50:53]
	v_mfma_i32_16x16x64_i8 v[38:41], v[166:169], v[190:193], v[38:41]
	v_mfma_i32_16x16x64_i8 v[34:37], v[174:177], v[190:193], v[34:37]
	v_mfma_i32_16x16x64_i8 v[22:25], v[166:169], v[198:201], v[22:25]
	v_mfma_i32_16x16x64_i8 v[18:21], v[174:177], v[198:201], v[18:21]
	v_mfma_i32_16x16x64_i8 v[6:9], v[166:169], v[206:209], v[6:9]
	v_mfma_i32_16x16x64_i8 v[2:5], v[174:177], v[206:209], v[2:5]
	s_setprio 0
	s_barrier
	s_add_i32 s76, s76, 2
	s_add_u32 s50, s50, 0x100
	s_addc_u32 s51, s51, 0
	s_cmp_gt_u32 s76, 5
	s_cbranch_scc0 .LBB0_667
	s_cmpk_lt_u32 s17, 0x100
	s_cbranch_scc0 .LBB0_661
	s_barrier
	s_branch .LBB0_661

.LBB0_821:
	s_add_u32 s4, s79, s50
	s_addc_u32 s5, s82, s51
	s_add_u32 s46, s4, 0x9800100
	s_addc_u32 s47, s5, 0
	s_add_u32 s58, s64, s50
	s_addc_u32 s59, s83, s51
	s_add_i32 s85, 0, 0x10000
	s_cmpk_eq_i32 s50, 0x1500
	s_cselect_b32 s47, s49, s47
	s_cselect_b32 s46, s48, s46
	v_add_u32_e32 v0, s85, v134
	s_cselect_b32 s59, s71, s59
	s_cselect_b32 s58, s70, s58
	s_add_i32 s86, 0, 0x14000
	ds_read_b128 v[136:139], v0
	ds_read_b128 v[140:143], v0 offset:1024
	ds_read_b128 v[144:147], v0 offset:2048
	ds_read_b128 v[148:151], v0 offset:3072
	ds_read_b128 v[152:155], v0 offset:16384
	ds_read_b128 v[156:159], v0 offset:17408
	ds_read_b128 v[160:163], v0 offset:18432
	ds_read_b128 v[164:167], v0 offset:19456
	ds_read_b128 v[168:171], v135
	ds_read_b128 v[172:175], v135 offset:1024
	ds_read_b128 v[176:179], v135 offset:2048
	ds_read_b128 v[180:183], v135 offset:3072
	ds_read_b128 v[184:187], v135 offset:4096
	ds_read_b128 v[188:191], v135 offset:5120
	ds_read_b128 v[192:195], v135 offset:6144
	ds_read_b128 v[198:201], v135 offset:7168
	s_add_i32 m0, s60, 0xc000
	s_add_u32 s100, s4, s88
	s_addc_u32 s101, s5, s89
	global_load_lds_dwordx4 v130, s[100:101]
	s_add_i32 m0, s60, 0xe000
	s_nop 0
	global_load_lds_dwordx4 v131, s[100:101]
	s_waitcnt vmcnt(8)
	s_waitcnt lgkmcnt(0)
	s_barrier
	s_setprio 1
	s_waitcnt lgkmcnt(0)
	v_mfma_f32_16x16x32_bf16 v[126:129], v[136:139], v[168:171], v[126:129]
	v_mfma_f32_16x16x32_bf16 v[122:125], v[144:147], v[168:171], v[122:125]
	v_mfma_f32_16x16x32_bf16 v[110:113], v[136:139], v[176:179], v[110:113]
	v_mfma_f32_16x16x32_bf16 v[106:109], v[144:147], v[176:179], v[106:109]
	v_mfma_f32_16x16x32_bf16 v[94:97], v[136:139], v[184:187], v[94:97]
	v_mfma_f32_16x16x32_bf16 v[90:93], v[144:147], v[184:187], v[90:93]
	v_mfma_f32_16x16x32_bf16 v[78:81], v[136:139], v[192:195], v[78:81]
	v_mfma_f32_16x16x32_bf16 v[74:77], v[144:147], v[192:195], v[74:77]
	s_setprio 0
	s_setprio 1
	v_mfma_f32_16x16x32_bf16 v[126:129], v[140:143], v[172:175], v[126:129]
	v_mfma_f32_16x16x32_bf16 v[122:125], v[148:151], v[172:175], v[122:125]
	v_mfma_f32_16x16x32_bf16 v[110:113], v[140:143], v[180:183], v[110:113]
	v_mfma_f32_16x16x32_bf16 v[106:109], v[148:151], v[180:183], v[106:109]
	v_mfma_f32_16x16x32_bf16 v[94:97], v[140:143], v[188:191], v[94:97]
	v_mfma_f32_16x16x32_bf16 v[90:93], v[148:151], v[188:191], v[90:93]
	v_mfma_f32_16x16x32_bf16 v[78:81], v[140:143], v[198:201], v[78:81]
	v_mfma_f32_16x16x32_bf16 v[74:77], v[148:151], v[198:201], v[74:77]
	s_setprio 0
	s_setprio 1
	v_mfma_f32_16x16x32_bf16 v[118:121], v[152:155], v[168:171], v[118:121]
	v_mfma_f32_16x16x32_bf16 v[114:117], v[160:163], v[168:171], v[114:117]
	v_mfma_f32_16x16x32_bf16 v[102:105], v[152:155], v[176:179], v[102:105]
	v_mfma_f32_16x16x32_bf16 v[98:101], v[160:163], v[176:179], v[98:101]
	v_mfma_f32_16x16x32_bf16 v[86:89], v[152:155], v[184:187], v[86:89]
	v_mfma_f32_16x16x32_bf16 v[82:85], v[160:163], v[184:187], v[82:85]
	v_mfma_f32_16x16x32_bf16 v[70:73], v[152:155], v[192:195], v[70:73]
	v_mfma_f32_16x16x32_bf16 v[66:69], v[160:163], v[192:195], v[66:69]
	s_setprio 0
	s_setprio 1
	v_mfma_f32_16x16x32_bf16 v[118:121], v[156:159], v[172:175], v[118:121]
	v_mfma_f32_16x16x32_bf16 v[114:117], v[164:167], v[172:175], v[114:117]
	v_mfma_f32_16x16x32_bf16 v[102:105], v[156:159], v[180:183], v[102:105]
	v_mfma_f32_16x16x32_bf16 v[98:101], v[164:167], v[180:183], v[98:101]
	v_mfma_f32_16x16x32_bf16 v[86:89], v[156:159], v[188:191], v[86:89]
	v_mfma_f32_16x16x32_bf16 v[82:85], v[164:167], v[188:191], v[82:85]
	v_mfma_f32_16x16x32_bf16 v[70:73], v[156:159], v[198:201], v[70:73]
	v_mfma_f32_16x16x32_bf16 v[66:69], v[164:167], v[198:201], v[66:69]
	s_setprio 0
	s_barrier
	s_add_i32 s4, s85, s26
	ds_read_b128 v[168:171], v135 offset:16384
	ds_read_b128 v[172:175], v135 offset:17408
	ds_read_b128 v[176:179], v135 offset:18432
	ds_read_b128 v[180:183], v135 offset:19456
	ds_read_b128 v[184:187], v135 offset:20480
	ds_read_b128 v[188:191], v135 offset:21504
	ds_read_b128 v[192:195], v135 offset:22528
	ds_read_b128 v[198:201], v135 offset:23552
	s_mov_b32 m0, s4
	s_nop 0
	global_load_lds_dwordx4 v132, s[58:59]
	s_add_i32 m0, s4, 0x2000
	s_add_u32 s4, s58, 0xb0000
	global_load_lds_dwordx4 v133, s[58:59]
	s_addc_u32 s5, s59, 0
	s_add_i32 s85, s86, s26
	s_mov_b32 m0, s85
	s_nop 0
	global_load_lds_dwordx4 v132, s[4:5]
	s_add_i32 m0, s85, 0x2000
	s_nop 0
	global_load_lds_dwordx4 v133, s[4:5]
	s_mov_b32 m0, s60
	s_nop 0
	global_load_lds_dwordx4 v130, s[46:47]
	s_mov_b32 m0, s65
	s_nop 0
	global_load_lds_dwordx4 v131, s[46:47]
	s_waitcnt vmcnt(8)
	s_waitcnt lgkmcnt(0)
	s_barrier
	s_setprio 1
	s_waitcnt lgkmcnt(0)
	v_mfma_f32_16x16x32_bf16 v[62:65], v[136:139], v[168:171], v[62:65]
	v_mfma_f32_16x16x32_bf16 v[58:61], v[144:147], v[168:171], v[58:61]
	v_mfma_f32_16x16x32_bf16 v[46:49], v[136:139], v[176:179], v[46:49]
	v_mfma_f32_16x16x32_bf16 v[42:45], v[144:147], v[176:179], v[42:45]
	v_mfma_f32_16x16x32_bf16 v[30:33], v[136:139], v[184:187], v[30:33]
	v_mfma_f32_16x16x32_bf16 v[26:29], v[144:147], v[184:187], v[26:29]
	v_mfma_f32_16x16x32_bf16 v[14:17], v[136:139], v[192:195], v[14:17]
	v_mfma_f32_16x16x32_bf16 v[10:13], v[144:147], v[192:195], v[10:13]
	s_setprio 0
	s_setprio 1
	v_mfma_f32_16x16x32_bf16 v[62:65], v[140:143], v[172:175], v[62:65]
	v_mfma_f32_16x16x32_bf16 v[58:61], v[148:151], v[172:175], v[58:61]
	v_mfma_f32_16x16x32_bf16 v[46:49], v[140:143], v[180:183], v[46:49]
	v_mfma_f32_16x16x32_bf16 v[42:45], v[148:151], v[180:183], v[42:45]
	v_mfma_f32_16x16x32_bf16 v[30:33], v[140:143], v[188:191], v[30:33]
	v_mfma_f32_16x16x32_bf16 v[26:29], v[148:151], v[188:191], v[26:29]
	v_mfma_f32_16x16x32_bf16 v[14:17], v[140:143], v[198:201], v[14:17]
	v_mfma_f32_16x16x32_bf16 v[10:13], v[148:151], v[198:201], v[10:13]
	s_setprio 0
	s_setprio 1
	v_mfma_f32_16x16x32_bf16 v[54:57], v[152:155], v[168:171], v[54:57]
	v_mfma_f32_16x16x32_bf16 v[50:53], v[160:163], v[168:171], v[50:53]
	v_mfma_f32_16x16x32_bf16 v[38:41], v[152:155], v[176:179], v[38:41]
	v_mfma_f32_16x16x32_bf16 v[34:37], v[160:163], v[176:179], v[34:37]
	v_mfma_f32_16x16x32_bf16 v[22:25], v[152:155], v[184:187], v[22:25]
	v_mfma_f32_16x16x32_bf16 v[18:21], v[160:163], v[184:187], v[18:21]
	v_mfma_f32_16x16x32_bf16 v[6:9], v[152:155], v[192:195], v[6:9]
	v_mfma_f32_16x16x32_bf16 v[2:5], v[160:163], v[192:195], v[2:5]
	s_setprio 0
	s_setprio 1
	v_mfma_f32_16x16x32_bf16 v[54:57], v[156:159], v[172:175], v[54:57]
	v_mfma_f32_16x16x32_bf16 v[50:53], v[164:167], v[172:175], v[50:53]
	v_mfma_f32_16x16x32_bf16 v[38:41], v[156:159], v[180:183], v[38:41]
	v_mfma_f32_16x16x32_bf16 v[34:37], v[164:167], v[180:183], v[34:37]
	v_mfma_f32_16x16x32_bf16 v[22:25], v[156:159], v[188:191], v[22:25]
	v_mfma_f32_16x16x32_bf16 v[18:21], v[164:167], v[188:191], v[18:21]
	v_mfma_f32_16x16x32_bf16 v[6:9], v[156:159], v[198:201], v[6:9]
	v_mfma_f32_16x16x32_bf16 v[2:5], v[164:167], v[198:201], v[2:5]
	s_setprio 0
	s_barrier
	s_add_i32 s85, 0, 0x18000
	s_add_i32 s86, 0, 0x1c000
	ds_read_b128 v[136:139], v0 offset:32768
	ds_read_b128 v[140:143], v0 offset:33792
	ds_read_b128 v[144:147], v0 offset:34816
	ds_read_b128 v[148:151], v0 offset:35840
	ds_read_b128 v[152:155], v0 offset:49152
	ds_read_b128 v[156:159], v0 offset:50176
	ds_read_b128 v[160:163], v0 offset:51200
	ds_read_b128 v[164:167], v0 offset:52224
	s_add_u32 s4, s46, 0xb0000
	s_mov_b32 m0, s68
	ds_read_b128 v[168:171], v135 offset:32768
	ds_read_b128 v[172:175], v135 offset:33792
	ds_read_b128 v[176:179], v135 offset:34816
	ds_read_b128 v[180:183], v135 offset:35840
	ds_read_b128 v[184:187], v135 offset:36864
	ds_read_b128 v[188:191], v135 offset:37888
	ds_read_b128 v[192:195], v135 offset:38912
	ds_read_b128 v[198:201], v135 offset:39936
	s_addc_u32 s5, s47, 0
	s_nop 0
	global_load_lds_dwordx4 v130, s[4:5]
	s_mov_b32 m0, s69
	s_nop 0
	global_load_lds_dwordx4 v131, s[4:5]
	s_waitcnt vmcnt(8)
	s_waitcnt lgkmcnt(0)
	s_barrier
	s_setprio 1
	s_waitcnt lgkmcnt(0)
	v_mfma_f32_16x16x32_bf16 v[126:129], v[136:139], v[168:171], v[126:129]
	v_mfma_f32_16x16x32_bf16 v[122:125], v[144:147], v[168:171], v[122:125]
	v_mfma_f32_16x16x32_bf16 v[110:113], v[136:139], v[176:179], v[110:113]
	v_mfma_f32_16x16x32_bf16 v[106:109], v[144:147], v[176:179], v[106:109]
	v_mfma_f32_16x16x32_bf16 v[94:97], v[136:139], v[184:187], v[94:97]
	v_mfma_f32_16x16x32_bf16 v[90:93], v[144:147], v[184:187], v[90:93]
	v_mfma_f32_16x16x32_bf16 v[78:81], v[136:139], v[192:195], v[78:81]
	v_mfma_f32_16x16x32_bf16 v[74:77], v[144:147], v[192:195], v[74:77]
	s_setprio 0
	s_setprio 1
	v_mfma_f32_16x16x32_bf16 v[126:129], v[140:143], v[172:175], v[126:129]
	v_mfma_f32_16x16x32_bf16 v[122:125], v[148:151], v[172:175], v[122:125]
	v_mfma_f32_16x16x32_bf16 v[110:113], v[140:143], v[180:183], v[110:113]
	v_mfma_f32_16x16x32_bf16 v[106:109], v[148:151], v[180:183], v[106:109]
	v_mfma_f32_16x16x32_bf16 v[94:97], v[140:143], v[188:191], v[94:97]
	v_mfma_f32_16x16x32_bf16 v[90:93], v[148:151], v[188:191], v[90:93]
	v_mfma_f32_16x16x32_bf16 v[78:81], v[140:143], v[198:201], v[78:81]
	v_mfma_f32_16x16x32_bf16 v[74:77], v[148:151], v[198:201], v[74:77]
	s_setprio 0
	s_setprio 1
	v_mfma_f32_16x16x32_bf16 v[118:121], v[152:155], v[168:171], v[118:121]
	v_mfma_f32_16x16x32_bf16 v[114:117], v[160:163], v[168:171], v[114:117]
	v_mfma_f32_16x16x32_bf16 v[102:105], v[152:155], v[176:179], v[102:105]
	v_mfma_f32_16x16x32_bf16 v[98:101], v[160:163], v[176:179], v[98:101]
	v_mfma_f32_16x16x32_bf16 v[86:89], v[152:155], v[184:187], v[86:89]
	v_mfma_f32_16x16x32_bf16 v[82:85], v[160:163], v[184:187], v[82:85]
	v_mfma_f32_16x16x32_bf16 v[70:73], v[152:155], v[192:195], v[70:73]
	v_mfma_f32_16x16x32_bf16 v[66:69], v[160:163], v[192:195], v[66:69]
	s_setprio 0
	s_setprio 1
	v_mfma_f32_16x16x32_bf16 v[118:121], v[156:159], v[172:175], v[118:121]
	v_mfma_f32_16x16x32_bf16 v[114:117], v[164:167], v[172:175], v[114:117]
	v_mfma_f32_16x16x32_bf16 v[102:105], v[156:159], v[180:183], v[102:105]
	v_mfma_f32_16x16x32_bf16 v[98:101], v[164:167], v[180:183], v[98:101]
	v_mfma_f32_16x16x32_bf16 v[86:89], v[156:159], v[188:191], v[86:89]
	v_mfma_f32_16x16x32_bf16 v[82:85], v[164:167], v[188:191], v[82:85]
	v_mfma_f32_16x16x32_bf16 v[70:73], v[156:159], v[198:201], v[70:73]
	v_mfma_f32_16x16x32_bf16 v[66:69], v[164:167], v[198:201], v[66:69]
	s_setprio 0
	s_barrier
	ds_read_b128 v[168:171], v135 offset:49152
	ds_read_b128 v[172:175], v135 offset:50176
	ds_read_b128 v[176:179], v135 offset:51200
	ds_read_b128 v[180:183], v135 offset:52224
	ds_read_b128 v[184:187], v135 offset:53248
	ds_read_b128 v[188:191], v135 offset:54272
	ds_read_b128 v[192:195], v135 offset:55296
	ds_read_b128 v[198:201], v135 offset:56320
	s_add_i32 s4, s85, s26
	s_add_u32 s100, s58, s38
	s_addc_u32 s101, s59, s39
	s_mov_b32 m0, s4
	s_nop 0
	global_load_lds_dwordx4 v132, s[100:101]
	s_add_i32 m0, s4, 0x2000
	s_add_u32 s4, s58, 0xb0080
	s_addc_u32 s5, s59, 0
	s_add_i32 s58, s86, s26
	global_load_lds_dwordx4 v133, s[100:101]
	s_mov_b32 m0, s58
	s_nop 0
	global_load_lds_dwordx4 v132, s[4:5]
	s_add_i32 m0, s58, 0x2000
	s_nop 0
	global_load_lds_dwordx4 v133, s[4:5]
	s_mov_b32 m0, s75
	s_add_u32 s100, s46, s38
	s_addc_u32 s101, s47, s39
	v_mov_b32_e32 v0, v131
	global_load_lds_dwordx4 v130, s[100:101]
	s_mov_b32 m0, s78
	s_nop 0
	global_load_lds_dwordx4 v131, s[100:101]
	s_waitcnt vmcnt(8)
	s_waitcnt lgkmcnt(0)
	s_barrier
	s_setprio 1
	s_waitcnt lgkmcnt(0)
	v_mfma_f32_16x16x32_bf16 v[62:65], v[136:139], v[168:171], v[62:65]
	v_mfma_f32_16x16x32_bf16 v[58:61], v[144:147], v[168:171], v[58:61]
	v_mfma_f32_16x16x32_bf16 v[46:49], v[136:139], v[176:179], v[46:49]
	v_mfma_f32_16x16x32_bf16 v[42:45], v[144:147], v[176:179], v[42:45]
	v_mfma_f32_16x16x32_bf16 v[30:33], v[136:139], v[184:187], v[30:33]
	v_mfma_f32_16x16x32_bf16 v[26:29], v[144:147], v[184:187], v[26:29]
	v_mfma_f32_16x16x32_bf16 v[14:17], v[136:139], v[192:195], v[14:17]
	v_mfma_f32_16x16x32_bf16 v[10:13], v[144:147], v[192:195], v[10:13]
	s_setprio 0
	s_setprio 1
	v_mfma_f32_16x16x32_bf16 v[62:65], v[140:143], v[172:175], v[62:65]
	v_mfma_f32_16x16x32_bf16 v[58:61], v[148:151], v[172:175], v[58:61]
	v_mfma_f32_16x16x32_bf16 v[46:49], v[140:143], v[180:183], v[46:49]
	v_mfma_f32_16x16x32_bf16 v[42:45], v[148:151], v[180:183], v[42:45]
	v_mfma_f32_16x16x32_bf16 v[30:33], v[140:143], v[188:191], v[30:33]
	v_mfma_f32_16x16x32_bf16 v[26:29], v[148:151], v[188:191], v[26:29]
	v_mfma_f32_16x16x32_bf16 v[14:17], v[140:143], v[198:201], v[14:17]
	v_mfma_f32_16x16x32_bf16 v[10:13], v[148:151], v[198:201], v[10:13]
	s_setprio 0
	s_setprio 1
	v_mfma_f32_16x16x32_bf16 v[54:57], v[152:155], v[168:171], v[54:57]
	v_mfma_f32_16x16x32_bf16 v[50:53], v[160:163], v[168:171], v[50:53]
	v_mfma_f32_16x16x32_bf16 v[38:41], v[152:155], v[176:179], v[38:41]
	v_mfma_f32_16x16x32_bf16 v[34:37], v[160:163], v[176:179], v[34:37]
	v_mfma_f32_16x16x32_bf16 v[22:25], v[152:155], v[184:187], v[22:25]
	v_mfma_f32_16x16x32_bf16 v[18:21], v[160:163], v[184:187], v[18:21]
	v_mfma_f32_16x16x32_bf16 v[6:9], v[152:155], v[192:195], v[6:9]
	v_mfma_f32_16x16x32_bf16 v[2:5], v[160:163], v[192:195], v[2:5]
	s_setprio 0
	s_setprio 1
	v_mfma_f32_16x16x32_bf16 v[54:57], v[156:159], v[172:175], v[54:57]
	v_mfma_f32_16x16x32_bf16 v[50:53], v[164:167], v[172:175], v[50:53]
	v_mfma_f32_16x16x32_bf16 v[38:41], v[156:159], v[180:183], v[38:41]
	v_mfma_f32_16x16x32_bf16 v[34:37], v[164:167], v[180:183], v[34:37]
	v_mfma_f32_16x16x32_bf16 v[22:25], v[156:159], v[188:191], v[22:25]
	v_mfma_f32_16x16x32_bf16 v[18:21], v[164:167], v[188:191], v[18:21]
	v_mfma_f32_16x16x32_bf16 v[6:9], v[156:159], v[198:201], v[6:9]
	v_mfma_f32_16x16x32_bf16 v[2:5], v[164:167], v[198:201], v[2:5]
	s_setprio 0
	s_barrier
	s_add_i32 s84, s84, 2
	s_add_u32 s50, s50, 0x100
	s_addc_u32 s51, s51, 0
	s_cmp_gt_u32 s84, 41
	s_cbranch_scc0 .LBB0_821
	s_cmpk_lt_u32 s24, 0x100
	s_cbranch_scc0 .LBB0_824
	s_barrier

.LBB0_869:
	s_add_u32 s4, s10, s2
	s_addc_u32 s5, s11, s3
	s_add_u32 s22, s4, 0x100
	s_addc_u32 s23, s5, 0
	s_add_u32 s46, s58, s2
	s_addc_u32 s47, s59, s3
	s_add_i32 s69, 0, 0x10000
	s_cmp_eq_u32 s68, 40
	s_cselect_b32 s23, s11, s23
	s_cselect_b32 s22, s10, s22
	v_add_u32_e32 v0, s69, v126
	s_cselect_b32 s47, s17, s47
	s_cselect_b32 s46, s16, s46
	s_add_i32 s70, 0, 0x14000
	ds_read_b128 v[128:131], v0
	ds_read_b128 v[142:145], v0 offset:1024
	ds_read_b128 v[146:149], v0 offset:2048
	ds_read_b128 v[150:153], v0 offset:3072
	ds_read_b128 v[154:157], v0 offset:16384
	ds_read_b128 v[160:163], v0 offset:17408
	ds_read_b128 v[164:167], v0 offset:18432
	ds_read_b128 v[168:171], v0 offset:19456
	ds_read_b128 v[172:175], v127
	ds_read_b128 v[176:179], v127 offset:1024
	ds_read_b128 v[180:183], v127 offset:2048
	ds_read_b128 v[184:187], v127 offset:3072
	ds_read_b128 v[188:191], v127 offset:4096
	ds_read_b128 v[192:195], v127 offset:5120
	ds_read_b128 v[196:199], v127 offset:6144
	ds_read_b128 v[200:203], v127 offset:7168
	s_add_i32 m0, s41, 0xc000
	s_add_u32 s100, s4, s62
	s_addc_u32 s101, s5, s63
	global_load_lds_dwordx4 v122, s[100:101]
	s_add_i32 m0, s41, 0xe000
	s_nop 0
	global_load_lds_dwordx4 v123, s[100:101]
	s_waitcnt vmcnt(8)
	s_waitcnt lgkmcnt(0)
	s_barrier
	s_setprio 1
	s_waitcnt lgkmcnt(0)
	v_mfma_f32_16x16x32_bf16 v[138:141], v[128:131], v[172:175], v[138:141]
	v_mfma_f32_16x16x32_bf16 v[132:135], v[146:149], v[172:175], v[134:137]
	v_mfma_f32_16x16x32_bf16 v[110:113], v[128:131], v[180:183], v[110:113]
	v_mfma_f32_16x16x32_bf16 v[106:109], v[146:149], v[180:183], v[106:109]
	v_mfma_f32_16x16x32_bf16 v[94:97], v[128:131], v[188:191], v[94:97]
	v_mfma_f32_16x16x32_bf16 v[90:93], v[146:149], v[188:191], v[90:93]
	v_mfma_f32_16x16x32_bf16 v[78:81], v[128:131], v[196:199], v[78:81]
	v_mfma_f32_16x16x32_bf16 v[74:77], v[146:149], v[196:199], v[74:77]
	s_setprio 0
	s_setprio 1
	v_mfma_f32_16x16x32_bf16 v[138:141], v[142:145], v[176:179], v[138:141]
	v_mfma_f32_16x16x32_bf16 v[132:135], v[150:153], v[176:179], v[132:135]
	v_mfma_f32_16x16x32_bf16 v[110:113], v[142:145], v[184:187], v[110:113]
	v_mfma_f32_16x16x32_bf16 v[106:109], v[150:153], v[184:187], v[106:109]
	v_mfma_f32_16x16x32_bf16 v[94:97], v[142:145], v[192:195], v[94:97]
	v_mfma_f32_16x16x32_bf16 v[90:93], v[150:153], v[192:195], v[90:93]
	v_mfma_f32_16x16x32_bf16 v[78:81], v[142:145], v[200:203], v[78:81]
	v_mfma_f32_16x16x32_bf16 v[74:77], v[150:153], v[200:203], v[74:77]
	s_setprio 0
	s_setprio 1
	v_mfma_f32_16x16x32_bf16 v[118:121], v[154:157], v[172:175], v[118:121]
	v_mfma_f32_16x16x32_bf16 v[114:117], v[164:167], v[172:175], v[114:117]
	v_mfma_f32_16x16x32_bf16 v[102:105], v[154:157], v[180:183], v[102:105]
	v_mfma_f32_16x16x32_bf16 v[98:101], v[164:167], v[180:183], v[98:101]
	v_mfma_f32_16x16x32_bf16 v[86:89], v[154:157], v[188:191], v[86:89]
	v_mfma_f32_16x16x32_bf16 v[82:85], v[164:167], v[188:191], v[82:85]
	v_mfma_f32_16x16x32_bf16 v[70:73], v[154:157], v[196:199], v[70:73]
	v_mfma_f32_16x16x32_bf16 v[66:69], v[164:167], v[196:199], v[66:69]
	s_setprio 0
	s_setprio 1
	v_mfma_f32_16x16x32_bf16 v[118:121], v[160:163], v[176:179], v[118:121]
	v_mfma_f32_16x16x32_bf16 v[114:117], v[168:171], v[176:179], v[114:117]
	v_mfma_f32_16x16x32_bf16 v[102:105], v[160:163], v[184:187], v[102:105]
	v_mfma_f32_16x16x32_bf16 v[98:101], v[168:171], v[184:187], v[98:101]
	v_mfma_f32_16x16x32_bf16 v[86:89], v[160:163], v[192:195], v[86:89]
	v_mfma_f32_16x16x32_bf16 v[82:85], v[168:171], v[192:195], v[82:85]
	v_mfma_f32_16x16x32_bf16 v[70:73], v[160:163], v[200:203], v[70:73]
	v_mfma_f32_16x16x32_bf16 v[66:69], v[168:171], v[200:203], v[66:69]
	s_setprio 0
	s_barrier
	s_add_i32 s4, s69, s26
	ds_read_b128 v[172:175], v127 offset:16384
	ds_read_b128 v[176:179], v127 offset:17408
	ds_read_b128 v[180:183], v127 offset:18432
	ds_read_b128 v[184:187], v127 offset:19456
	ds_read_b128 v[188:191], v127 offset:20480
	ds_read_b128 v[192:195], v127 offset:21504
	ds_read_b128 v[196:199], v127 offset:22528
	ds_read_b128 v[200:203], v127 offset:23552
	s_mov_b32 m0, s4
	s_nop 0
	global_load_lds_dwordx4 v124, s[46:47]
	s_add_i32 m0, s4, 0x2000
	s_add_u32 s4, s46, 0xb0000
	global_load_lds_dwordx4 v125, s[46:47]
	s_addc_u32 s5, s47, 0
	s_add_i32 s69, s70, s26
	s_mov_b32 m0, s69
	s_nop 0
	global_load_lds_dwordx4 v124, s[4:5]
	s_add_i32 m0, s69, 0x2000
	s_nop 0
	global_load_lds_dwordx4 v125, s[4:5]
	s_mov_b32 m0, s41
	s_nop 0
	global_load_lds_dwordx4 v122, s[22:23]
	s_mov_b32 m0, s48
	s_nop 0
	global_load_lds_dwordx4 v123, s[22:23]
	s_waitcnt vmcnt(8)
	s_waitcnt lgkmcnt(0)
	s_barrier
	s_setprio 1
	s_waitcnt lgkmcnt(0)
	v_mfma_f32_16x16x32_bf16 v[62:65], v[128:131], v[172:175], v[62:65]
	v_mfma_f32_16x16x32_bf16 v[58:61], v[146:149], v[172:175], v[58:61]
	v_mfma_f32_16x16x32_bf16 v[46:49], v[128:131], v[180:183], v[46:49]
	v_mfma_f32_16x16x32_bf16 v[42:45], v[146:149], v[180:183], v[42:45]
	v_mfma_f32_16x16x32_bf16 v[30:33], v[128:131], v[188:191], v[30:33]
	v_mfma_f32_16x16x32_bf16 v[26:29], v[146:149], v[188:191], v[26:29]
	v_mfma_f32_16x16x32_bf16 v[14:17], v[128:131], v[196:199], v[14:17]
	v_mfma_f32_16x16x32_bf16 v[10:13], v[146:149], v[196:199], v[10:13]
	s_setprio 0
	s_setprio 1
	v_mfma_f32_16x16x32_bf16 v[62:65], v[142:145], v[176:179], v[62:65]
	v_mfma_f32_16x16x32_bf16 v[58:61], v[150:153], v[176:179], v[58:61]
	v_mfma_f32_16x16x32_bf16 v[46:49], v[142:145], v[184:187], v[46:49]
	v_mfma_f32_16x16x32_bf16 v[42:45], v[150:153], v[184:187], v[42:45]
	v_mfma_f32_16x16x32_bf16 v[30:33], v[142:145], v[192:195], v[30:33]
	v_mfma_f32_16x16x32_bf16 v[26:29], v[150:153], v[192:195], v[26:29]
	v_mfma_f32_16x16x32_bf16 v[14:17], v[142:145], v[200:203], v[14:17]
	v_mfma_f32_16x16x32_bf16 v[10:13], v[150:153], v[200:203], v[10:13]
	s_setprio 0
	s_setprio 1
	v_mfma_f32_16x16x32_bf16 v[54:57], v[154:157], v[172:175], v[54:57]
	v_mfma_f32_16x16x32_bf16 v[50:53], v[164:167], v[172:175], v[50:53]
	v_mfma_f32_16x16x32_bf16 v[38:41], v[154:157], v[180:183], v[38:41]
	v_mfma_f32_16x16x32_bf16 v[34:37], v[164:167], v[180:183], v[34:37]
	v_mfma_f32_16x16x32_bf16 v[22:25], v[154:157], v[188:191], v[22:25]
	v_mfma_f32_16x16x32_bf16 v[18:21], v[164:167], v[188:191], v[18:21]
	v_mfma_f32_16x16x32_bf16 v[6:9], v[154:157], v[196:199], v[6:9]
	v_mfma_f32_16x16x32_bf16 v[2:5], v[164:167], v[196:199], v[2:5]
	s_setprio 0
	s_setprio 1
	v_mfma_f32_16x16x32_bf16 v[54:57], v[160:163], v[176:179], v[54:57]
	v_mfma_f32_16x16x32_bf16 v[50:53], v[168:171], v[176:179], v[50:53]
	v_mfma_f32_16x16x32_bf16 v[38:41], v[160:163], v[184:187], v[38:41]
	v_mfma_f32_16x16x32_bf16 v[34:37], v[168:171], v[184:187], v[34:37]
	v_mfma_f32_16x16x32_bf16 v[22:25], v[160:163], v[192:195], v[22:25]
	v_mfma_f32_16x16x32_bf16 v[18:21], v[168:171], v[192:195], v[18:21]
	v_mfma_f32_16x16x32_bf16 v[6:9], v[160:163], v[200:203], v[6:9]
	v_mfma_f32_16x16x32_bf16 v[2:5], v[168:171], v[200:203], v[2:5]
	s_setprio 0
	s_barrier
	s_add_i32 s69, 0, 0x18000
	s_add_i32 s70, 0, 0x1c000
	ds_read_b128 v[128:131], v0 offset:32768
	ds_read_b128 v[142:145], v0 offset:33792
	ds_read_b128 v[146:149], v0 offset:34816
	ds_read_b128 v[150:153], v0 offset:35840
	ds_read_b128 v[154:157], v0 offset:49152
	ds_read_b128 v[160:163], v0 offset:50176
	ds_read_b128 v[164:167], v0 offset:51200
	ds_read_b128 v[168:171], v0 offset:52224
	s_add_u32 s4, s22, 0xb0000
	s_mov_b32 m0, s49
	ds_read_b128 v[172:175], v127 offset:32768
	ds_read_b128 v[176:179], v127 offset:33792
	ds_read_b128 v[180:183], v127 offset:34816
	ds_read_b128 v[184:187], v127 offset:35840
	ds_read_b128 v[188:191], v127 offset:36864
	ds_read_b128 v[192:195], v127 offset:37888
	ds_read_b128 v[196:199], v127 offset:38912
	ds_read_b128 v[200:203], v127 offset:39936
	s_addc_u32 s5, s23, 0
	s_nop 0
	global_load_lds_dwordx4 v122, s[4:5]
	s_mov_b32 m0, s50
	s_nop 0
	global_load_lds_dwordx4 v123, s[4:5]
	s_waitcnt vmcnt(8)
	s_waitcnt lgkmcnt(0)
	s_barrier
	s_setprio 1
	s_waitcnt lgkmcnt(0)
	v_mfma_f32_16x16x32_bf16 v[136:139], v[128:131], v[172:175], v[138:141]
	v_mfma_f32_16x16x32_bf16 v[132:135], v[146:149], v[172:175], v[132:135]
	v_mfma_f32_16x16x32_bf16 v[110:113], v[128:131], v[180:183], v[110:113]
	v_mfma_f32_16x16x32_bf16 v[106:109], v[146:149], v[180:183], v[106:109]
	v_mfma_f32_16x16x32_bf16 v[94:97], v[128:131], v[188:191], v[94:97]
	v_mfma_f32_16x16x32_bf16 v[90:93], v[146:149], v[188:191], v[90:93]
	v_mfma_f32_16x16x32_bf16 v[78:81], v[128:131], v[196:199], v[78:81]
	v_mfma_f32_16x16x32_bf16 v[74:77], v[146:149], v[196:199], v[74:77]
	s_setprio 0
	s_setprio 1
	v_mfma_f32_16x16x32_bf16 v[138:141], v[142:145], v[176:179], v[136:139]
	v_mfma_f32_16x16x32_bf16 v[134:137], v[150:153], v[176:179], v[132:135]
	v_mfma_f32_16x16x32_bf16 v[110:113], v[142:145], v[184:187], v[110:113]
	v_mfma_f32_16x16x32_bf16 v[106:109], v[150:153], v[184:187], v[106:109]
	v_mfma_f32_16x16x32_bf16 v[94:97], v[142:145], v[192:195], v[94:97]
	v_mfma_f32_16x16x32_bf16 v[90:93], v[150:153], v[192:195], v[90:93]
	v_mfma_f32_16x16x32_bf16 v[78:81], v[142:145], v[200:203], v[78:81]
	v_mfma_f32_16x16x32_bf16 v[74:77], v[150:153], v[200:203], v[74:77]
	s_setprio 0
	s_setprio 1
	v_mfma_f32_16x16x32_bf16 v[118:121], v[154:157], v[172:175], v[118:121]
	v_mfma_f32_16x16x32_bf16 v[114:117], v[164:167], v[172:175], v[114:117]
	v_mfma_f32_16x16x32_bf16 v[102:105], v[154:157], v[180:183], v[102:105]
	v_mfma_f32_16x16x32_bf16 v[98:101], v[164:167], v[180:183], v[98:101]
	v_mfma_f32_16x16x32_bf16 v[86:89], v[154:157], v[188:191], v[86:89]
	v_mfma_f32_16x16x32_bf16 v[82:85], v[164:167], v[188:191], v[82:85]
	v_mfma_f32_16x16x32_bf16 v[70:73], v[154:157], v[196:199], v[70:73]
	v_mfma_f32_16x16x32_bf16 v[66:69], v[164:167], v[196:199], v[66:69]
	s_setprio 0
	s_setprio 1
	v_mfma_f32_16x16x32_bf16 v[118:121], v[160:163], v[176:179], v[118:121]
	v_mfma_f32_16x16x32_bf16 v[114:117], v[168:171], v[176:179], v[114:117]
	v_mfma_f32_16x16x32_bf16 v[102:105], v[160:163], v[184:187], v[102:105]
	v_mfma_f32_16x16x32_bf16 v[98:101], v[168:171], v[184:187], v[98:101]
	v_mfma_f32_16x16x32_bf16 v[86:89], v[160:163], v[192:195], v[86:89]
	v_mfma_f32_16x16x32_bf16 v[82:85], v[168:171], v[192:195], v[82:85]
	v_mfma_f32_16x16x32_bf16 v[70:73], v[160:163], v[200:203], v[70:73]
	v_mfma_f32_16x16x32_bf16 v[66:69], v[168:171], v[200:203], v[66:69]
	s_setprio 0
	s_barrier
	ds_read_b128 v[172:175], v127 offset:49152
	ds_read_b128 v[176:179], v127 offset:50176
	ds_read_b128 v[180:183], v127 offset:51200
	ds_read_b128 v[184:187], v127 offset:52224
	ds_read_b128 v[188:191], v127 offset:53248
	ds_read_b128 v[192:195], v127 offset:54272
	ds_read_b128 v[196:199], v127 offset:55296
	ds_read_b128 v[200:203], v127 offset:56320
	s_add_i32 s4, s69, s26
	s_add_u32 s100, s46, s38
	s_addc_u32 s101, s47, s39
	s_mov_b32 m0, s4
	s_nop 0
	global_load_lds_dwordx4 v124, s[100:101]
	s_add_i32 m0, s4, 0x2000
	s_add_u32 s4, s46, 0xb0080
	s_addc_u32 s5, s47, 0
	s_add_i32 s46, s70, s26
	global_load_lds_dwordx4 v125, s[100:101]
	s_mov_b32 m0, s46
	s_nop 0
	global_load_lds_dwordx4 v124, s[4:5]
	s_add_i32 m0, s46, 0x2000
	s_nop 0
	global_load_lds_dwordx4 v125, s[4:5]
	s_mov_b32 m0, s64
	s_add_u32 s100, s22, s38
	s_addc_u32 s101, s23, s39
	v_mov_b32_e32 v0, v123
	global_load_lds_dwordx4 v122, s[100:101]
	s_mov_b32 m0, s65
	s_nop 0
	global_load_lds_dwordx4 v123, s[100:101]
	s_waitcnt vmcnt(8)
	s_waitcnt lgkmcnt(0)
	s_barrier
	s_setprio 1
	s_waitcnt lgkmcnt(0)
	v_mfma_f32_16x16x32_bf16 v[62:65], v[128:131], v[172:175], v[62:65]
	v_mfma_f32_16x16x32_bf16 v[58:61], v[146:149], v[172:175], v[58:61]
	v_mfma_f32_16x16x32_bf16 v[46:49], v[128:131], v[180:183], v[46:49]
	v_mfma_f32_16x16x32_bf16 v[42:45], v[146:149], v[180:183], v[42:45]
	v_mfma_f32_16x16x32_bf16 v[30:33], v[128:131], v[188:191], v[30:33]
	v_mfma_f32_16x16x32_bf16 v[26:29], v[146:149], v[188:191], v[26:29]
	v_mfma_f32_16x16x32_bf16 v[14:17], v[128:131], v[196:199], v[14:17]
	v_mfma_f32_16x16x32_bf16 v[10:13], v[146:149], v[196:199], v[10:13]
	s_setprio 0
	s_setprio 1
	v_mfma_f32_16x16x32_bf16 v[62:65], v[142:145], v[176:179], v[62:65]
	v_mfma_f32_16x16x32_bf16 v[58:61], v[150:153], v[176:179], v[58:61]
	v_mfma_f32_16x16x32_bf16 v[46:49], v[142:145], v[184:187], v[46:49]
	v_mfma_f32_16x16x32_bf16 v[42:45], v[150:153], v[184:187], v[42:45]
	v_mfma_f32_16x16x32_bf16 v[30:33], v[142:145], v[192:195], v[30:33]
	v_mfma_f32_16x16x32_bf16 v[26:29], v[150:153], v[192:195], v[26:29]
	v_mfma_f32_16x16x32_bf16 v[14:17], v[142:145], v[200:203], v[14:17]
	v_mfma_f32_16x16x32_bf16 v[10:13], v[150:153], v[200:203], v[10:13]
	s_setprio 0
	s_setprio 1
	v_mfma_f32_16x16x32_bf16 v[54:57], v[154:157], v[172:175], v[54:57]
	v_mfma_f32_16x16x32_bf16 v[50:53], v[164:167], v[172:175], v[50:53]
	v_mfma_f32_16x16x32_bf16 v[38:41], v[154:157], v[180:183], v[38:41]
	v_mfma_f32_16x16x32_bf16 v[34:37], v[164:167], v[180:183], v[34:37]
	v_mfma_f32_16x16x32_bf16 v[22:25], v[154:157], v[188:191], v[22:25]
	v_mfma_f32_16x16x32_bf16 v[18:21], v[164:167], v[188:191], v[18:21]
	v_mfma_f32_16x16x32_bf16 v[6:9], v[154:157], v[196:199], v[6:9]
	v_mfma_f32_16x16x32_bf16 v[2:5], v[164:167], v[196:199], v[2:5]
	s_setprio 0
	s_setprio 1
	v_mfma_f32_16x16x32_bf16 v[54:57], v[160:163], v[176:179], v[54:57]
	v_mfma_f32_16x16x32_bf16 v[50:53], v[168:171], v[176:179], v[50:53]
	v_mfma_f32_16x16x32_bf16 v[38:41], v[160:163], v[184:187], v[38:41]
	v_mfma_f32_16x16x32_bf16 v[34:37], v[168:171], v[184:187], v[34:37]
	v_mfma_f32_16x16x32_bf16 v[22:25], v[160:163], v[192:195], v[22:25]
	v_mfma_f32_16x16x32_bf16 v[18:21], v[168:171], v[192:195], v[18:21]
	v_mfma_f32_16x16x32_bf16 v[6:9], v[160:163], v[200:203], v[6:9]
	v_mfma_f32_16x16x32_bf16 v[2:5], v[168:171], v[200:203], v[2:5]
	s_setprio 0
	s_barrier
	s_add_i32 s68, s68, 2
	s_add_u32 s2, s2, 0x100
	s_addc_u32 s3, s3, 0
	s_cmp_gt_u32 s68, 41
	s_cbranch_scc0 .LBB0_869
	s_cmpk_lt_u32 s25, 0x100
	s_cbranch_scc0 .LBB0_872
	s_barrier

.LBB0_953:
	s_add_u32 s58, s4, s2
	s_addc_u32 s59, s5, s3
	s_add_u32 s14, s58, 0x100
	s_addc_u32 s15, s59, 0
	s_add_u32 s16, s43, s2
	s_addc_u32 s17, s46, s3
	s_add_i32 s51, 0, 0x10000
	s_cmp_eq_u32 s50, 40
	s_cselect_b32 s15, s5, s15
	s_cselect_b32 s14, s4, s14
	v_add_u32_e32 v0, s51, v135
	s_cselect_b32 s17, s7, s17
	s_cselect_b32 s16, s6, s16
	s_add_i32 s60, 0, 0x14000
	ds_read_b128 v[138:141], v0
	ds_read_b128 v[142:145], v0 offset:1024
	ds_read_b128 v[146:149], v0 offset:2048
	ds_read_b128 v[150:153], v0 offset:3072
	ds_read_b128 v[154:157], v0 offset:16384
	ds_read_b128 v[158:161], v0 offset:17408
	ds_read_b128 v[162:165], v0 offset:18432
	ds_read_b128 v[166:169], v0 offset:19456
	ds_read_b128 v[170:173], v136
	ds_read_b128 v[174:177], v136 offset:1024
	ds_read_b128 v[178:181], v136 offset:2048
	ds_read_b128 v[182:185], v136 offset:3072
	ds_read_b128 v[186:189], v136 offset:4096
	ds_read_b128 v[190:193], v136 offset:5120
	ds_read_b128 v[194:197], v136 offset:6144
	ds_read_b128 v[198:201], v136 offset:7168
	s_add_i32 m0, s37, 0xc000
	s_add_u32 s100, s58, s62
	s_addc_u32 s101, s59, s63
	global_load_lds_dwordx4 v130, s[100:101]
	s_add_i32 m0, s37, 0xe000
	s_nop 0
	global_load_lds_dwordx4 v131, s[100:101]
	s_waitcnt vmcnt(8)
	s_waitcnt lgkmcnt(0)
	s_barrier
	s_setprio 1
	s_waitcnt lgkmcnt(0)
	v_mfma_f32_16x16x32_bf16 v[126:129], v[138:141], v[170:173], v[126:129]
	v_mfma_f32_16x16x32_bf16 v[122:125], v[146:149], v[170:173], v[122:125]
	v_mfma_f32_16x16x32_bf16 v[110:113], v[138:141], v[178:181], v[110:113]
	v_mfma_f32_16x16x32_bf16 v[106:109], v[146:149], v[178:181], v[106:109]
	v_mfma_f32_16x16x32_bf16 v[94:97], v[138:141], v[186:189], v[94:97]
	v_mfma_f32_16x16x32_bf16 v[90:93], v[146:149], v[186:189], v[90:93]
	v_mfma_f32_16x16x32_bf16 v[78:81], v[138:141], v[194:197], v[78:81]
	v_mfma_f32_16x16x32_bf16 v[74:77], v[146:149], v[194:197], v[74:77]
	s_setprio 0
	s_setprio 1
	v_mfma_f32_16x16x32_bf16 v[126:129], v[142:145], v[174:177], v[126:129]
	v_mfma_f32_16x16x32_bf16 v[122:125], v[150:153], v[174:177], v[122:125]
	v_mfma_f32_16x16x32_bf16 v[110:113], v[142:145], v[182:185], v[110:113]
	v_mfma_f32_16x16x32_bf16 v[106:109], v[150:153], v[182:185], v[106:109]
	v_mfma_f32_16x16x32_bf16 v[94:97], v[142:145], v[190:193], v[94:97]
	v_mfma_f32_16x16x32_bf16 v[90:93], v[150:153], v[190:193], v[90:93]
	v_mfma_f32_16x16x32_bf16 v[78:81], v[142:145], v[198:201], v[78:81]
	v_mfma_f32_16x16x32_bf16 v[74:77], v[150:153], v[198:201], v[74:77]
	s_setprio 0
	s_setprio 1
	v_mfma_f32_16x16x32_bf16 v[118:121], v[154:157], v[170:173], v[118:121]
	v_mfma_f32_16x16x32_bf16 v[114:117], v[162:165], v[170:173], v[114:117]
	v_mfma_f32_16x16x32_bf16 v[102:105], v[154:157], v[178:181], v[102:105]
	v_mfma_f32_16x16x32_bf16 v[98:101], v[162:165], v[178:181], v[98:101]
	v_mfma_f32_16x16x32_bf16 v[86:89], v[154:157], v[186:189], v[86:89]
	v_mfma_f32_16x16x32_bf16 v[82:85], v[162:165], v[186:189], v[82:85]
	v_mfma_f32_16x16x32_bf16 v[70:73], v[154:157], v[194:197], v[70:73]
	v_mfma_f32_16x16x32_bf16 v[66:69], v[162:165], v[194:197], v[66:69]
	s_setprio 0
	s_setprio 1
	v_mfma_f32_16x16x32_bf16 v[118:121], v[158:161], v[174:177], v[118:121]
	v_mfma_f32_16x16x32_bf16 v[114:117], v[166:169], v[174:177], v[114:117]
	v_mfma_f32_16x16x32_bf16 v[102:105], v[158:161], v[182:185], v[102:105]
	v_mfma_f32_16x16x32_bf16 v[98:101], v[166:169], v[182:185], v[98:101]
	v_mfma_f32_16x16x32_bf16 v[86:89], v[158:161], v[190:193], v[86:89]
	v_mfma_f32_16x16x32_bf16 v[82:85], v[166:169], v[190:193], v[82:85]
	v_mfma_f32_16x16x32_bf16 v[70:73], v[158:161], v[198:201], v[70:73]
	v_mfma_f32_16x16x32_bf16 v[66:69], v[166:169], v[198:201], v[66:69]
	s_setprio 0
	s_barrier
	s_add_i32 s51, s51, s26
	ds_read_b128 v[170:173], v136 offset:16384
	ds_read_b128 v[174:177], v136 offset:17408
	ds_read_b128 v[178:181], v136 offset:18432
	ds_read_b128 v[182:185], v136 offset:19456
	ds_read_b128 v[186:189], v136 offset:20480
	ds_read_b128 v[190:193], v136 offset:21504
	ds_read_b128 v[194:197], v136 offset:22528
	ds_read_b128 v[198:201], v136 offset:23552
	s_mov_b32 m0, s51
	s_nop 0
	global_load_lds_dwordx4 v133, s[16:17]
	s_add_i32 m0, s51, 0x2000
	s_add_u32 s58, s16, 0xb0000
	global_load_lds_dwordx4 v134, s[16:17]
	s_addc_u32 s59, s17, 0
	s_add_i32 s51, s60, s26
	s_mov_b32 m0, s51
	s_nop 0
	global_load_lds_dwordx4 v133, s[58:59]
	s_add_i32 m0, s51, 0x2000
	s_nop 0
	global_load_lds_dwordx4 v134, s[58:59]
	s_mov_b32 m0, s37
	s_nop 0
	global_load_lds_dwordx4 v130, s[14:15]
	s_mov_b32 m0, s40
	s_nop 0
	global_load_lds_dwordx4 v131, s[14:15]
	s_waitcnt vmcnt(8)
	s_waitcnt lgkmcnt(0)
	s_barrier
	s_setprio 1
	s_waitcnt lgkmcnt(0)
	v_mfma_f32_16x16x32_bf16 v[62:65], v[138:141], v[170:173], v[62:65]
	v_mfma_f32_16x16x32_bf16 v[58:61], v[146:149], v[170:173], v[58:61]
	v_mfma_f32_16x16x32_bf16 v[46:49], v[138:141], v[178:181], v[46:49]
	v_mfma_f32_16x16x32_bf16 v[42:45], v[146:149], v[178:181], v[42:45]
	v_mfma_f32_16x16x32_bf16 v[30:33], v[138:141], v[186:189], v[30:33]
	v_mfma_f32_16x16x32_bf16 v[26:29], v[146:149], v[186:189], v[26:29]
	v_mfma_f32_16x16x32_bf16 v[14:17], v[138:141], v[194:197], v[14:17]
	v_mfma_f32_16x16x32_bf16 v[10:13], v[146:149], v[194:197], v[10:13]
	s_setprio 0
	s_setprio 1
	v_mfma_f32_16x16x32_bf16 v[62:65], v[142:145], v[174:177], v[62:65]
	v_mfma_f32_16x16x32_bf16 v[58:61], v[150:153], v[174:177], v[58:61]
	v_mfma_f32_16x16x32_bf16 v[46:49], v[142:145], v[182:185], v[46:49]
	v_mfma_f32_16x16x32_bf16 v[42:45], v[150:153], v[182:185], v[42:45]
	v_mfma_f32_16x16x32_bf16 v[30:33], v[142:145], v[190:193], v[30:33]
	v_mfma_f32_16x16x32_bf16 v[26:29], v[150:153], v[190:193], v[26:29]
	v_mfma_f32_16x16x32_bf16 v[14:17], v[142:145], v[198:201], v[14:17]
	v_mfma_f32_16x16x32_bf16 v[10:13], v[150:153], v[198:201], v[10:13]
	s_setprio 0
	s_setprio 1
	v_mfma_f32_16x16x32_bf16 v[54:57], v[154:157], v[170:173], v[54:57]
	v_mfma_f32_16x16x32_bf16 v[50:53], v[162:165], v[170:173], v[50:53]
	v_mfma_f32_16x16x32_bf16 v[38:41], v[154:157], v[178:181], v[38:41]
	v_mfma_f32_16x16x32_bf16 v[34:37], v[162:165], v[178:181], v[34:37]
	v_mfma_f32_16x16x32_bf16 v[22:25], v[154:157], v[186:189], v[22:25]
	v_mfma_f32_16x16x32_bf16 v[18:21], v[162:165], v[186:189], v[18:21]
	v_mfma_f32_16x16x32_bf16 v[6:9], v[154:157], v[194:197], v[6:9]
	v_mfma_f32_16x16x32_bf16 v[2:5], v[162:165], v[194:197], v[2:5]
	s_setprio 0
	s_setprio 1
	v_mfma_f32_16x16x32_bf16 v[54:57], v[158:161], v[174:177], v[54:57]
	v_mfma_f32_16x16x32_bf16 v[50:53], v[166:169], v[174:177], v[50:53]
	v_mfma_f32_16x16x32_bf16 v[38:41], v[158:161], v[182:185], v[38:41]
	v_mfma_f32_16x16x32_bf16 v[34:37], v[166:169], v[182:185], v[34:37]
	v_mfma_f32_16x16x32_bf16 v[22:25], v[158:161], v[190:193], v[22:25]
	v_mfma_f32_16x16x32_bf16 v[18:21], v[166:169], v[190:193], v[18:21]
	v_mfma_f32_16x16x32_bf16 v[6:9], v[158:161], v[198:201], v[6:9]
	v_mfma_f32_16x16x32_bf16 v[2:5], v[166:169], v[198:201], v[2:5]
	s_setprio 0
	s_barrier
	s_add_i32 s51, 0, 0x18000
	s_add_i32 s60, 0, 0x1c000
	ds_read_b128 v[138:141], v0 offset:32768
	ds_read_b128 v[142:145], v0 offset:33792
	ds_read_b128 v[146:149], v0 offset:34816
	ds_read_b128 v[150:153], v0 offset:35840
	ds_read_b128 v[154:157], v0 offset:49152
	ds_read_b128 v[158:161], v0 offset:50176
	ds_read_b128 v[162:165], v0 offset:51200
	ds_read_b128 v[166:169], v0 offset:52224
	s_add_u32 s58, s14, 0xb0000
	s_mov_b32 m0, s41
	ds_read_b128 v[170:173], v136 offset:32768
	ds_read_b128 v[174:177], v136 offset:33792
	ds_read_b128 v[178:181], v136 offset:34816
	ds_read_b128 v[182:185], v136 offset:35840
	ds_read_b128 v[186:189], v136 offset:36864
	ds_read_b128 v[190:193], v136 offset:37888
	ds_read_b128 v[194:197], v136 offset:38912
	ds_read_b128 v[198:201], v136 offset:39936
	s_addc_u32 s59, s15, 0
	s_nop 0
	global_load_lds_dwordx4 v130, s[58:59]
	s_mov_b32 m0, s42
	s_nop 0
	global_load_lds_dwordx4 v131, s[58:59]
	s_waitcnt vmcnt(8)
	s_waitcnt lgkmcnt(0)
	s_barrier
	s_setprio 1
	s_waitcnt lgkmcnt(0)
	v_mfma_f32_16x16x32_bf16 v[126:129], v[138:141], v[170:173], v[126:129]
	v_mfma_f32_16x16x32_bf16 v[122:125], v[146:149], v[170:173], v[122:125]
	v_mfma_f32_16x16x32_bf16 v[110:113], v[138:141], v[178:181], v[110:113]
	v_mfma_f32_16x16x32_bf16 v[106:109], v[146:149], v[178:181], v[106:109]
	v_mfma_f32_16x16x32_bf16 v[94:97], v[138:141], v[186:189], v[94:97]
	v_mfma_f32_16x16x32_bf16 v[90:93], v[146:149], v[186:189], v[90:93]
	v_mfma_f32_16x16x32_bf16 v[78:81], v[138:141], v[194:197], v[78:81]
	v_mfma_f32_16x16x32_bf16 v[74:77], v[146:149], v[194:197], v[74:77]
	s_setprio 0
	s_setprio 1
	v_mfma_f32_16x16x32_bf16 v[126:129], v[142:145], v[174:177], v[126:129]
	v_mfma_f32_16x16x32_bf16 v[122:125], v[150:153], v[174:177], v[122:125]
	v_mfma_f32_16x16x32_bf16 v[110:113], v[142:145], v[182:185], v[110:113]
	v_mfma_f32_16x16x32_bf16 v[106:109], v[150:153], v[182:185], v[106:109]
	v_mfma_f32_16x16x32_bf16 v[94:97], v[142:145], v[190:193], v[94:97]
	v_mfma_f32_16x16x32_bf16 v[90:93], v[150:153], v[190:193], v[90:93]
	v_mfma_f32_16x16x32_bf16 v[78:81], v[142:145], v[198:201], v[78:81]
	v_mfma_f32_16x16x32_bf16 v[74:77], v[150:153], v[198:201], v[74:77]
	s_setprio 0
	s_setprio 1
	v_mfma_f32_16x16x32_bf16 v[118:121], v[154:157], v[170:173], v[118:121]
	v_mfma_f32_16x16x32_bf16 v[114:117], v[162:165], v[170:173], v[114:117]
	v_mfma_f32_16x16x32_bf16 v[102:105], v[154:157], v[178:181], v[102:105]
	v_mfma_f32_16x16x32_bf16 v[98:101], v[162:165], v[178:181], v[98:101]
	v_mfma_f32_16x16x32_bf16 v[86:89], v[154:157], v[186:189], v[86:89]
	v_mfma_f32_16x16x32_bf16 v[82:85], v[162:165], v[186:189], v[82:85]
	v_mfma_f32_16x16x32_bf16 v[70:73], v[154:157], v[194:197], v[70:73]
	v_mfma_f32_16x16x32_bf16 v[66:69], v[162:165], v[194:197], v[66:69]
	s_setprio 0
	s_setprio 1
	v_mfma_f32_16x16x32_bf16 v[118:121], v[158:161], v[174:177], v[118:121]
	v_mfma_f32_16x16x32_bf16 v[114:117], v[166:169], v[174:177], v[114:117]
	v_mfma_f32_16x16x32_bf16 v[102:105], v[158:161], v[182:185], v[102:105]
	v_mfma_f32_16x16x32_bf16 v[98:101], v[166:169], v[182:185], v[98:101]
	v_mfma_f32_16x16x32_bf16 v[86:89], v[158:161], v[190:193], v[86:89]
	v_mfma_f32_16x16x32_bf16 v[82:85], v[166:169], v[190:193], v[82:85]
	v_mfma_f32_16x16x32_bf16 v[70:73], v[158:161], v[198:201], v[70:73]
	v_mfma_f32_16x16x32_bf16 v[66:69], v[166:169], v[198:201], v[66:69]
	s_setprio 0
	s_barrier
	ds_read_b128 v[170:173], v136 offset:49152
	ds_read_b128 v[174:177], v136 offset:50176
	ds_read_b128 v[178:181], v136 offset:51200
	ds_read_b128 v[182:185], v136 offset:52224
	ds_read_b128 v[186:189], v136 offset:53248
	ds_read_b128 v[190:193], v136 offset:54272
	ds_read_b128 v[194:197], v136 offset:55296
	ds_read_b128 v[198:201], v136 offset:56320
	s_add_i32 s51, s51, s26
	s_add_u32 s100, s16, s38
	s_addc_u32 s101, s17, s39
	s_mov_b32 m0, s51
	s_nop 0
	global_load_lds_dwordx4 v133, s[100:101]
	s_add_i32 m0, s51, 0x2000
	s_nop 0
	s_add_u32 s16, s16, 0xb0080
	s_addc_u32 s17, s17, 0
	s_add_i32 s51, s60, s26
	global_load_lds_dwordx4 v134, s[100:101]
	s_mov_b32 m0, s51
	s_nop 0
	global_load_lds_dwordx4 v133, s[16:17]
	s_add_i32 m0, s51, 0x2000
	s_nop 0
	global_load_lds_dwordx4 v134, s[16:17]
	s_mov_b32 m0, s48
	s_add_u32 s100, s14, s38
	s_addc_u32 s101, s15, s39
	v_mov_b32_e32 v0, v131
	global_load_lds_dwordx4 v130, s[100:101]
	s_mov_b32 m0, s49
	s_nop 0
	global_load_lds_dwordx4 v131, s[100:101]
	s_waitcnt vmcnt(8)
	s_waitcnt lgkmcnt(0)
	s_barrier
	s_setprio 1
	s_waitcnt lgkmcnt(0)
	v_mfma_f32_16x16x32_bf16 v[62:65], v[138:141], v[170:173], v[62:65]
	v_mfma_f32_16x16x32_bf16 v[58:61], v[146:149], v[170:173], v[58:61]
	v_mfma_f32_16x16x32_bf16 v[46:49], v[138:141], v[178:181], v[46:49]
	v_mfma_f32_16x16x32_bf16 v[42:45], v[146:149], v[178:181], v[42:45]
	v_mfma_f32_16x16x32_bf16 v[30:33], v[138:141], v[186:189], v[30:33]
	v_mfma_f32_16x16x32_bf16 v[26:29], v[146:149], v[186:189], v[26:29]
	v_mfma_f32_16x16x32_bf16 v[14:17], v[138:141], v[194:197], v[14:17]
	v_mfma_f32_16x16x32_bf16 v[10:13], v[146:149], v[194:197], v[10:13]
	s_setprio 0
	s_setprio 1
	v_mfma_f32_16x16x32_bf16 v[62:65], v[142:145], v[174:177], v[62:65]
	v_mfma_f32_16x16x32_bf16 v[58:61], v[150:153], v[174:177], v[58:61]
	v_mfma_f32_16x16x32_bf16 v[46:49], v[142:145], v[182:185], v[46:49]
	v_mfma_f32_16x16x32_bf16 v[42:45], v[150:153], v[182:185], v[42:45]
	v_mfma_f32_16x16x32_bf16 v[30:33], v[142:145], v[190:193], v[30:33]
	v_mfma_f32_16x16x32_bf16 v[26:29], v[150:153], v[190:193], v[26:29]
	v_mfma_f32_16x16x32_bf16 v[14:17], v[142:145], v[198:201], v[14:17]
	v_mfma_f32_16x16x32_bf16 v[10:13], v[150:153], v[198:201], v[10:13]
	s_setprio 0
	s_setprio 1
	v_mfma_f32_16x16x32_bf16 v[54:57], v[154:157], v[170:173], v[54:57]
	v_mfma_f32_16x16x32_bf16 v[50:53], v[162:165], v[170:173], v[50:53]
	v_mfma_f32_16x16x32_bf16 v[38:41], v[154:157], v[178:181], v[38:41]
	v_mfma_f32_16x16x32_bf16 v[34:37], v[162:165], v[178:181], v[34:37]
	v_mfma_f32_16x16x32_bf16 v[22:25], v[154:157], v[186:189], v[22:25]
	v_mfma_f32_16x16x32_bf16 v[18:21], v[162:165], v[186:189], v[18:21]
	v_mfma_f32_16x16x32_bf16 v[6:9], v[154:157], v[194:197], v[6:9]
	v_mfma_f32_16x16x32_bf16 v[2:5], v[162:165], v[194:197], v[2:5]
	s_setprio 0
	s_setprio 1
	v_mfma_f32_16x16x32_bf16 v[54:57], v[158:161], v[174:177], v[54:57]
	v_mfma_f32_16x16x32_bf16 v[50:53], v[166:169], v[174:177], v[50:53]
	v_mfma_f32_16x16x32_bf16 v[38:41], v[158:161], v[182:185], v[38:41]
	v_mfma_f32_16x16x32_bf16 v[34:37], v[166:169], v[182:185], v[34:37]
	v_mfma_f32_16x16x32_bf16 v[22:25], v[158:161], v[190:193], v[22:25]
	v_mfma_f32_16x16x32_bf16 v[18:21], v[166:169], v[190:193], v[18:21]
	v_mfma_f32_16x16x32_bf16 v[6:9], v[158:161], v[198:201], v[6:9]
	v_mfma_f32_16x16x32_bf16 v[2:5], v[166:169], v[198:201], v[2:5]
	s_setprio 0
	s_barrier
	s_add_i32 s50, s50, 2
	s_add_u32 s2, s2, 0x100
	s_addc_u32 s3, s3, 0
	s_cmp_gt_u32 s50, 41
	s_cbranch_scc0 .LBB0_953
	s_cmpk_lt_u32 s25, 0x100
	s_cbranch_scc0 .LBB0_956
	s_barrier

.LBB0_1087:
	s_add_u32 s2, s6, 0x40080
	s_addc_u32 s3, s7, 0
	s_add_u32 s8, s8, 0x100
	s_addc_u32 s9, s9, 0
	s_mov_b32 s22, -2
	s_add_u32 s4, s2, 0xfffc0080
	s_addc_u32 s5, s3, -1
	s_add_i32 s23, 0, 0x10000
	s_cmp_eq_u32 s22, 12
	s_cselect_b32 s5, s49, s5
	s_cselect_b32 s4, s48, s4
	s_waitcnt vmcnt(0)
	v_add_u32_e32 v0, s23, v145
	s_cselect_b32 s7, s97, s9
	s_cselect_b32 s6, s96, s8
	s_add_i32 s25, 0, 0x14000
	ds_read_b128 v[146:149], v0
	ds_read_b128 v[152:155], v0 offset:1024
	ds_read_b128 v[156:159], v0 offset:2048
	ds_read_b128 v[160:163], v0 offset:3072
	ds_read_b128 v[164:167], v0 offset:16384
	ds_read_b128 v[168:171], v0 offset:17408
	ds_read_b128 v[172:175], v0 offset:18432
	ds_read_b128 v[176:179], v0 offset:19456
	ds_read_b128 v[180:183], v150
	ds_read_b128 v[184:187], v150 offset:1024
	ds_read_b128 v[188:191], v150 offset:2048
	ds_read_b128 v[192:195], v150 offset:3072
	ds_read_b128 v[196:199], v150 offset:4096
	ds_read_b128 v[200:203], v150 offset:5120
	ds_read_b128 v[204:207], v150 offset:6144
	ds_read_b128 v[208:211], v150 offset:7168
	s_add_i32 m0, s60, 0xc000
	s_nop 0
	global_load_lds_dwordx4 v131, s[2:3]
	s_add_i32 m0, s60, 0xe000
	s_nop 0
	global_load_lds_dwordx4 v133, s[2:3]
	s_waitcnt vmcnt(8)
	s_waitcnt lgkmcnt(0)
	s_barrier
	s_setprio 1
	s_waitcnt lgkmcnt(0)
	v_mfma_f32_16x16x32_bf16 v[126:129], v[146:149], v[180:183], 0
	v_mfma_f32_16x16x32_bf16 v[122:125], v[156:159], v[180:183], 0
	v_mfma_f32_16x16x32_bf16 v[110:113], v[146:149], v[188:191], 0
	v_mfma_f32_16x16x32_bf16 v[106:109], v[156:159], v[188:191], 0
	v_mfma_f32_16x16x32_bf16 v[94:97], v[146:149], v[196:199], 0
	v_mfma_f32_16x16x32_bf16 v[90:93], v[156:159], v[196:199], 0
	v_mfma_f32_16x16x32_bf16 v[78:81], v[146:149], v[204:207], 0
	v_mfma_f32_16x16x32_bf16 v[74:77], v[156:159], v[204:207], 0
	s_setprio 0
	s_setprio 1
	v_mfma_f32_16x16x32_bf16 v[126:129], v[152:155], v[184:187], v[126:129]
	v_mfma_f32_16x16x32_bf16 v[122:125], v[160:163], v[184:187], v[122:125]
	v_mfma_f32_16x16x32_bf16 v[110:113], v[152:155], v[192:195], v[110:113]
	v_mfma_f32_16x16x32_bf16 v[106:109], v[160:163], v[192:195], v[106:109]
	v_mfma_f32_16x16x32_bf16 v[94:97], v[152:155], v[200:203], v[94:97]
	v_mfma_f32_16x16x32_bf16 v[90:93], v[160:163], v[200:203], v[90:93]
	v_mfma_f32_16x16x32_bf16 v[78:81], v[152:155], v[208:211], v[78:81]
	v_mfma_f32_16x16x32_bf16 v[74:77], v[160:163], v[208:211], v[74:77]
	s_setprio 0
	s_setprio 1
	v_mfma_f32_16x16x32_bf16 v[118:121], v[164:167], v[180:183], 0
	v_mfma_f32_16x16x32_bf16 v[114:117], v[172:175], v[180:183], 0
	v_mfma_f32_16x16x32_bf16 v[102:105], v[164:167], v[188:191], 0
	v_mfma_f32_16x16x32_bf16 v[98:101], v[172:175], v[188:191], 0
	v_mfma_f32_16x16x32_bf16 v[86:89], v[164:167], v[196:199], 0
	v_mfma_f32_16x16x32_bf16 v[82:85], v[172:175], v[196:199], 0
	v_mfma_f32_16x16x32_bf16 v[70:73], v[164:167], v[204:207], 0
	v_mfma_f32_16x16x32_bf16 v[66:69], v[172:175], v[204:207], 0
	s_setprio 0
	s_setprio 1
	v_mfma_f32_16x16x32_bf16 v[118:121], v[168:171], v[184:187], v[118:121]
	v_mfma_f32_16x16x32_bf16 v[114:117], v[176:179], v[184:187], v[114:117]
	v_mfma_f32_16x16x32_bf16 v[102:105], v[168:171], v[192:195], v[102:105]
	v_mfma_f32_16x16x32_bf16 v[98:101], v[176:179], v[192:195], v[98:101]
	v_mfma_f32_16x16x32_bf16 v[86:89], v[168:171], v[200:203], v[86:89]
	v_mfma_f32_16x16x32_bf16 v[82:85], v[176:179], v[200:203], v[82:85]
	v_mfma_f32_16x16x32_bf16 v[70:73], v[168:171], v[208:211], v[70:73]
	v_mfma_f32_16x16x32_bf16 v[66:69], v[176:179], v[208:211], v[66:69]
	s_setprio 0
	s_barrier
	s_add_i32 s23, s23, s42
	ds_read_b128 v[180:183], v150 offset:16384
	ds_read_b128 v[184:187], v150 offset:17408
	ds_read_b128 v[188:191], v150 offset:18432
	ds_read_b128 v[192:195], v150 offset:19456
	ds_read_b128 v[196:199], v150 offset:20480
	ds_read_b128 v[200:203], v150 offset:21504
	ds_read_b128 v[204:207], v150 offset:22528
	ds_read_b128 v[208:211], v150 offset:23552
	s_mov_b32 m0, s23
	s_nop 0
	global_load_lds_dwordx4 v137, s[6:7]
	s_add_i32 m0, s23, 0x2000
	s_add_u32 s46, s6, 0x40000
	global_load_lds_dwordx4 v139, s[6:7]
	s_addc_u32 s47, s7, 0
	s_add_i32 s23, s25, s42
	s_mov_b32 m0, s23
	s_nop 0
	global_load_lds_dwordx4 v137, s[46:47]
	s_add_i32 m0, s23, 0x2000
	s_nop 0
	global_load_lds_dwordx4 v139, s[46:47]
	s_mov_b32 m0, s60
	s_nop 0
	global_load_lds_dwordx4 v131, s[4:5]
	s_mov_b32 m0, s61
	s_nop 0
	global_load_lds_dwordx4 v133, s[4:5]
	s_waitcnt vmcnt(8)
	s_waitcnt lgkmcnt(0)
	s_barrier
	s_setprio 1
	s_waitcnt lgkmcnt(0)
	v_mfma_f32_16x16x32_bf16 v[62:65], v[146:149], v[180:183], 0
	v_mfma_f32_16x16x32_bf16 v[58:61], v[156:159], v[180:183], 0
	v_mfma_f32_16x16x32_bf16 v[46:49], v[146:149], v[188:191], 0
	v_mfma_f32_16x16x32_bf16 v[42:45], v[156:159], v[188:191], 0
	v_mfma_f32_16x16x32_bf16 v[30:33], v[146:149], v[196:199], 0
	v_mfma_f32_16x16x32_bf16 v[26:29], v[156:159], v[196:199], 0
	v_mfma_f32_16x16x32_bf16 v[14:17], v[146:149], v[204:207], 0
	v_mfma_f32_16x16x32_bf16 v[10:13], v[156:159], v[204:207], 0
	s_setprio 0
	s_setprio 1
	v_mfma_f32_16x16x32_bf16 v[62:65], v[152:155], v[184:187], v[62:65]
	v_mfma_f32_16x16x32_bf16 v[58:61], v[160:163], v[184:187], v[58:61]
	v_mfma_f32_16x16x32_bf16 v[46:49], v[152:155], v[192:195], v[46:49]
	v_mfma_f32_16x16x32_bf16 v[42:45], v[160:163], v[192:195], v[42:45]
	v_mfma_f32_16x16x32_bf16 v[30:33], v[152:155], v[200:203], v[30:33]
	v_mfma_f32_16x16x32_bf16 v[26:29], v[160:163], v[200:203], v[26:29]
	v_mfma_f32_16x16x32_bf16 v[14:17], v[152:155], v[208:211], v[14:17]
	v_mfma_f32_16x16x32_bf16 v[10:13], v[160:163], v[208:211], v[10:13]
	s_setprio 0
	s_setprio 1
	v_mfma_f32_16x16x32_bf16 v[54:57], v[164:167], v[180:183], 0
	v_mfma_f32_16x16x32_bf16 v[50:53], v[172:175], v[180:183], 0
	v_mfma_f32_16x16x32_bf16 v[38:41], v[164:167], v[188:191], 0
	v_mfma_f32_16x16x32_bf16 v[34:37], v[172:175], v[188:191], 0
	v_mfma_f32_16x16x32_bf16 v[22:25], v[164:167], v[196:199], 0
	v_mfma_f32_16x16x32_bf16 v[18:21], v[172:175], v[196:199], 0
	v_mfma_f32_16x16x32_bf16 v[6:9], v[164:167], v[204:207], 0
	v_mfma_f32_16x16x32_bf16 v[2:5], v[172:175], v[204:207], 0
	s_setprio 0
	s_setprio 1
	v_mfma_f32_16x16x32_bf16 v[54:57], v[168:171], v[184:187], v[54:57]
	v_mfma_f32_16x16x32_bf16 v[50:53], v[176:179], v[184:187], v[50:53]
	v_mfma_f32_16x16x32_bf16 v[38:41], v[168:171], v[192:195], v[38:41]
	v_mfma_f32_16x16x32_bf16 v[34:37], v[176:179], v[192:195], v[34:37]
	v_mfma_f32_16x16x32_bf16 v[22:25], v[168:171], v[200:203], v[22:25]
	v_mfma_f32_16x16x32_bf16 v[18:21], v[176:179], v[200:203], v[18:21]
	v_mfma_f32_16x16x32_bf16 v[6:9], v[168:171], v[208:211], v[6:9]
	v_mfma_f32_16x16x32_bf16 v[2:5], v[176:179], v[208:211], v[2:5]
	s_setprio 0
	s_barrier
	s_add_i32 s23, 0, 0x18000
	s_add_i32 s25, 0, 0x1c000
	ds_read_b128 v[146:149], v0 offset:32768
	ds_read_b128 v[152:155], v0 offset:33792
	ds_read_b128 v[156:159], v0 offset:34816
	ds_read_b128 v[160:163], v0 offset:35840
	ds_read_b128 v[164:167], v0 offset:49152
	ds_read_b128 v[168:171], v0 offset:50176
	ds_read_b128 v[172:175], v0 offset:51200
	ds_read_b128 v[176:179], v0 offset:52224
	s_add_u32 s46, s4, 0x40000
	s_mov_b32 m0, s66
	ds_read_b128 v[180:183], v150 offset:32768
	ds_read_b128 v[184:187], v150 offset:33792
	ds_read_b128 v[188:191], v150 offset:34816
	ds_read_b128 v[192:195], v150 offset:35840
	ds_read_b128 v[196:199], v150 offset:36864
	ds_read_b128 v[200:203], v150 offset:37888
	ds_read_b128 v[204:207], v150 offset:38912
	ds_read_b128 v[208:211], v150 offset:39936
	s_addc_u32 s47, s5, 0
	s_nop 0
	global_load_lds_dwordx4 v131, s[46:47]
	s_mov_b32 m0, s67
	s_nop 0
	global_load_lds_dwordx4 v133, s[46:47]
	s_waitcnt vmcnt(8)
	s_waitcnt lgkmcnt(0)
	s_barrier
	s_setprio 1
	s_waitcnt lgkmcnt(0)
	v_mfma_f32_16x16x32_bf16 v[126:129], v[146:149], v[180:183], v[126:129]
	v_mfma_f32_16x16x32_bf16 v[122:125], v[156:159], v[180:183], v[122:125]
	v_mfma_f32_16x16x32_bf16 v[110:113], v[146:149], v[188:191], v[110:113]
	v_mfma_f32_16x16x32_bf16 v[106:109], v[156:159], v[188:191], v[106:109]
	v_mfma_f32_16x16x32_bf16 v[94:97], v[146:149], v[196:199], v[94:97]
	v_mfma_f32_16x16x32_bf16 v[90:93], v[156:159], v[196:199], v[90:93]
	v_mfma_f32_16x16x32_bf16 v[78:81], v[146:149], v[204:207], v[78:81]
	v_mfma_f32_16x16x32_bf16 v[74:77], v[156:159], v[204:207], v[74:77]
	s_setprio 0
	s_setprio 1
	v_mfma_f32_16x16x32_bf16 v[126:129], v[152:155], v[184:187], v[126:129]
	v_mfma_f32_16x16x32_bf16 v[122:125], v[160:163], v[184:187], v[122:125]
	v_mfma_f32_16x16x32_bf16 v[110:113], v[152:155], v[192:195], v[110:113]
	v_mfma_f32_16x16x32_bf16 v[106:109], v[160:163], v[192:195], v[106:109]
	v_mfma_f32_16x16x32_bf16 v[94:97], v[152:155], v[200:203], v[94:97]
	v_mfma_f32_16x16x32_bf16 v[90:93], v[160:163], v[200:203], v[90:93]
	v_mfma_f32_16x16x32_bf16 v[78:81], v[152:155], v[208:211], v[78:81]
	v_mfma_f32_16x16x32_bf16 v[74:77], v[160:163], v[208:211], v[74:77]
	s_setprio 0
	s_setprio 1
	v_mfma_f32_16x16x32_bf16 v[118:121], v[164:167], v[180:183], v[118:121]
	v_mfma_f32_16x16x32_bf16 v[114:117], v[172:175], v[180:183], v[114:117]
	v_mfma_f32_16x16x32_bf16 v[102:105], v[164:167], v[188:191], v[102:105]
	v_mfma_f32_16x16x32_bf16 v[98:101], v[172:175], v[188:191], v[98:101]
	v_mfma_f32_16x16x32_bf16 v[86:89], v[164:167], v[196:199], v[86:89]
	v_mfma_f32_16x16x32_bf16 v[82:85], v[172:175], v[196:199], v[82:85]
	v_mfma_f32_16x16x32_bf16 v[70:73], v[164:167], v[204:207], v[70:73]
	v_mfma_f32_16x16x32_bf16 v[66:69], v[172:175], v[204:207], v[66:69]
	s_setprio 0
	s_setprio 1
	v_mfma_f32_16x16x32_bf16 v[118:121], v[168:171], v[184:187], v[118:121]
	v_mfma_f32_16x16x32_bf16 v[114:117], v[176:179], v[184:187], v[114:117]
	v_mfma_f32_16x16x32_bf16 v[102:105], v[168:171], v[192:195], v[102:105]
	v_mfma_f32_16x16x32_bf16 v[98:101], v[176:179], v[192:195], v[98:101]
	v_mfma_f32_16x16x32_bf16 v[86:89], v[168:171], v[200:203], v[86:89]
	v_mfma_f32_16x16x32_bf16 v[82:85], v[176:179], v[200:203], v[82:85]
	v_mfma_f32_16x16x32_bf16 v[70:73], v[168:171], v[208:211], v[70:73]
	v_mfma_f32_16x16x32_bf16 v[66:69], v[176:179], v[208:211], v[66:69]
	s_setprio 0
	s_barrier
	ds_read_b128 v[180:183], v150 offset:49152
	ds_read_b128 v[184:187], v150 offset:50176
	ds_read_b128 v[188:191], v150 offset:51200
	ds_read_b128 v[192:195], v150 offset:52224
	ds_read_b128 v[196:199], v150 offset:53248
	ds_read_b128 v[200:203], v150 offset:54272
	ds_read_b128 v[204:207], v150 offset:55296
	ds_read_b128 v[208:211], v150 offset:56320
	s_add_i32 s23, s23, s42
	s_add_u32 s100, s6, s38
	s_addc_u32 s101, s7, s39
	s_mov_b32 m0, s23
	s_nop 0
	global_load_lds_dwordx4 v137, s[100:101]
	s_add_i32 m0, s23, 0x2000
	s_nop 0
	s_add_u32 s6, s6, 0x40080
	s_addc_u32 s7, s7, 0
	s_add_i32 s23, s25, s42
	global_load_lds_dwordx4 v139, s[100:101]
	s_mov_b32 m0, s23
	s_nop 0
	global_load_lds_dwordx4 v137, s[6:7]
	s_add_i32 m0, s23, 0x2000
	s_nop 0
	global_load_lds_dwordx4 v139, s[6:7]
	s_mov_b32 m0, s70
	s_add_u32 s100, s4, s38
	s_addc_u32 s101, s5, s39
	v_mov_b32_e32 v0, v133
	global_load_lds_dwordx4 v131, s[100:101]
	s_mov_b32 m0, s71
	s_nop 0
	global_load_lds_dwordx4 v133, s[100:101]
	s_waitcnt vmcnt(8)
	s_waitcnt lgkmcnt(0)
	s_barrier
	s_setprio 1
	s_waitcnt lgkmcnt(0)
	v_mfma_f32_16x16x32_bf16 v[62:65], v[146:149], v[180:183], v[62:65]
	v_mfma_f32_16x16x32_bf16 v[58:61], v[156:159], v[180:183], v[58:61]
	v_mfma_f32_16x16x32_bf16 v[46:49], v[146:149], v[188:191], v[46:49]
	v_mfma_f32_16x16x32_bf16 v[42:45], v[156:159], v[188:191], v[42:45]
	v_mfma_f32_16x16x32_bf16 v[30:33], v[146:149], v[196:199], v[30:33]
	v_mfma_f32_16x16x32_bf16 v[26:29], v[156:159], v[196:199], v[26:29]
	v_mfma_f32_16x16x32_bf16 v[14:17], v[146:149], v[204:207], v[14:17]
	v_mfma_f32_16x16x32_bf16 v[10:13], v[156:159], v[204:207], v[10:13]
	s_setprio 0
	s_setprio 1
	v_mfma_f32_16x16x32_bf16 v[62:65], v[152:155], v[184:187], v[62:65]
	v_mfma_f32_16x16x32_bf16 v[58:61], v[160:163], v[184:187], v[58:61]
	v_mfma_f32_16x16x32_bf16 v[46:49], v[152:155], v[192:195], v[46:49]
	v_mfma_f32_16x16x32_bf16 v[42:45], v[160:163], v[192:195], v[42:45]
	v_mfma_f32_16x16x32_bf16 v[30:33], v[152:155], v[200:203], v[30:33]
	v_mfma_f32_16x16x32_bf16 v[26:29], v[160:163], v[200:203], v[26:29]
	v_mfma_f32_16x16x32_bf16 v[14:17], v[152:155], v[208:211], v[14:17]
	v_mfma_f32_16x16x32_bf16 v[10:13], v[160:163], v[208:211], v[10:13]
	s_setprio 0
	s_setprio 1
	v_mfma_f32_16x16x32_bf16 v[54:57], v[164:167], v[180:183], v[54:57]
	v_mfma_f32_16x16x32_bf16 v[50:53], v[172:175], v[180:183], v[50:53]
	v_mfma_f32_16x16x32_bf16 v[38:41], v[164:167], v[188:191], v[38:41]
	v_mfma_f32_16x16x32_bf16 v[34:37], v[172:175], v[188:191], v[34:37]
	v_mfma_f32_16x16x32_bf16 v[22:25], v[164:167], v[196:199], v[22:25]
	v_mfma_f32_16x16x32_bf16 v[18:21], v[172:175], v[196:199], v[18:21]
	v_mfma_f32_16x16x32_bf16 v[6:9], v[164:167], v[204:207], v[6:9]
	v_mfma_f32_16x16x32_bf16 v[2:5], v[172:175], v[204:207], v[2:5]
	s_setprio 0
	s_setprio 1
	v_mfma_f32_16x16x32_bf16 v[54:57], v[168:171], v[184:187], v[54:57]
	v_mfma_f32_16x16x32_bf16 v[50:53], v[176:179], v[184:187], v[50:53]
	v_mfma_f32_16x16x32_bf16 v[38:41], v[168:171], v[192:195], v[38:41]
	v_mfma_f32_16x16x32_bf16 v[34:37], v[176:179], v[192:195], v[34:37]
	v_mfma_f32_16x16x32_bf16 v[22:25], v[168:171], v[200:203], v[22:25]
	v_mfma_f32_16x16x32_bf16 v[18:21], v[176:179], v[200:203], v[18:21]
	v_mfma_f32_16x16x32_bf16 v[6:9], v[168:171], v[208:211], v[6:9]
	v_mfma_f32_16x16x32_bf16 v[2:5], v[176:179], v[208:211], v[2:5]
	s_setprio 0
	s_barrier
	s_add_i32 s22, s22, 2
	s_add_u32 s2, s2, 0x100
	s_addc_u32 s3, s3, 0
	s_add_u32 s8, s8, 0x100
	s_addc_u32 s9, s9, 0
	s_cmp_gt_u32 s22, 13
	s_cbranch_scc0 .LBB0_1088
	s_branch .Lpeel_exit_1088
.LBB0_1088:
	s_add_u32 s4, s2, 0xfffc0080
	s_addc_u32 s5, s3, -1
	s_add_i32 s23, 0, 0x10000
	s_cmp_eq_u32 s22, 12
	s_cselect_b32 s5, s49, s5
	s_cselect_b32 s4, s48, s4
	v_add_u32_e32 v0, s23, v145
	s_cselect_b32 s7, s97, s9
	s_cselect_b32 s6, s96, s8
	s_add_i32 s25, 0, 0x14000
	ds_read_b128 v[146:149], v0
	ds_read_b128 v[152:155], v0 offset:1024
	ds_read_b128 v[156:159], v0 offset:2048
	ds_read_b128 v[160:163], v0 offset:3072
	ds_read_b128 v[164:167], v0 offset:16384
	ds_read_b128 v[168:171], v0 offset:17408
	ds_read_b128 v[172:175], v0 offset:18432
	ds_read_b128 v[176:179], v0 offset:19456
	ds_read_b128 v[180:183], v150
	ds_read_b128 v[184:187], v150 offset:1024
	ds_read_b128 v[188:191], v150 offset:2048
	ds_read_b128 v[192:195], v150 offset:3072
	ds_read_b128 v[196:199], v150 offset:4096
	ds_read_b128 v[200:203], v150 offset:5120
	ds_read_b128 v[204:207], v150 offset:6144
	ds_read_b128 v[208:211], v150 offset:7168
	s_add_i32 m0, s60, 0xc000
	s_nop 0
	global_load_lds_dwordx4 v131, s[2:3]
	s_add_i32 m0, s60, 0xe000
	s_nop 0
	global_load_lds_dwordx4 v133, s[2:3]
	s_waitcnt vmcnt(8)
	s_waitcnt lgkmcnt(0)
	s_barrier
	s_setprio 1
	s_waitcnt lgkmcnt(0)
	v_mfma_f32_16x16x32_bf16 v[126:129], v[146:149], v[180:183], v[126:129]
	v_mfma_f32_16x16x32_bf16 v[122:125], v[156:159], v[180:183], v[122:125]
	v_mfma_f32_16x16x32_bf16 v[110:113], v[146:149], v[188:191], v[110:113]
	v_mfma_f32_16x16x32_bf16 v[106:109], v[156:159], v[188:191], v[106:109]
	v_mfma_f32_16x16x32_bf16 v[94:97], v[146:149], v[196:199], v[94:97]
	v_mfma_f32_16x16x32_bf16 v[90:93], v[156:159], v[196:199], v[90:93]
	v_mfma_f32_16x16x32_bf16 v[78:81], v[146:149], v[204:207], v[78:81]
	v_mfma_f32_16x16x32_bf16 v[74:77], v[156:159], v[204:207], v[74:77]
	s_setprio 0
	s_setprio 1
	v_mfma_f32_16x16x32_bf16 v[126:129], v[152:155], v[184:187], v[126:129]
	v_mfma_f32_16x16x32_bf16 v[122:125], v[160:163], v[184:187], v[122:125]
	v_mfma_f32_16x16x32_bf16 v[110:113], v[152:155], v[192:195], v[110:113]
	v_mfma_f32_16x16x32_bf16 v[106:109], v[160:163], v[192:195], v[106:109]
	v_mfma_f32_16x16x32_bf16 v[94:97], v[152:155], v[200:203], v[94:97]
	v_mfma_f32_16x16x32_bf16 v[90:93], v[160:163], v[200:203], v[90:93]
	v_mfma_f32_16x16x32_bf16 v[78:81], v[152:155], v[208:211], v[78:81]
	v_mfma_f32_16x16x32_bf16 v[74:77], v[160:163], v[208:211], v[74:77]
	s_setprio 0
	s_setprio 1
	v_mfma_f32_16x16x32_bf16 v[118:121], v[164:167], v[180:183], v[118:121]
	v_mfma_f32_16x16x32_bf16 v[114:117], v[172:175], v[180:183], v[114:117]
	v_mfma_f32_16x16x32_bf16 v[102:105], v[164:167], v[188:191], v[102:105]
	v_mfma_f32_16x16x32_bf16 v[98:101], v[172:175], v[188:191], v[98:101]
	v_mfma_f32_16x16x32_bf16 v[86:89], v[164:167], v[196:199], v[86:89]
	v_mfma_f32_16x16x32_bf16 v[82:85], v[172:175], v[196:199], v[82:85]
	v_mfma_f32_16x16x32_bf16 v[70:73], v[164:167], v[204:207], v[70:73]
	v_mfma_f32_16x16x32_bf16 v[66:69], v[172:175], v[204:207], v[66:69]
	s_setprio 0
	s_setprio 1
	v_mfma_f32_16x16x32_bf16 v[118:121], v[168:171], v[184:187], v[118:121]
	v_mfma_f32_16x16x32_bf16 v[114:117], v[176:179], v[184:187], v[114:117]
	v_mfma_f32_16x16x32_bf16 v[102:105], v[168:171], v[192:195], v[102:105]
	v_mfma_f32_16x16x32_bf16 v[98:101], v[176:179], v[192:195], v[98:101]
	v_mfma_f32_16x16x32_bf16 v[86:89], v[168:171], v[200:203], v[86:89]
	v_mfma_f32_16x16x32_bf16 v[82:85], v[176:179], v[200:203], v[82:85]
	v_mfma_f32_16x16x32_bf16 v[70:73], v[168:171], v[208:211], v[70:73]
	v_mfma_f32_16x16x32_bf16 v[66:69], v[176:179], v[208:211], v[66:69]
	s_setprio 0
	s_barrier
	s_add_i32 s23, s23, s42
	ds_read_b128 v[180:183], v150 offset:16384
	ds_read_b128 v[184:187], v150 offset:17408
	ds_read_b128 v[188:191], v150 offset:18432
	ds_read_b128 v[192:195], v150 offset:19456
	ds_read_b128 v[196:199], v150 offset:20480
	ds_read_b128 v[200:203], v150 offset:21504
	ds_read_b128 v[204:207], v150 offset:22528
	ds_read_b128 v[208:211], v150 offset:23552
	s_mov_b32 m0, s23
	s_nop 0
	global_load_lds_dwordx4 v137, s[6:7]
	s_add_i32 m0, s23, 0x2000
	s_add_u32 s46, s6, 0x40000
	global_load_lds_dwordx4 v139, s[6:7]
	s_addc_u32 s47, s7, 0
	s_add_i32 s23, s25, s42
	s_mov_b32 m0, s23
	s_nop 0
	global_load_lds_dwordx4 v137, s[46:47]
	s_add_i32 m0, s23, 0x2000
	s_nop 0
	global_load_lds_dwordx4 v139, s[46:47]
	s_mov_b32 m0, s60
	s_nop 0
	global_load_lds_dwordx4 v131, s[4:5]
	s_mov_b32 m0, s61
	s_nop 0
	global_load_lds_dwordx4 v133, s[4:5]
	s_waitcnt vmcnt(8)
	s_waitcnt lgkmcnt(0)
	s_barrier
	s_setprio 1
	s_waitcnt lgkmcnt(0)
	v_mfma_f32_16x16x32_bf16 v[62:65], v[146:149], v[180:183], v[62:65]
	v_mfma_f32_16x16x32_bf16 v[58:61], v[156:159], v[180:183], v[58:61]
	v_mfma_f32_16x16x32_bf16 v[46:49], v[146:149], v[188:191], v[46:49]
	v_mfma_f32_16x16x32_bf16 v[42:45], v[156:159], v[188:191], v[42:45]
	v_mfma_f32_16x16x32_bf16 v[30:33], v[146:149], v[196:199], v[30:33]
	v_mfma_f32_16x16x32_bf16 v[26:29], v[156:159], v[196:199], v[26:29]
	v_mfma_f32_16x16x32_bf16 v[14:17], v[146:149], v[204:207], v[14:17]
	v_mfma_f32_16x16x32_bf16 v[10:13], v[156:159], v[204:207], v[10:13]
	s_setprio 0
	s_setprio 1
	v_mfma_f32_16x16x32_bf16 v[62:65], v[152:155], v[184:187], v[62:65]
	v_mfma_f32_16x16x32_bf16 v[58:61], v[160:163], v[184:187], v[58:61]
	v_mfma_f32_16x16x32_bf16 v[46:49], v[152:155], v[192:195], v[46:49]
	v_mfma_f32_16x16x32_bf16 v[42:45], v[160:163], v[192:195], v[42:45]
	v_mfma_f32_16x16x32_bf16 v[30:33], v[152:155], v[200:203], v[30:33]
	v_mfma_f32_16x16x32_bf16 v[26:29], v[160:163], v[200:203], v[26:29]
	v_mfma_f32_16x16x32_bf16 v[14:17], v[152:155], v[208:211], v[14:17]
	v_mfma_f32_16x16x32_bf16 v[10:13], v[160:163], v[208:211], v[10:13]
	s_setprio 0
	s_setprio 1
	v_mfma_f32_16x16x32_bf16 v[54:57], v[164:167], v[180:183], v[54:57]
	v_mfma_f32_16x16x32_bf16 v[50:53], v[172:175], v[180:183], v[50:53]
	v_mfma_f32_16x16x32_bf16 v[38:41], v[164:167], v[188:191], v[38:41]
	v_mfma_f32_16x16x32_bf16 v[34:37], v[172:175], v[188:191], v[34:37]
	v_mfma_f32_16x16x32_bf16 v[22:25], v[164:167], v[196:199], v[22:25]
	v_mfma_f32_16x16x32_bf16 v[18:21], v[172:175], v[196:199], v[18:21]
	v_mfma_f32_16x16x32_bf16 v[6:9], v[164:167], v[204:207], v[6:9]
	v_mfma_f32_16x16x32_bf16 v[2:5], v[172:175], v[204:207], v[2:5]
	s_setprio 0
	s_setprio 1
	v_mfma_f32_16x16x32_bf16 v[54:57], v[168:171], v[184:187], v[54:57]
	v_mfma_f32_16x16x32_bf16 v[50:53], v[176:179], v[184:187], v[50:53]
	v_mfma_f32_16x16x32_bf16 v[38:41], v[168:171], v[192:195], v[38:41]
	v_mfma_f32_16x16x32_bf16 v[34:37], v[176:179], v[192:195], v[34:37]
	v_mfma_f32_16x16x32_bf16 v[22:25], v[168:171], v[200:203], v[22:25]
	v_mfma_f32_16x16x32_bf16 v[18:21], v[176:179], v[200:203], v[18:21]
	v_mfma_f32_16x16x32_bf16 v[6:9], v[168:171], v[208:211], v[6:9]
	v_mfma_f32_16x16x32_bf16 v[2:5], v[176:179], v[208:211], v[2:5]
	s_setprio 0
	s_barrier
	s_add_i32 s23, 0, 0x18000
	s_add_i32 s25, 0, 0x1c000
	ds_read_b128 v[146:149], v0 offset:32768
	ds_read_b128 v[152:155], v0 offset:33792
	ds_read_b128 v[156:159], v0 offset:34816
	ds_read_b128 v[160:163], v0 offset:35840
	ds_read_b128 v[164:167], v0 offset:49152
	ds_read_b128 v[168:171], v0 offset:50176
	ds_read_b128 v[172:175], v0 offset:51200
	ds_read_b128 v[176:179], v0 offset:52224
	s_add_u32 s46, s4, 0x40000
	s_mov_b32 m0, s66
	ds_read_b128 v[180:183], v150 offset:32768
	ds_read_b128 v[184:187], v150 offset:33792
	ds_read_b128 v[188:191], v150 offset:34816
	ds_read_b128 v[192:195], v150 offset:35840
	ds_read_b128 v[196:199], v150 offset:36864
	ds_read_b128 v[200:203], v150 offset:37888
	ds_read_b128 v[204:207], v150 offset:38912
	ds_read_b128 v[208:211], v150 offset:39936
	s_addc_u32 s47, s5, 0
	s_nop 0
	global_load_lds_dwordx4 v131, s[46:47]
	s_mov_b32 m0, s67
	s_nop 0
	global_load_lds_dwordx4 v133, s[46:47]
	s_waitcnt vmcnt(8)
	s_waitcnt lgkmcnt(0)
	s_barrier
	s_setprio 1
	s_waitcnt lgkmcnt(0)
	v_mfma_f32_16x16x32_bf16 v[126:129], v[146:149], v[180:183], v[126:129]
	v_mfma_f32_16x16x32_bf16 v[122:125], v[156:159], v[180:183], v[122:125]
	v_mfma_f32_16x16x32_bf16 v[110:113], v[146:149], v[188:191], v[110:113]
	v_mfma_f32_16x16x32_bf16 v[106:109], v[156:159], v[188:191], v[106:109]
	v_mfma_f32_16x16x32_bf16 v[94:97], v[146:149], v[196:199], v[94:97]
	v_mfma_f32_16x16x32_bf16 v[90:93], v[156:159], v[196:199], v[90:93]
	v_mfma_f32_16x16x32_bf16 v[78:81], v[146:149], v[204:207], v[78:81]
	v_mfma_f32_16x16x32_bf16 v[74:77], v[156:159], v[204:207], v[74:77]
	s_setprio 0
	s_setprio 1
	v_mfma_f32_16x16x32_bf16 v[126:129], v[152:155], v[184:187], v[126:129]
	v_mfma_f32_16x16x32_bf16 v[122:125], v[160:163], v[184:187], v[122:125]
	v_mfma_f32_16x16x32_bf16 v[110:113], v[152:155], v[192:195], v[110:113]
	v_mfma_f32_16x16x32_bf16 v[106:109], v[160:163], v[192:195], v[106:109]
	v_mfma_f32_16x16x32_bf16 v[94:97], v[152:155], v[200:203], v[94:97]
	v_mfma_f32_16x16x32_bf16 v[90:93], v[160:163], v[200:203], v[90:93]
	v_mfma_f32_16x16x32_bf16 v[78:81], v[152:155], v[208:211], v[78:81]
	v_mfma_f32_16x16x32_bf16 v[74:77], v[160:163], v[208:211], v[74:77]
	s_setprio 0
	s_setprio 1
	v_mfma_f32_16x16x32_bf16 v[118:121], v[164:167], v[180:183], v[118:121]
	v_mfma_f32_16x16x32_bf16 v[114:117], v[172:175], v[180:183], v[114:117]
	v_mfma_f32_16x16x32_bf16 v[102:105], v[164:167], v[188:191], v[102:105]
	v_mfma_f32_16x16x32_bf16 v[98:101], v[172:175], v[188:191], v[98:101]
	v_mfma_f32_16x16x32_bf16 v[86:89], v[164:167], v[196:199], v[86:89]
	v_mfma_f32_16x16x32_bf16 v[82:85], v[172:175], v[196:199], v[82:85]
	v_mfma_f32_16x16x32_bf16 v[70:73], v[164:167], v[204:207], v[70:73]
	v_mfma_f32_16x16x32_bf16 v[66:69], v[172:175], v[204:207], v[66:69]
	s_setprio 0
	s_setprio 1
	v_mfma_f32_16x16x32_bf16 v[118:121], v[168:171], v[184:187], v[118:121]
	v_mfma_f32_16x16x32_bf16 v[114:117], v[176:179], v[184:187], v[114:117]
	v_mfma_f32_16x16x32_bf16 v[102:105], v[168:171], v[192:195], v[102:105]
	v_mfma_f32_16x16x32_bf16 v[98:101], v[176:179], v[192:195], v[98:101]
	v_mfma_f32_16x16x32_bf16 v[86:89], v[168:171], v[200:203], v[86:89]
	v_mfma_f32_16x16x32_bf16 v[82:85], v[176:179], v[200:203], v[82:85]
	v_mfma_f32_16x16x32_bf16 v[70:73], v[168:171], v[208:211], v[70:73]
	v_mfma_f32_16x16x32_bf16 v[66:69], v[176:179], v[208:211], v[66:69]
	s_setprio 0
	s_barrier
	ds_read_b128 v[180:183], v150 offset:49152
	ds_read_b128 v[184:187], v150 offset:50176
	ds_read_b128 v[188:191], v150 offset:51200
	ds_read_b128 v[192:195], v150 offset:52224
	ds_read_b128 v[196:199], v150 offset:53248
	ds_read_b128 v[200:203], v150 offset:54272
	ds_read_b128 v[204:207], v150 offset:55296
	ds_read_b128 v[208:211], v150 offset:56320
	s_add_i32 s23, s23, s42
	s_add_u32 s100, s6, s38
	s_addc_u32 s101, s7, s39
	s_mov_b32 m0, s23
	s_nop 0
	global_load_lds_dwordx4 v137, s[100:101]
	s_add_i32 m0, s23, 0x2000
	s_nop 0
	s_add_u32 s6, s6, 0x40080
	s_addc_u32 s7, s7, 0
	s_add_i32 s23, s25, s42
	global_load_lds_dwordx4 v139, s[100:101]
	s_mov_b32 m0, s23
	s_nop 0
	global_load_lds_dwordx4 v137, s[6:7]
	s_add_i32 m0, s23, 0x2000
	s_nop 0
	global_load_lds_dwordx4 v139, s[6:7]
	s_mov_b32 m0, s70
	s_add_u32 s100, s4, s38
	s_addc_u32 s101, s5, s39
	v_mov_b32_e32 v0, v133
	global_load_lds_dwordx4 v131, s[100:101]
	s_mov_b32 m0, s71
	s_nop 0
	global_load_lds_dwordx4 v133, s[100:101]
	s_waitcnt vmcnt(8)
	s_waitcnt lgkmcnt(0)
	s_barrier
	s_setprio 1
	s_waitcnt lgkmcnt(0)
	v_mfma_f32_16x16x32_bf16 v[62:65], v[146:149], v[180:183], v[62:65]
	v_mfma_f32_16x16x32_bf16 v[58:61], v[156:159], v[180:183], v[58:61]
	v_mfma_f32_16x16x32_bf16 v[46:49], v[146:149], v[188:191], v[46:49]
	v_mfma_f32_16x16x32_bf16 v[42:45], v[156:159], v[188:191], v[42:45]
	v_mfma_f32_16x16x32_bf16 v[30:33], v[146:149], v[196:199], v[30:33]
	v_mfma_f32_16x16x32_bf16 v[26:29], v[156:159], v[196:199], v[26:29]
	v_mfma_f32_16x16x32_bf16 v[14:17], v[146:149], v[204:207], v[14:17]
	v_mfma_f32_16x16x32_bf16 v[10:13], v[156:159], v[204:207], v[10:13]
	s_setprio 0
	s_setprio 1
	v_mfma_f32_16x16x32_bf16 v[62:65], v[152:155], v[184:187], v[62:65]
	v_mfma_f32_16x16x32_bf16 v[58:61], v[160:163], v[184:187], v[58:61]
	v_mfma_f32_16x16x32_bf16 v[46:49], v[152:155], v[192:195], v[46:49]
	v_mfma_f32_16x16x32_bf16 v[42:45], v[160:163], v[192:195], v[42:45]
	v_mfma_f32_16x16x32_bf16 v[30:33], v[152:155], v[200:203], v[30:33]
	v_mfma_f32_16x16x32_bf16 v[26:29], v[160:163], v[200:203], v[26:29]
	v_mfma_f32_16x16x32_bf16 v[14:17], v[152:155], v[208:211], v[14:17]
	v_mfma_f32_16x16x32_bf16 v[10:13], v[160:163], v[208:211], v[10:13]
	s_setprio 0
	s_setprio 1
	v_mfma_f32_16x16x32_bf16 v[54:57], v[164:167], v[180:183], v[54:57]
	v_mfma_f32_16x16x32_bf16 v[50:53], v[172:175], v[180:183], v[50:53]
	v_mfma_f32_16x16x32_bf16 v[38:41], v[164:167], v[188:191], v[38:41]
	v_mfma_f32_16x16x32_bf16 v[34:37], v[172:175], v[188:191], v[34:37]
	v_mfma_f32_16x16x32_bf16 v[22:25], v[164:167], v[196:199], v[22:25]
	v_mfma_f32_16x16x32_bf16 v[18:21], v[172:175], v[196:199], v[18:21]
	v_mfma_f32_16x16x32_bf16 v[6:9], v[164:167], v[204:207], v[6:9]
	v_mfma_f32_16x16x32_bf16 v[2:5], v[172:175], v[204:207], v[2:5]
	s_setprio 0
	s_setprio 1
	v_mfma_f32_16x16x32_bf16 v[54:57], v[168:171], v[184:187], v[54:57]
	v_mfma_f32_16x16x32_bf16 v[50:53], v[176:179], v[184:187], v[50:53]
	v_mfma_f32_16x16x32_bf16 v[38:41], v[168:171], v[192:195], v[38:41]
	v_mfma_f32_16x16x32_bf16 v[34:37], v[176:179], v[192:195], v[34:37]
	v_mfma_f32_16x16x32_bf16 v[22:25], v[168:171], v[200:203], v[22:25]
	v_mfma_f32_16x16x32_bf16 v[18:21], v[176:179], v[200:203], v[18:21]
	v_mfma_f32_16x16x32_bf16 v[6:9], v[168:171], v[208:211], v[6:9]
	v_mfma_f32_16x16x32_bf16 v[2:5], v[176:179], v[208:211], v[2:5]
	s_setprio 0
	s_barrier
	s_add_i32 s22, s22, 2
	s_add_u32 s2, s2, 0x100
	s_addc_u32 s3, s3, 0
	s_add_u32 s8, s8, 0x100
	s_addc_u32 s9, s9, 0
	s_cmp_gt_u32 s22, 13
	s_cbranch_scc0 .LBB0_1088

.LBB0_1473:
	s_add_u32 s16, s4, s14
	s_addc_u32 s17, s5, s15
	s_add_u32 s22, s16, 0x100
	s_addc_u32 s23, s17, 0
	s_and_b64 s[10:11], s[12:13], exec
	s_cselect_b32 s11, s5, s23
	s_cselect_b32 s10, s4, s22
	s_add_u32 s14, s6, s14
	s_addc_u32 s15, s7, s15
	s_add_u32 s14, s14, 0x100
	s_addc_u32 s15, s15, 0
	s_add_i32 s69, 0, 0x10000
	s_and_b64 s[12:13], s[12:13], exec
	s_cselect_b32 s13, s7, s15
	s_cselect_b32 s12, s6, s14
	s_add_i32 s15, 0, 0x14000
	s_add_u32 s46, s16, 0x80080
	s_addc_u32 s47, s17, 0
	s_add_i32 s71, s69, s41
	s_add_i32 m0, s42, 0xc000
	s_add_i32 s74, s42, 0xe000
	s_add_i32 s67, s71, 0x2000
	v_add_u32_e32 v0, s69, v136
	s_add_u32 s22, s12, 0x40000
	ds_read_b128 v[138:141], v0
	ds_read_b128 v[142:145], v0 offset:1024
	ds_read_b128 v[146:149], v0 offset:2048
	ds_read_b128 v[150:153], v0 offset:3072
	s_addc_u32 s23, s13, 0
	s_add_i32 s68, s15, s41
	ds_read_b128 v[154:157], v0 offset:16384
	ds_read_b128 v[158:161], v0 offset:17408
	ds_read_b128 v[162:165], v0 offset:18432
	ds_read_b128 v[166:169], v0 offset:19456
	s_add_i32 s66, s68, 0x2000
	s_add_i32 s65, 0, 0x18000
	s_add_i32 s64, 0, 0x1c000
	s_add_u32 s16, s10, 0x80000
	s_addc_u32 s17, s11, 0
	s_add_i32 s61, s65, s41
	s_add_i32 s60, s61, 0x2000
	s_add_u32 s14, s12, 0x40080
	s_addc_u32 s15, s13, 0
	s_add_i32 s70, s64, s41
	s_add_i32 s69, s70, 0x2000
	ds_read_b128 v[170:173], v137
	ds_read_b128 v[174:177], v137 offset:1024
	ds_read_b128 v[178:181], v137 offset:2048
	ds_read_b128 v[182:185], v137 offset:3072
	ds_read_b128 v[186:189], v137 offset:4096
	ds_read_b128 v[190:193], v137 offset:5120
	ds_read_b128 v[194:197], v137 offset:6144
	ds_read_b128 v[198:201], v137 offset:7168
	s_nop 0
	global_load_lds_dwordx4 v130, s[46:47]
	s_mov_b32 m0, s74
	s_nop 0
	global_load_lds_dwordx4 v132, s[46:47]
	s_waitcnt vmcnt(8)
	s_waitcnt lgkmcnt(0)
	s_barrier
	s_setprio 1
	s_waitcnt lgkmcnt(0)
	v_mfma_f32_16x16x32_bf16 v[126:129], v[138:141], v[170:173], v[126:129]
	v_mfma_f32_16x16x32_bf16 v[122:125], v[146:149], v[170:173], v[122:125]
	v_mfma_f32_16x16x32_bf16 v[118:121], v[138:141], v[178:181], v[118:121]
	v_mfma_f32_16x16x32_bf16 v[110:113], v[146:149], v[178:181], v[110:113]
	v_mfma_f32_16x16x32_bf16 v[102:105], v[138:141], v[186:189], v[102:105]
	v_mfma_f32_16x16x32_bf16 v[94:97], v[146:149], v[186:189], v[94:97]
	v_mfma_f32_16x16x32_bf16 v[86:89], v[138:141], v[194:197], v[86:89]
	v_mfma_f32_16x16x32_bf16 v[78:81], v[146:149], v[194:197], v[78:81]
	s_setprio 0
	s_setprio 1
	v_mfma_f32_16x16x32_bf16 v[126:129], v[142:145], v[174:177], v[126:129]
	v_mfma_f32_16x16x32_bf16 v[122:125], v[150:153], v[174:177], v[122:125]
	v_mfma_f32_16x16x32_bf16 v[118:121], v[142:145], v[182:185], v[118:121]
	v_mfma_f32_16x16x32_bf16 v[110:113], v[150:153], v[182:185], v[110:113]
	v_mfma_f32_16x16x32_bf16 v[102:105], v[142:145], v[190:193], v[102:105]
	v_mfma_f32_16x16x32_bf16 v[94:97], v[150:153], v[190:193], v[94:97]
	v_mfma_f32_16x16x32_bf16 v[86:89], v[142:145], v[198:201], v[86:89]
	v_mfma_f32_16x16x32_bf16 v[78:81], v[150:153], v[198:201], v[78:81]
	s_setprio 0
	s_setprio 1
	v_mfma_f32_16x16x32_bf16 v[114:117], v[154:157], v[170:173], v[114:117]
	v_mfma_f32_16x16x32_bf16 v[106:109], v[162:165], v[170:173], v[106:109]
	v_mfma_f32_16x16x32_bf16 v[98:101], v[154:157], v[178:181], v[98:101]
	v_mfma_f32_16x16x32_bf16 v[90:93], v[162:165], v[178:181], v[90:93]
	v_mfma_f32_16x16x32_bf16 v[82:85], v[154:157], v[186:189], v[82:85]
	v_mfma_f32_16x16x32_bf16 v[74:77], v[162:165], v[186:189], v[74:77]
	v_mfma_f32_16x16x32_bf16 v[70:73], v[154:157], v[194:197], v[70:73]
	v_mfma_f32_16x16x32_bf16 v[62:65], v[162:165], v[194:197], v[62:65]
	s_setprio 0
	s_setprio 1
	v_mfma_f32_16x16x32_bf16 v[114:117], v[158:161], v[174:177], v[114:117]
	v_mfma_f32_16x16x32_bf16 v[106:109], v[166:169], v[174:177], v[106:109]
	v_mfma_f32_16x16x32_bf16 v[98:101], v[158:161], v[182:185], v[98:101]
	v_mfma_f32_16x16x32_bf16 v[90:93], v[166:169], v[182:185], v[90:93]
	v_mfma_f32_16x16x32_bf16 v[82:85], v[158:161], v[190:193], v[82:85]
	v_mfma_f32_16x16x32_bf16 v[74:77], v[166:169], v[190:193], v[74:77]
	v_mfma_f32_16x16x32_bf16 v[70:73], v[158:161], v[198:201], v[70:73]
	v_mfma_f32_16x16x32_bf16 v[62:65], v[166:169], v[198:201], v[62:65]
	s_setprio 0
	s_barrier
	s_mov_b32 m0, s71
	ds_read_b128 v[170:173], v137 offset:16384
	ds_read_b128 v[174:177], v137 offset:17408
	ds_read_b128 v[178:181], v137 offset:18432
	ds_read_b128 v[182:185], v137 offset:19456
	ds_read_b128 v[186:189], v137 offset:20480
	ds_read_b128 v[190:193], v137 offset:21504
	ds_read_b128 v[194:197], v137 offset:22528
	ds_read_b128 v[198:201], v137 offset:23552
	s_nop 0
	global_load_lds_dwordx4 v131, s[12:13]
	s_mov_b32 m0, s67
	s_nop 0
	global_load_lds_dwordx4 v133, s[12:13]
	s_mov_b32 m0, s68
	s_nop 0
	global_load_lds_dwordx4 v131, s[22:23]
	s_mov_b32 m0, s66
	s_nop 0
	global_load_lds_dwordx4 v133, s[22:23]
	s_mov_b32 m0, s42
	s_nop 0
	global_load_lds_dwordx4 v130, s[10:11]
	s_mov_b32 m0, s43
	s_nop 0
	global_load_lds_dwordx4 v132, s[10:11]
	s_waitcnt vmcnt(8)
	s_waitcnt lgkmcnt(0)
	s_barrier
	s_setprio 1
	s_waitcnt lgkmcnt(0)
	v_mfma_f32_16x16x32_bf16 v[66:69], v[138:141], v[170:173], v[66:69]
	v_mfma_f32_16x16x32_bf16 v[58:61], v[146:149], v[170:173], v[58:61]
	v_mfma_f32_16x16x32_bf16 v[54:57], v[138:141], v[178:181], v[54:57]
	v_mfma_f32_16x16x32_bf16 v[46:49], v[146:149], v[178:181], v[46:49]
	v_mfma_f32_16x16x32_bf16 v[38:41], v[138:141], v[186:189], v[38:41]
	v_mfma_f32_16x16x32_bf16 v[30:33], v[146:149], v[186:189], v[30:33]
	v_mfma_f32_16x16x32_bf16 v[22:25], v[138:141], v[194:197], v[22:25]
	v_mfma_f32_16x16x32_bf16 v[14:17], v[146:149], v[194:197], v[14:17]
	s_setprio 0
	s_setprio 1
	v_mfma_f32_16x16x32_bf16 v[66:69], v[142:145], v[174:177], v[66:69]
	v_mfma_f32_16x16x32_bf16 v[58:61], v[150:153], v[174:177], v[58:61]
	v_mfma_f32_16x16x32_bf16 v[54:57], v[142:145], v[182:185], v[54:57]
	v_mfma_f32_16x16x32_bf16 v[46:49], v[150:153], v[182:185], v[46:49]
	v_mfma_f32_16x16x32_bf16 v[38:41], v[142:145], v[190:193], v[38:41]
	v_mfma_f32_16x16x32_bf16 v[30:33], v[150:153], v[190:193], v[30:33]
	v_mfma_f32_16x16x32_bf16 v[22:25], v[142:145], v[198:201], v[22:25]
	v_mfma_f32_16x16x32_bf16 v[14:17], v[150:153], v[198:201], v[14:17]
	s_setprio 0
	s_setprio 1
	v_mfma_f32_16x16x32_bf16 v[50:53], v[154:157], v[170:173], v[50:53]
	v_mfma_f32_16x16x32_bf16 v[42:45], v[162:165], v[170:173], v[42:45]
	v_mfma_f32_16x16x32_bf16 v[34:37], v[154:157], v[178:181], v[34:37]
	v_mfma_f32_16x16x32_bf16 v[26:29], v[162:165], v[178:181], v[26:29]
	v_mfma_f32_16x16x32_bf16 v[18:21], v[154:157], v[186:189], v[18:21]
	v_mfma_f32_16x16x32_bf16 v[10:13], v[162:165], v[186:189], v[10:13]
	v_mfma_f32_16x16x32_bf16 v[6:9], v[154:157], v[194:197], v[6:9]
	v_mfma_f32_16x16x32_bf16 v[2:5], v[162:165], v[194:197], v[2:5]
	s_setprio 0
	s_setprio 1
	v_mfma_f32_16x16x32_bf16 v[50:53], v[158:161], v[174:177], v[50:53]
	v_mfma_f32_16x16x32_bf16 v[42:45], v[166:169], v[174:177], v[42:45]
	v_mfma_f32_16x16x32_bf16 v[34:37], v[158:161], v[182:185], v[34:37]
	v_mfma_f32_16x16x32_bf16 v[26:29], v[166:169], v[182:185], v[26:29]
	v_mfma_f32_16x16x32_bf16 v[18:21], v[158:161], v[190:193], v[18:21]
	v_mfma_f32_16x16x32_bf16 v[10:13], v[166:169], v[190:193], v[10:13]
	v_mfma_f32_16x16x32_bf16 v[6:9], v[158:161], v[198:201], v[6:9]
	v_mfma_f32_16x16x32_bf16 v[2:5], v[166:169], v[198:201], v[2:5]
	s_setprio 0
	s_barrier
	ds_read_b128 v[138:141], v0 offset:32768
	ds_read_b128 v[142:145], v0 offset:33792
	ds_read_b128 v[146:149], v0 offset:34816
	ds_read_b128 v[150:153], v0 offset:35840
	ds_read_b128 v[154:157], v0 offset:49152
	ds_read_b128 v[158:161], v0 offset:50176
	ds_read_b128 v[162:165], v0 offset:51200
	ds_read_b128 v[166:169], v0 offset:52224
	s_mov_b32 m0, s50
	ds_read_b128 v[170:173], v137 offset:32768
	ds_read_b128 v[174:177], v137 offset:33792
	ds_read_b128 v[178:181], v137 offset:34816
	ds_read_b128 v[182:185], v137 offset:35840
	ds_read_b128 v[186:189], v137 offset:36864
	ds_read_b128 v[190:193], v137 offset:37888
	ds_read_b128 v[194:197], v137 offset:38912
	ds_read_b128 v[198:201], v137 offset:39936
	s_nop 0
	global_load_lds_dwordx4 v130, s[16:17]
	s_mov_b32 m0, s51
	s_nop 0
	global_load_lds_dwordx4 v132, s[16:17]
	s_waitcnt vmcnt(8)
	s_waitcnt lgkmcnt(0)
	s_barrier
	s_setprio 1
	s_waitcnt lgkmcnt(0)
	v_mfma_f32_16x16x32_bf16 v[126:129], v[138:141], v[170:173], v[126:129]
	v_mfma_f32_16x16x32_bf16 v[122:125], v[146:149], v[170:173], v[122:125]
	v_mfma_f32_16x16x32_bf16 v[118:121], v[138:141], v[178:181], v[118:121]
	v_mfma_f32_16x16x32_bf16 v[110:113], v[146:149], v[178:181], v[110:113]
	v_mfma_f32_16x16x32_bf16 v[102:105], v[138:141], v[186:189], v[102:105]
	v_mfma_f32_16x16x32_bf16 v[94:97], v[146:149], v[186:189], v[94:97]
	v_mfma_f32_16x16x32_bf16 v[86:89], v[138:141], v[194:197], v[86:89]
	v_mfma_f32_16x16x32_bf16 v[78:81], v[146:149], v[194:197], v[78:81]
	s_setprio 0
	s_setprio 1
	v_mfma_f32_16x16x32_bf16 v[126:129], v[142:145], v[174:177], v[126:129]
	v_mfma_f32_16x16x32_bf16 v[122:125], v[150:153], v[174:177], v[122:125]
	v_mfma_f32_16x16x32_bf16 v[118:121], v[142:145], v[182:185], v[118:121]
	v_mfma_f32_16x16x32_bf16 v[110:113], v[150:153], v[182:185], v[110:113]
	v_mfma_f32_16x16x32_bf16 v[102:105], v[142:145], v[190:193], v[102:105]
	v_mfma_f32_16x16x32_bf16 v[94:97], v[150:153], v[190:193], v[94:97]
	v_mfma_f32_16x16x32_bf16 v[86:89], v[142:145], v[198:201], v[86:89]
	v_mfma_f32_16x16x32_bf16 v[78:81], v[150:153], v[198:201], v[78:81]
	s_setprio 0
	s_setprio 1
	v_mfma_f32_16x16x32_bf16 v[114:117], v[154:157], v[170:173], v[114:117]
	v_mfma_f32_16x16x32_bf16 v[106:109], v[162:165], v[170:173], v[106:109]
	v_mfma_f32_16x16x32_bf16 v[98:101], v[154:157], v[178:181], v[98:101]
	v_mfma_f32_16x16x32_bf16 v[90:93], v[162:165], v[178:181], v[90:93]
	v_mfma_f32_16x16x32_bf16 v[82:85], v[154:157], v[186:189], v[82:85]
	v_mfma_f32_16x16x32_bf16 v[74:77], v[162:165], v[186:189], v[74:77]
	v_mfma_f32_16x16x32_bf16 v[70:73], v[154:157], v[194:197], v[70:73]
	v_mfma_f32_16x16x32_bf16 v[62:65], v[162:165], v[194:197], v[62:65]
	s_setprio 0
	s_setprio 1
	v_mfma_f32_16x16x32_bf16 v[114:117], v[158:161], v[174:177], v[114:117]
	v_mfma_f32_16x16x32_bf16 v[106:109], v[166:169], v[174:177], v[106:109]
	v_mfma_f32_16x16x32_bf16 v[98:101], v[158:161], v[182:185], v[98:101]
	v_mfma_f32_16x16x32_bf16 v[90:93], v[166:169], v[182:185], v[90:93]
	v_mfma_f32_16x16x32_bf16 v[82:85], v[158:161], v[190:193], v[82:85]
	v_mfma_f32_16x16x32_bf16 v[74:77], v[166:169], v[190:193], v[74:77]
	v_mfma_f32_16x16x32_bf16 v[70:73], v[158:161], v[198:201], v[70:73]
	v_mfma_f32_16x16x32_bf16 v[62:65], v[166:169], v[198:201], v[62:65]
	s_setprio 0
	s_barrier
	ds_read_b128 v[170:173], v137 offset:49152
	ds_read_b128 v[174:177], v137 offset:50176
	ds_read_b128 v[178:181], v137 offset:51200
	ds_read_b128 v[182:185], v137 offset:52224
	ds_read_b128 v[186:189], v137 offset:53248
	ds_read_b128 v[190:193], v137 offset:54272
	ds_read_b128 v[194:197], v137 offset:55296
	ds_read_b128 v[198:201], v137 offset:56320
	s_mov_b32 m0, s61
	s_add_u32 s100, s12, s38
	s_addc_u32 s101, s13, s39
	global_load_lds_dwordx4 v131, s[100:101]
	s_mov_b32 m0, s60
	s_nop 0
	global_load_lds_dwordx4 v133, s[100:101]
	s_mov_b32 m0, s70
	s_nop 0
	global_load_lds_dwordx4 v131, s[14:15]
	s_mov_b32 m0, s69
	s_nop 0
	global_load_lds_dwordx4 v133, s[14:15]
	s_mov_b32 m0, s58
	s_add_u32 s100, s10, s38
	s_addc_u32 s101, s11, s39
	v_mov_b32_e32 v0, v132
	global_load_lds_dwordx4 v130, s[100:101]
	s_mov_b32 m0, s59
	s_nop 0
	global_load_lds_dwordx4 v132, s[100:101]
	s_waitcnt vmcnt(8)
	s_waitcnt lgkmcnt(0)
	s_barrier
	s_setprio 1
	s_waitcnt lgkmcnt(0)
	v_mfma_f32_16x16x32_bf16 v[66:69], v[138:141], v[170:173], v[66:69]
	v_mfma_f32_16x16x32_bf16 v[58:61], v[146:149], v[170:173], v[58:61]
	v_mfma_f32_16x16x32_bf16 v[54:57], v[138:141], v[178:181], v[54:57]
	v_mfma_f32_16x16x32_bf16 v[46:49], v[146:149], v[178:181], v[46:49]
	v_mfma_f32_16x16x32_bf16 v[38:41], v[138:141], v[186:189], v[38:41]
	v_mfma_f32_16x16x32_bf16 v[30:33], v[146:149], v[186:189], v[30:33]
	v_mfma_f32_16x16x32_bf16 v[22:25], v[138:141], v[194:197], v[22:25]
	v_mfma_f32_16x16x32_bf16 v[14:17], v[146:149], v[194:197], v[14:17]
	s_setprio 0
	s_setprio 1
	v_mfma_f32_16x16x32_bf16 v[66:69], v[142:145], v[174:177], v[66:69]
	v_mfma_f32_16x16x32_bf16 v[58:61], v[150:153], v[174:177], v[58:61]
	v_mfma_f32_16x16x32_bf16 v[54:57], v[142:145], v[182:185], v[54:57]
	v_mfma_f32_16x16x32_bf16 v[46:49], v[150:153], v[182:185], v[46:49]
	v_mfma_f32_16x16x32_bf16 v[38:41], v[142:145], v[190:193], v[38:41]
	v_mfma_f32_16x16x32_bf16 v[30:33], v[150:153], v[190:193], v[30:33]
	v_mfma_f32_16x16x32_bf16 v[22:25], v[142:145], v[198:201], v[22:25]
	v_mfma_f32_16x16x32_bf16 v[14:17], v[150:153], v[198:201], v[14:17]
	s_setprio 0
	s_setprio 1
	v_mfma_f32_16x16x32_bf16 v[50:53], v[154:157], v[170:173], v[50:53]
	v_mfma_f32_16x16x32_bf16 v[42:45], v[162:165], v[170:173], v[42:45]
	v_mfma_f32_16x16x32_bf16 v[34:37], v[154:157], v[178:181], v[34:37]
	v_mfma_f32_16x16x32_bf16 v[26:29], v[162:165], v[178:181], v[26:29]
	v_mfma_f32_16x16x32_bf16 v[18:21], v[154:157], v[186:189], v[18:21]
	v_mfma_f32_16x16x32_bf16 v[10:13], v[162:165], v[186:189], v[10:13]
	v_mfma_f32_16x16x32_bf16 v[6:9], v[154:157], v[194:197], v[6:9]
	v_mfma_f32_16x16x32_bf16 v[2:5], v[162:165], v[194:197], v[2:5]
	s_setprio 0
	s_setprio 1
	v_mfma_f32_16x16x32_bf16 v[50:53], v[158:161], v[174:177], v[50:53]
	v_mfma_f32_16x16x32_bf16 v[42:45], v[166:169], v[174:177], v[42:45]
	v_mfma_f32_16x16x32_bf16 v[34:37], v[158:161], v[182:185], v[34:37]
	v_mfma_f32_16x16x32_bf16 v[26:29], v[166:169], v[182:185], v[26:29]
	v_mfma_f32_16x16x32_bf16 v[18:21], v[158:161], v[190:193], v[18:21]
	v_mfma_f32_16x16x32_bf16 v[10:13], v[166:169], v[190:193], v[10:13]
	v_mfma_f32_16x16x32_bf16 v[6:9], v[158:161], v[198:201], v[6:9]
	v_mfma_f32_16x16x32_bf16 v[2:5], v[166:169], v[198:201], v[2:5]
	s_setprio 0
	s_barrier
	s_andn2_b64 vcc, exec, s[8:9]
	s_mov_b64 s[12:13], -1
	s_mov_b64 s[8:9], 0
	s_mov_b64 s[14:15], 0x100
	s_cbranch_vccz .LBB0_1473
	s_cmpk_lt_u32 s24, 0x100
	s_cbranch_scc0 .LBB0_1476
	s_barrier

.LBB0_1481:
	s_add_u32 s16, s4, s14
	s_addc_u32 s17, s5, s15
	s_add_u32 s22, s16, 0x100
	s_addc_u32 s23, s17, 0
	s_and_b64 s[10:11], s[12:13], exec
	s_cselect_b32 s11, s5, s23
	s_cselect_b32 s10, s4, s22
	s_add_u32 s14, s6, s14
	s_addc_u32 s15, s7, s15
	s_add_u32 s14, s14, 0x900
	s_addc_u32 s15, s15, 0
	s_add_i32 s70, 0, 0x10000
	s_and_b64 s[12:13], s[12:13], exec
	s_cselect_b32 s13, s58, s15
	s_cselect_b32 s12, s51, s14
	s_add_i32 s15, 0, 0x14000
	s_add_u32 s46, s16, 0x40080
	s_addc_u32 s47, s17, 0
	s_add_i32 s74, s70, s40
	s_add_i32 m0, s41, 0xc000
	s_add_i32 s75, s41, 0xe000
	s_add_i32 s68, s74, 0x2000
	v_add_u32_e32 v0, s70, v136
	s_add_u32 s22, s12, 0x80000
	ds_read_b128 v[138:141], v0
	ds_read_b128 v[142:145], v0 offset:1024
	ds_read_b128 v[146:149], v0 offset:2048
	ds_read_b128 v[150:153], v0 offset:3072
	s_addc_u32 s23, s13, 0
	s_add_i32 s69, s15, s40
	ds_read_b128 v[154:157], v0 offset:16384
	ds_read_b128 v[158:161], v0 offset:17408
	ds_read_b128 v[162:165], v0 offset:18432
	ds_read_b128 v[166:169], v0 offset:19456
	s_add_i32 s67, s69, 0x2000
	s_add_i32 s66, 0, 0x18000
	s_add_i32 s65, 0, 0x1c000
	s_add_u32 s16, s10, 0x40000
	s_addc_u32 s17, s11, 0
	s_add_i32 s64, s66, s40
	s_add_i32 s61, s64, 0x2000
	s_add_u32 s14, s12, 0x80080
	s_addc_u32 s15, s13, 0
	s_add_i32 s71, s65, s40
	s_add_i32 s70, s71, 0x2000
	ds_read_b128 v[170:173], v137
	ds_read_b128 v[174:177], v137 offset:1024
	ds_read_b128 v[178:181], v137 offset:2048
	ds_read_b128 v[182:185], v137 offset:3072
	ds_read_b128 v[186:189], v137 offset:4096
	ds_read_b128 v[190:193], v137 offset:5120
	ds_read_b128 v[194:197], v137 offset:6144
	ds_read_b128 v[198:201], v137 offset:7168
	s_nop 0
	global_load_lds_dwordx4 v130, s[46:47]
	s_mov_b32 m0, s75
	s_nop 0
	global_load_lds_dwordx4 v132, s[46:47]
	s_waitcnt vmcnt(8)
	s_waitcnt lgkmcnt(0)
	s_barrier
	s_setprio 1
	s_waitcnt lgkmcnt(0)
	v_mfma_f32_16x16x32_bf16 v[126:129], v[138:141], v[170:173], v[126:129]
	v_mfma_f32_16x16x32_bf16 v[122:125], v[146:149], v[170:173], v[122:125]
	v_mfma_f32_16x16x32_bf16 v[118:121], v[138:141], v[178:181], v[118:121]
	v_mfma_f32_16x16x32_bf16 v[110:113], v[146:149], v[178:181], v[110:113]
	v_mfma_f32_16x16x32_bf16 v[102:105], v[138:141], v[186:189], v[102:105]
	v_mfma_f32_16x16x32_bf16 v[94:97], v[146:149], v[186:189], v[94:97]
	v_mfma_f32_16x16x32_bf16 v[86:89], v[138:141], v[194:197], v[86:89]
	v_mfma_f32_16x16x32_bf16 v[78:81], v[146:149], v[194:197], v[78:81]
	s_setprio 0
	s_setprio 1
	v_mfma_f32_16x16x32_bf16 v[126:129], v[142:145], v[174:177], v[126:129]
	v_mfma_f32_16x16x32_bf16 v[122:125], v[150:153], v[174:177], v[122:125]
	v_mfma_f32_16x16x32_bf16 v[118:121], v[142:145], v[182:185], v[118:121]
	v_mfma_f32_16x16x32_bf16 v[110:113], v[150:153], v[182:185], v[110:113]
	v_mfma_f32_16x16x32_bf16 v[102:105], v[142:145], v[190:193], v[102:105]
	v_mfma_f32_16x16x32_bf16 v[94:97], v[150:153], v[190:193], v[94:97]
	v_mfma_f32_16x16x32_bf16 v[86:89], v[142:145], v[198:201], v[86:89]
	v_mfma_f32_16x16x32_bf16 v[78:81], v[150:153], v[198:201], v[78:81]
	s_setprio 0
	s_setprio 1
	v_mfma_f32_16x16x32_bf16 v[114:117], v[154:157], v[170:173], v[114:117]
	v_mfma_f32_16x16x32_bf16 v[106:109], v[162:165], v[170:173], v[106:109]
	v_mfma_f32_16x16x32_bf16 v[98:101], v[154:157], v[178:181], v[98:101]
	v_mfma_f32_16x16x32_bf16 v[90:93], v[162:165], v[178:181], v[90:93]
	v_mfma_f32_16x16x32_bf16 v[82:85], v[154:157], v[186:189], v[82:85]
	v_mfma_f32_16x16x32_bf16 v[74:77], v[162:165], v[186:189], v[74:77]
	v_mfma_f32_16x16x32_bf16 v[70:73], v[154:157], v[194:197], v[70:73]
	v_mfma_f32_16x16x32_bf16 v[62:65], v[162:165], v[194:197], v[62:65]
	s_setprio 0
	s_setprio 1
	v_mfma_f32_16x16x32_bf16 v[114:117], v[158:161], v[174:177], v[114:117]
	v_mfma_f32_16x16x32_bf16 v[106:109], v[166:169], v[174:177], v[106:109]
	v_mfma_f32_16x16x32_bf16 v[98:101], v[158:161], v[182:185], v[98:101]
	v_mfma_f32_16x16x32_bf16 v[90:93], v[166:169], v[182:185], v[90:93]
	v_mfma_f32_16x16x32_bf16 v[82:85], v[158:161], v[190:193], v[82:85]
	v_mfma_f32_16x16x32_bf16 v[74:77], v[166:169], v[190:193], v[74:77]
	v_mfma_f32_16x16x32_bf16 v[70:73], v[158:161], v[198:201], v[70:73]
	v_mfma_f32_16x16x32_bf16 v[62:65], v[166:169], v[198:201], v[62:65]
	s_setprio 0
	s_barrier
	s_mov_b32 m0, s74
	ds_read_b128 v[170:173], v137 offset:16384
	ds_read_b128 v[174:177], v137 offset:17408
	ds_read_b128 v[178:181], v137 offset:18432
	ds_read_b128 v[182:185], v137 offset:19456
	ds_read_b128 v[186:189], v137 offset:20480
	ds_read_b128 v[190:193], v137 offset:21504
	ds_read_b128 v[194:197], v137 offset:22528
	ds_read_b128 v[198:201], v137 offset:23552
	s_nop 0
	global_load_lds_dwordx4 v131, s[12:13]
	s_mov_b32 m0, s68
	s_nop 0
	global_load_lds_dwordx4 v133, s[12:13]
	s_mov_b32 m0, s69
	s_nop 0
	global_load_lds_dwordx4 v131, s[22:23]
	s_mov_b32 m0, s67
	s_nop 0
	global_load_lds_dwordx4 v133, s[22:23]
	s_mov_b32 m0, s41
	s_nop 0
	global_load_lds_dwordx4 v130, s[10:11]
	s_mov_b32 m0, s42
	s_nop 0
	global_load_lds_dwordx4 v132, s[10:11]
	s_waitcnt vmcnt(8)
	s_waitcnt lgkmcnt(0)
	s_barrier
	s_setprio 1
	s_waitcnt lgkmcnt(0)
	v_mfma_f32_16x16x32_bf16 v[66:69], v[138:141], v[170:173], v[66:69]
	v_mfma_f32_16x16x32_bf16 v[58:61], v[146:149], v[170:173], v[58:61]
	v_mfma_f32_16x16x32_bf16 v[54:57], v[138:141], v[178:181], v[54:57]
	v_mfma_f32_16x16x32_bf16 v[46:49], v[146:149], v[178:181], v[46:49]
	v_mfma_f32_16x16x32_bf16 v[38:41], v[138:141], v[186:189], v[38:41]
	v_mfma_f32_16x16x32_bf16 v[30:33], v[146:149], v[186:189], v[30:33]
	v_mfma_f32_16x16x32_bf16 v[22:25], v[138:141], v[194:197], v[22:25]
	v_mfma_f32_16x16x32_bf16 v[14:17], v[146:149], v[194:197], v[14:17]
	s_setprio 0
	s_setprio 1
	v_mfma_f32_16x16x32_bf16 v[66:69], v[142:145], v[174:177], v[66:69]
	v_mfma_f32_16x16x32_bf16 v[58:61], v[150:153], v[174:177], v[58:61]
	v_mfma_f32_16x16x32_bf16 v[54:57], v[142:145], v[182:185], v[54:57]
	v_mfma_f32_16x16x32_bf16 v[46:49], v[150:153], v[182:185], v[46:49]
	v_mfma_f32_16x16x32_bf16 v[38:41], v[142:145], v[190:193], v[38:41]
	v_mfma_f32_16x16x32_bf16 v[30:33], v[150:153], v[190:193], v[30:33]
	v_mfma_f32_16x16x32_bf16 v[22:25], v[142:145], v[198:201], v[22:25]
	v_mfma_f32_16x16x32_bf16 v[14:17], v[150:153], v[198:201], v[14:17]
	s_setprio 0
	s_setprio 1
	v_mfma_f32_16x16x32_bf16 v[50:53], v[154:157], v[170:173], v[50:53]
	v_mfma_f32_16x16x32_bf16 v[42:45], v[162:165], v[170:173], v[42:45]
	v_mfma_f32_16x16x32_bf16 v[34:37], v[154:157], v[178:181], v[34:37]
	v_mfma_f32_16x16x32_bf16 v[26:29], v[162:165], v[178:181], v[26:29]
	v_mfma_f32_16x16x32_bf16 v[18:21], v[154:157], v[186:189], v[18:21]
	v_mfma_f32_16x16x32_bf16 v[10:13], v[162:165], v[186:189], v[10:13]
	v_mfma_f32_16x16x32_bf16 v[6:9], v[154:157], v[194:197], v[6:9]
	v_mfma_f32_16x16x32_bf16 v[2:5], v[162:165], v[194:197], v[2:5]
	s_setprio 0
	s_setprio 1
	v_mfma_f32_16x16x32_bf16 v[50:53], v[158:161], v[174:177], v[50:53]
	v_mfma_f32_16x16x32_bf16 v[42:45], v[166:169], v[174:177], v[42:45]
	v_mfma_f32_16x16x32_bf16 v[34:37], v[158:161], v[182:185], v[34:37]
	v_mfma_f32_16x16x32_bf16 v[26:29], v[166:169], v[182:185], v[26:29]
	v_mfma_f32_16x16x32_bf16 v[18:21], v[158:161], v[190:193], v[18:21]
	v_mfma_f32_16x16x32_bf16 v[10:13], v[166:169], v[190:193], v[10:13]
	v_mfma_f32_16x16x32_bf16 v[6:9], v[158:161], v[198:201], v[6:9]
	v_mfma_f32_16x16x32_bf16 v[2:5], v[166:169], v[198:201], v[2:5]
	s_setprio 0
	s_barrier
	ds_read_b128 v[138:141], v0 offset:32768
	ds_read_b128 v[142:145], v0 offset:33792
	ds_read_b128 v[146:149], v0 offset:34816
	ds_read_b128 v[150:153], v0 offset:35840
	ds_read_b128 v[154:157], v0 offset:49152
	ds_read_b128 v[158:161], v0 offset:50176
	ds_read_b128 v[162:165], v0 offset:51200
	ds_read_b128 v[166:169], v0 offset:52224
	s_mov_b32 m0, s43
	ds_read_b128 v[170:173], v137 offset:32768
	ds_read_b128 v[174:177], v137 offset:33792
	ds_read_b128 v[178:181], v137 offset:34816
	ds_read_b128 v[182:185], v137 offset:35840
	ds_read_b128 v[186:189], v137 offset:36864
	ds_read_b128 v[190:193], v137 offset:37888
	ds_read_b128 v[194:197], v137 offset:38912
	ds_read_b128 v[198:201], v137 offset:39936
	s_nop 0
	global_load_lds_dwordx4 v130, s[16:17]
	s_mov_b32 m0, s50
	s_nop 0
	global_load_lds_dwordx4 v132, s[16:17]
	s_waitcnt vmcnt(8)
	s_waitcnt lgkmcnt(0)
	s_barrier
	s_setprio 1
	s_waitcnt lgkmcnt(0)
	v_mfma_f32_16x16x32_bf16 v[126:129], v[138:141], v[170:173], v[126:129]
	v_mfma_f32_16x16x32_bf16 v[122:125], v[146:149], v[170:173], v[122:125]
	v_mfma_f32_16x16x32_bf16 v[118:121], v[138:141], v[178:181], v[118:121]
	v_mfma_f32_16x16x32_bf16 v[110:113], v[146:149], v[178:181], v[110:113]
	v_mfma_f32_16x16x32_bf16 v[102:105], v[138:141], v[186:189], v[102:105]
	v_mfma_f32_16x16x32_bf16 v[94:97], v[146:149], v[186:189], v[94:97]
	v_mfma_f32_16x16x32_bf16 v[86:89], v[138:141], v[194:197], v[86:89]
	v_mfma_f32_16x16x32_bf16 v[78:81], v[146:149], v[194:197], v[78:81]
	s_setprio 0
	s_setprio 1
	v_mfma_f32_16x16x32_bf16 v[126:129], v[142:145], v[174:177], v[126:129]
	v_mfma_f32_16x16x32_bf16 v[122:125], v[150:153], v[174:177], v[122:125]
	v_mfma_f32_16x16x32_bf16 v[118:121], v[142:145], v[182:185], v[118:121]
	v_mfma_f32_16x16x32_bf16 v[110:113], v[150:153], v[182:185], v[110:113]
	v_mfma_f32_16x16x32_bf16 v[102:105], v[142:145], v[190:193], v[102:105]
	v_mfma_f32_16x16x32_bf16 v[94:97], v[150:153], v[190:193], v[94:97]
	v_mfma_f32_16x16x32_bf16 v[86:89], v[142:145], v[198:201], v[86:89]
	v_mfma_f32_16x16x32_bf16 v[78:81], v[150:153], v[198:201], v[78:81]
	s_setprio 0
	s_setprio 1
	v_mfma_f32_16x16x32_bf16 v[114:117], v[154:157], v[170:173], v[114:117]
	v_mfma_f32_16x16x32_bf16 v[106:109], v[162:165], v[170:173], v[106:109]
	v_mfma_f32_16x16x32_bf16 v[98:101], v[154:157], v[178:181], v[98:101]
	v_mfma_f32_16x16x32_bf16 v[90:93], v[162:165], v[178:181], v[90:93]
	v_mfma_f32_16x16x32_bf16 v[82:85], v[154:157], v[186:189], v[82:85]
	v_mfma_f32_16x16x32_bf16 v[74:77], v[162:165], v[186:189], v[74:77]
	v_mfma_f32_16x16x32_bf16 v[70:73], v[154:157], v[194:197], v[70:73]
	v_mfma_f32_16x16x32_bf16 v[62:65], v[162:165], v[194:197], v[62:65]
	s_setprio 0
	s_setprio 1
	v_mfma_f32_16x16x32_bf16 v[114:117], v[158:161], v[174:177], v[114:117]
	v_mfma_f32_16x16x32_bf16 v[106:109], v[166:169], v[174:177], v[106:109]
	v_mfma_f32_16x16x32_bf16 v[98:101], v[158:161], v[182:185], v[98:101]
	v_mfma_f32_16x16x32_bf16 v[90:93], v[166:169], v[182:185], v[90:93]
	v_mfma_f32_16x16x32_bf16 v[82:85], v[158:161], v[190:193], v[82:85]
	v_mfma_f32_16x16x32_bf16 v[74:77], v[166:169], v[190:193], v[74:77]
	v_mfma_f32_16x16x32_bf16 v[70:73], v[158:161], v[198:201], v[70:73]
	v_mfma_f32_16x16x32_bf16 v[62:65], v[166:169], v[198:201], v[62:65]
	s_setprio 0
	s_barrier
	ds_read_b128 v[170:173], v137 offset:49152
	ds_read_b128 v[174:177], v137 offset:50176
	ds_read_b128 v[178:181], v137 offset:51200
	ds_read_b128 v[182:185], v137 offset:52224
	ds_read_b128 v[186:189], v137 offset:53248
	ds_read_b128 v[190:193], v137 offset:54272
	ds_read_b128 v[194:197], v137 offset:55296
	ds_read_b128 v[198:201], v137 offset:56320
	s_mov_b32 m0, s64
	s_add_u32 s100, s12, s38
	s_addc_u32 s101, s13, s39
	global_load_lds_dwordx4 v131, s[100:101]
	s_mov_b32 m0, s61
	s_nop 0
	global_load_lds_dwordx4 v133, s[100:101]
	s_mov_b32 m0, s71
	s_nop 0
	global_load_lds_dwordx4 v131, s[14:15]
	s_mov_b32 m0, s70
	s_nop 0
	global_load_lds_dwordx4 v133, s[14:15]
	s_mov_b32 m0, s59
	s_add_u32 s100, s10, s38
	s_addc_u32 s101, s11, s39
	v_mov_b32_e32 v0, v132
	global_load_lds_dwordx4 v130, s[100:101]
	s_mov_b32 m0, s60
	s_nop 0
	global_load_lds_dwordx4 v132, s[100:101]
	s_waitcnt vmcnt(8)
	s_waitcnt lgkmcnt(0)
	s_barrier
	s_setprio 1
	s_waitcnt lgkmcnt(0)
	v_mfma_f32_16x16x32_bf16 v[66:69], v[138:141], v[170:173], v[66:69]
	v_mfma_f32_16x16x32_bf16 v[58:61], v[146:149], v[170:173], v[58:61]
	v_mfma_f32_16x16x32_bf16 v[54:57], v[138:141], v[178:181], v[54:57]
	v_mfma_f32_16x16x32_bf16 v[46:49], v[146:149], v[178:181], v[46:49]
	v_mfma_f32_16x16x32_bf16 v[38:41], v[138:141], v[186:189], v[38:41]
	v_mfma_f32_16x16x32_bf16 v[30:33], v[146:149], v[186:189], v[30:33]
	v_mfma_f32_16x16x32_bf16 v[22:25], v[138:141], v[194:197], v[22:25]
	v_mfma_f32_16x16x32_bf16 v[14:17], v[146:149], v[194:197], v[14:17]
	s_setprio 0
	s_setprio 1
	v_mfma_f32_16x16x32_bf16 v[66:69], v[142:145], v[174:177], v[66:69]
	v_mfma_f32_16x16x32_bf16 v[58:61], v[150:153], v[174:177], v[58:61]
	v_mfma_f32_16x16x32_bf16 v[54:57], v[142:145], v[182:185], v[54:57]
	v_mfma_f32_16x16x32_bf16 v[46:49], v[150:153], v[182:185], v[46:49]
	v_mfma_f32_16x16x32_bf16 v[38:41], v[142:145], v[190:193], v[38:41]
	v_mfma_f32_16x16x32_bf16 v[30:33], v[150:153], v[190:193], v[30:33]
	v_mfma_f32_16x16x32_bf16 v[22:25], v[142:145], v[198:201], v[22:25]
	v_mfma_f32_16x16x32_bf16 v[14:17], v[150:153], v[198:201], v[14:17]
	s_setprio 0
	s_setprio 1
	v_mfma_f32_16x16x32_bf16 v[50:53], v[154:157], v[170:173], v[50:53]
	v_mfma_f32_16x16x32_bf16 v[42:45], v[162:165], v[170:173], v[42:45]
	v_mfma_f32_16x16x32_bf16 v[34:37], v[154:157], v[178:181], v[34:37]
	v_mfma_f32_16x16x32_bf16 v[26:29], v[162:165], v[178:181], v[26:29]
	v_mfma_f32_16x16x32_bf16 v[18:21], v[154:157], v[186:189], v[18:21]
	v_mfma_f32_16x16x32_bf16 v[10:13], v[162:165], v[186:189], v[10:13]
	v_mfma_f32_16x16x32_bf16 v[6:9], v[154:157], v[194:197], v[6:9]
	v_mfma_f32_16x16x32_bf16 v[2:5], v[162:165], v[194:197], v[2:5]
	s_setprio 0
	s_setprio 1
	v_mfma_f32_16x16x32_bf16 v[50:53], v[158:161], v[174:177], v[50:53]
	v_mfma_f32_16x16x32_bf16 v[42:45], v[166:169], v[174:177], v[42:45]
	v_mfma_f32_16x16x32_bf16 v[34:37], v[158:161], v[182:185], v[34:37]
	v_mfma_f32_16x16x32_bf16 v[26:29], v[166:169], v[182:185], v[26:29]
	v_mfma_f32_16x16x32_bf16 v[18:21], v[158:161], v[190:193], v[18:21]
	v_mfma_f32_16x16x32_bf16 v[10:13], v[166:169], v[190:193], v[10:13]
	v_mfma_f32_16x16x32_bf16 v[6:9], v[158:161], v[198:201], v[6:9]
	v_mfma_f32_16x16x32_bf16 v[2:5], v[166:169], v[198:201], v[2:5]
	s_setprio 0
	s_barrier
	s_andn2_b64 vcc, exec, s[8:9]
	s_mov_b64 s[12:13], -1
	s_mov_b64 s[8:9], 0
	s_mov_b64 s[14:15], 0x100
	s_cbranch_vccz .LBB0_1481
	s_cmpk_lt_u32 s24, 0x100
	s_cbranch_scc0 .LBB0_1484
	s_barrier

.LBB0_1570:
	s_add_u32 s48, s41, s6
	s_addc_u32 s49, s42, s7
	s_add_u32 s8, s48, 0x9800100
	s_addc_u32 s9, s49, 0
	s_add_u32 s10, s43, s6
	s_addc_u32 s11, s46, s7
	s_cmpk_eq_i32 s6, 0x700
	s_cselect_b32 s9, s3, s9
	s_cselect_b32 s8, s2, s8
	s_cselect_b32 s11, s26, s11
	s_cselect_b32 s10, s25, s10
	s_add_i32 s50, 0, 0x10000
	v_add_u32_e32 v0, s50, v169
	s_add_i32 s51, 0, 0x14000
	ds_read_b128 v[172:175], v0
	ds_read_b128 v[176:179], v0 offset:1024
	ds_read_b128 v[180:183], v0 offset:2048
	ds_read_b128 v[184:187], v0 offset:3072
	ds_read_b128 v[188:191], v0 offset:16384
	ds_read_b128 v[192:195], v0 offset:17408
	ds_read_b128 v[196:199], v0 offset:18432
	ds_read_b128 v[200:203], v0 offset:19456
	ds_read_b128 v[204:207], v170
	ds_read_b128 v[208:211], v170 offset:1024
	ds_read_b128 v[212:215], v170 offset:2048
	ds_read_b128 v[216:219], v170 offset:3072
	ds_read_b128 v[220:223], v170 offset:4096
	ds_read_b128 v[224:227], v170 offset:5120
	ds_read_b128 v[232:235], v170 offset:6144
	ds_read_b128 v[242:245], v170 offset:7168
	s_mov_b64 s[58:59], 0x9840080
	s_add_u32 s100, s48, s58
	s_addc_u32 s101, s49, s59
	s_add_i32 m0, s17, 0xc000
	s_nop 0
	global_load_lds_dwordx4 v164, s[100:101]
	s_add_i32 m0, s17, 0xe000
	s_nop 0
	global_load_lds_dwordx4 v166, s[100:101]
	s_waitcnt vmcnt(8)
	s_waitcnt lgkmcnt(0)
	s_barrier
	s_setprio 1
	s_waitcnt lgkmcnt(0)
	v_mfma_f32_16x16x32_bf16 v[160:163], v[172:175], v[204:207], v[160:163]
	v_mfma_f32_16x16x32_bf16 v[156:159], v[180:183], v[204:207], v[156:159]
	v_mfma_f32_16x16x32_bf16 v[112:115], v[172:175], v[212:215], v[112:115]
	v_mfma_f32_16x16x32_bf16 v[108:111], v[180:183], v[212:215], v[108:111]
	v_mfma_f32_16x16x32_bf16 v[96:99], v[172:175], v[220:223], v[96:99]
	v_mfma_f32_16x16x32_bf16 v[92:95], v[180:183], v[220:223], v[92:95]
	v_mfma_f32_16x16x32_bf16 v[80:83], v[172:175], v[232:235], v[80:83]
	v_mfma_f32_16x16x32_bf16 v[76:79], v[180:183], v[232:235], v[76:79]
	s_setprio 0
	s_setprio 1
	v_mfma_f32_16x16x32_bf16 v[160:163], v[176:179], v[208:211], v[160:163]
	v_mfma_f32_16x16x32_bf16 v[156:159], v[184:187], v[208:211], v[156:159]
	v_mfma_f32_16x16x32_bf16 v[112:115], v[176:179], v[216:219], v[112:115]
	v_mfma_f32_16x16x32_bf16 v[108:111], v[184:187], v[216:219], v[108:111]
	v_mfma_f32_16x16x32_bf16 v[96:99], v[176:179], v[224:227], v[96:99]
	v_mfma_f32_16x16x32_bf16 v[92:95], v[184:187], v[224:227], v[92:95]
	v_mfma_f32_16x16x32_bf16 v[80:83], v[176:179], v[242:245], v[80:83]
	v_mfma_f32_16x16x32_bf16 v[76:79], v[184:187], v[242:245], v[76:79]
	s_setprio 0
	s_setprio 1
	v_mfma_f32_16x16x32_bf16 v[128:131], v[188:191], v[204:207], v[128:131]
	v_mfma_f32_16x16x32_bf16 v[120:123], v[196:199], v[204:207], v[120:123]
	v_mfma_f32_16x16x32_bf16 v[104:107], v[188:191], v[212:215], v[104:107]
	v_mfma_f32_16x16x32_bf16 v[100:103], v[196:199], v[212:215], v[100:103]
	v_mfma_f32_16x16x32_bf16 v[88:91], v[188:191], v[220:223], v[88:91]
	v_mfma_f32_16x16x32_bf16 v[84:87], v[196:199], v[220:223], v[84:87]
	v_mfma_f32_16x16x32_bf16 v[72:75], v[188:191], v[232:235], v[72:75]
	v_mfma_f32_16x16x32_bf16 v[68:71], v[196:199], v[232:235], v[68:71]
	s_setprio 0
	s_setprio 1
	v_mfma_f32_16x16x32_bf16 v[128:131], v[192:195], v[208:211], v[128:131]
	v_mfma_f32_16x16x32_bf16 v[120:123], v[200:203], v[208:211], v[120:123]
	v_mfma_f32_16x16x32_bf16 v[104:107], v[192:195], v[216:219], v[104:107]
	v_mfma_f32_16x16x32_bf16 v[100:103], v[200:203], v[216:219], v[100:103]
	v_mfma_f32_16x16x32_bf16 v[88:91], v[192:195], v[224:227], v[88:91]
	v_mfma_f32_16x16x32_bf16 v[84:87], v[200:203], v[224:227], v[84:87]
	v_mfma_f32_16x16x32_bf16 v[72:75], v[192:195], v[242:245], v[72:75]
	v_mfma_f32_16x16x32_bf16 v[68:71], v[200:203], v[242:245], v[68:71]
	s_setprio 0
	s_barrier
	s_add_i32 s48, s50, s16
	ds_read_b128 v[204:207], v170 offset:16384
	ds_read_b128 v[208:211], v170 offset:17408
	ds_read_b128 v[212:215], v170 offset:18432
	ds_read_b128 v[216:219], v170 offset:19456
	ds_read_b128 v[220:223], v170 offset:20480
	ds_read_b128 v[224:227], v170 offset:21504
	ds_read_b128 v[232:235], v170 offset:22528
	ds_read_b128 v[242:245], v170 offset:23552
	s_mov_b32 m0, s48
	s_nop 0
	global_load_lds_dwordx4 v167, s[10:11]
	s_add_i32 m0, s48, 0x2000
	s_add_u32 s48, s10, 0x40000
	global_load_lds_dwordx4 v168, s[10:11]
	s_addc_u32 s49, s11, 0
	s_add_i32 s50, s51, s16
	s_mov_b32 m0, s50
	s_nop 0
	global_load_lds_dwordx4 v167, s[48:49]
	s_add_i32 m0, s50, 0x2000
	s_nop 0
	global_load_lds_dwordx4 v168, s[48:49]
	s_mov_b32 m0, s17
	s_nop 0
	global_load_lds_dwordx4 v164, s[8:9]
	s_mov_b32 m0, s22
	s_nop 0
	global_load_lds_dwordx4 v166, s[8:9]
	s_waitcnt vmcnt(8)
	s_waitcnt lgkmcnt(0)
	s_barrier
	s_setprio 1
	s_waitcnt lgkmcnt(0)
	v_mfma_f32_16x16x32_bf16 v[64:67], v[172:175], v[204:207], v[64:67]
	v_mfma_f32_16x16x32_bf16 v[60:63], v[180:183], v[204:207], v[60:63]
	v_mfma_f32_16x16x32_bf16 v[48:51], v[172:175], v[212:215], v[48:51]
	v_mfma_f32_16x16x32_bf16 v[44:47], v[180:183], v[212:215], v[44:47]
	v_mfma_f32_16x16x32_bf16 v[32:35], v[172:175], v[220:223], v[32:35]
	v_mfma_f32_16x16x32_bf16 v[28:31], v[180:183], v[220:223], v[28:31]
	v_mfma_f32_16x16x32_bf16 v[16:19], v[172:175], v[232:235], v[16:19]
	v_mfma_f32_16x16x32_bf16 v[12:15], v[180:183], v[232:235], v[12:15]
	s_setprio 0
	s_setprio 1
	v_mfma_f32_16x16x32_bf16 v[64:67], v[176:179], v[208:211], v[64:67]
	v_mfma_f32_16x16x32_bf16 v[60:63], v[184:187], v[208:211], v[60:63]
	v_mfma_f32_16x16x32_bf16 v[48:51], v[176:179], v[216:219], v[48:51]
	v_mfma_f32_16x16x32_bf16 v[44:47], v[184:187], v[216:219], v[44:47]
	v_mfma_f32_16x16x32_bf16 v[32:35], v[176:179], v[224:227], v[32:35]
	v_mfma_f32_16x16x32_bf16 v[28:31], v[184:187], v[224:227], v[28:31]
	v_mfma_f32_16x16x32_bf16 v[16:19], v[176:179], v[242:245], v[16:19]
	v_mfma_f32_16x16x32_bf16 v[12:15], v[184:187], v[242:245], v[12:15]
	s_setprio 0
	s_setprio 1
	v_mfma_f32_16x16x32_bf16 v[56:59], v[188:191], v[204:207], v[56:59]
	v_mfma_f32_16x16x32_bf16 v[52:55], v[196:199], v[204:207], v[52:55]
	v_mfma_f32_16x16x32_bf16 v[40:43], v[188:191], v[212:215], v[40:43]
	v_mfma_f32_16x16x32_bf16 v[36:39], v[196:199], v[212:215], v[36:39]
	v_mfma_f32_16x16x32_bf16 v[24:27], v[188:191], v[220:223], v[24:27]
	v_mfma_f32_16x16x32_bf16 v[20:23], v[196:199], v[220:223], v[20:23]
	v_mfma_f32_16x16x32_bf16 v[8:11], v[188:191], v[232:235], v[8:11]
	v_mfma_f32_16x16x32_bf16 v[2:5], v[196:199], v[232:235], v[4:7]
	s_setprio 0
	s_setprio 1
	v_mfma_f32_16x16x32_bf16 v[56:59], v[192:195], v[208:211], v[56:59]
	v_mfma_f32_16x16x32_bf16 v[52:55], v[200:203], v[208:211], v[52:55]
	v_mfma_f32_16x16x32_bf16 v[40:43], v[192:195], v[216:219], v[40:43]
	v_mfma_f32_16x16x32_bf16 v[36:39], v[200:203], v[216:219], v[36:39]
	v_mfma_f32_16x16x32_bf16 v[24:27], v[192:195], v[224:227], v[24:27]
	v_mfma_f32_16x16x32_bf16 v[20:23], v[200:203], v[224:227], v[20:23]
	v_mfma_f32_16x16x32_bf16 v[8:11], v[192:195], v[242:245], v[8:11]
	v_mfma_f32_16x16x32_bf16 v[2:5], v[200:203], v[242:245], v[2:5]
	s_setprio 0
	s_barrier
	s_add_i32 s50, 0, 0x18000
	s_add_i32 s51, 0, 0x1c000
	ds_read_b128 v[172:175], v0 offset:32768
	ds_read_b128 v[176:179], v0 offset:33792
	ds_read_b128 v[180:183], v0 offset:34816
	ds_read_b128 v[184:187], v0 offset:35840
	ds_read_b128 v[188:191], v0 offset:49152
	ds_read_b128 v[192:195], v0 offset:50176
	ds_read_b128 v[196:199], v0 offset:51200
	ds_read_b128 v[200:203], v0 offset:52224
	s_add_u32 s48, s8, 0x40000
	s_mov_b32 m0, s23
	ds_read_b128 v[204:207], v170 offset:32768
	ds_read_b128 v[208:211], v170 offset:33792
	ds_read_b128 v[212:215], v170 offset:34816
	ds_read_b128 v[216:219], v170 offset:35840
	ds_read_b128 v[220:223], v170 offset:36864
	ds_read_b128 v[224:227], v170 offset:37888
	ds_read_b128 v[232:235], v170 offset:38912
	ds_read_b128 v[242:245], v170 offset:39936
	s_addc_u32 s49, s9, 0
	s_nop 0
	global_load_lds_dwordx4 v164, s[48:49]
	s_mov_b32 m0, s24
	s_nop 0
	global_load_lds_dwordx4 v166, s[48:49]
	s_waitcnt vmcnt(8)
	s_waitcnt lgkmcnt(0)
	s_barrier
	s_setprio 1
	s_waitcnt lgkmcnt(0)
	v_mfma_f32_16x16x32_bf16 v[160:163], v[172:175], v[204:207], v[160:163]
	v_mfma_f32_16x16x32_bf16 v[156:159], v[180:183], v[204:207], v[156:159]
	v_mfma_f32_16x16x32_bf16 v[112:115], v[172:175], v[212:215], v[112:115]
	v_mfma_f32_16x16x32_bf16 v[108:111], v[180:183], v[212:215], v[108:111]
	v_mfma_f32_16x16x32_bf16 v[96:99], v[172:175], v[220:223], v[96:99]
	v_mfma_f32_16x16x32_bf16 v[92:95], v[180:183], v[220:223], v[92:95]
	v_mfma_f32_16x16x32_bf16 v[80:83], v[172:175], v[232:235], v[80:83]
	v_mfma_f32_16x16x32_bf16 v[76:79], v[180:183], v[232:235], v[76:79]
	s_setprio 0
	s_setprio 1
	v_mfma_f32_16x16x32_bf16 v[160:163], v[176:179], v[208:211], v[160:163]
	v_mfma_f32_16x16x32_bf16 v[156:159], v[184:187], v[208:211], v[156:159]
	v_mfma_f32_16x16x32_bf16 v[112:115], v[176:179], v[216:219], v[112:115]
	v_mfma_f32_16x16x32_bf16 v[108:111], v[184:187], v[216:219], v[108:111]
	v_mfma_f32_16x16x32_bf16 v[96:99], v[176:179], v[224:227], v[96:99]
	v_mfma_f32_16x16x32_bf16 v[92:95], v[184:187], v[224:227], v[92:95]
	v_mfma_f32_16x16x32_bf16 v[80:83], v[176:179], v[242:245], v[80:83]
	v_mfma_f32_16x16x32_bf16 v[76:79], v[184:187], v[242:245], v[76:79]
	s_setprio 0
	s_setprio 1
	v_mfma_f32_16x16x32_bf16 v[128:131], v[188:191], v[204:207], v[128:131]
	v_mfma_f32_16x16x32_bf16 v[120:123], v[196:199], v[204:207], v[120:123]
	v_mfma_f32_16x16x32_bf16 v[104:107], v[188:191], v[212:215], v[104:107]
	v_mfma_f32_16x16x32_bf16 v[100:103], v[196:199], v[212:215], v[100:103]
	v_mfma_f32_16x16x32_bf16 v[88:91], v[188:191], v[220:223], v[88:91]
	v_mfma_f32_16x16x32_bf16 v[84:87], v[196:199], v[220:223], v[84:87]
	v_mfma_f32_16x16x32_bf16 v[72:75], v[188:191], v[232:235], v[72:75]
	v_mfma_f32_16x16x32_bf16 v[68:71], v[196:199], v[232:235], v[68:71]
	s_setprio 0
	s_setprio 1
	v_mfma_f32_16x16x32_bf16 v[128:131], v[192:195], v[208:211], v[128:131]
	v_mfma_f32_16x16x32_bf16 v[120:123], v[200:203], v[208:211], v[120:123]
	v_mfma_f32_16x16x32_bf16 v[104:107], v[192:195], v[216:219], v[104:107]
	v_mfma_f32_16x16x32_bf16 v[100:103], v[200:203], v[216:219], v[100:103]
	v_mfma_f32_16x16x32_bf16 v[88:91], v[192:195], v[224:227], v[88:91]
	v_mfma_f32_16x16x32_bf16 v[84:87], v[200:203], v[224:227], v[84:87]
	v_mfma_f32_16x16x32_bf16 v[72:75], v[192:195], v[242:245], v[72:75]
	v_mfma_f32_16x16x32_bf16 v[68:71], v[200:203], v[242:245], v[68:71]
	s_setprio 0
	s_barrier
	ds_read_b128 v[204:207], v170 offset:49152
	ds_read_b128 v[208:211], v170 offset:50176
	ds_read_b128 v[212:215], v170 offset:51200
	ds_read_b128 v[216:219], v170 offset:52224
	ds_read_b128 v[220:223], v170 offset:53248
	ds_read_b128 v[224:227], v170 offset:54272
	ds_read_b128 v[232:235], v170 offset:55296
	ds_read_b128 v[242:245], v170 offset:56320
	s_add_i32 s48, s50, s16
	s_add_u32 s100, s10, s38
	s_addc_u32 s101, s11, s39
	s_mov_b32 m0, s48
	s_nop 0
	global_load_lds_dwordx4 v167, s[100:101]
	s_add_i32 m0, s48, 0x2000
	s_nop 0
	s_add_u32 s10, s10, 0x40080
	s_addc_u32 s11, s11, 0
	s_add_i32 s48, s51, s16
	global_load_lds_dwordx4 v168, s[100:101]
	s_mov_b32 m0, s48
	s_nop 0
	global_load_lds_dwordx4 v167, s[10:11]
	s_add_i32 m0, s48, 0x2000
	s_nop 0
	global_load_lds_dwordx4 v168, s[10:11]
	s_mov_b32 m0, s37
	s_add_u32 s100, s8, s38
	s_addc_u32 s101, s9, s39
	v_mov_b32_e32 v0, v166
	global_load_lds_dwordx4 v164, s[100:101]
	s_mov_b32 m0, s40
	s_nop 0
	global_load_lds_dwordx4 v166, s[100:101]
	s_waitcnt vmcnt(8)
	s_waitcnt lgkmcnt(0)
	s_barrier
	s_setprio 1
	s_waitcnt lgkmcnt(0)
	v_mfma_f32_16x16x32_bf16 v[64:67], v[172:175], v[204:207], v[64:67]
	v_mfma_f32_16x16x32_bf16 v[60:63], v[180:183], v[204:207], v[60:63]
	v_mfma_f32_16x16x32_bf16 v[48:51], v[172:175], v[212:215], v[48:51]
	v_mfma_f32_16x16x32_bf16 v[44:47], v[180:183], v[212:215], v[44:47]
	v_mfma_f32_16x16x32_bf16 v[32:35], v[172:175], v[220:223], v[32:35]
	v_mfma_f32_16x16x32_bf16 v[28:31], v[180:183], v[220:223], v[28:31]
	v_mfma_f32_16x16x32_bf16 v[16:19], v[172:175], v[232:235], v[16:19]
	v_mfma_f32_16x16x32_bf16 v[12:15], v[180:183], v[232:235], v[12:15]
	s_setprio 0
	s_setprio 1
	v_mfma_f32_16x16x32_bf16 v[64:67], v[176:179], v[208:211], v[64:67]
	v_mfma_f32_16x16x32_bf16 v[60:63], v[184:187], v[208:211], v[60:63]
	v_mfma_f32_16x16x32_bf16 v[48:51], v[176:179], v[216:219], v[48:51]
	v_mfma_f32_16x16x32_bf16 v[44:47], v[184:187], v[216:219], v[44:47]
	v_mfma_f32_16x16x32_bf16 v[32:35], v[176:179], v[224:227], v[32:35]
	v_mfma_f32_16x16x32_bf16 v[28:31], v[184:187], v[224:227], v[28:31]
	v_mfma_f32_16x16x32_bf16 v[16:19], v[176:179], v[242:245], v[16:19]
	v_mfma_f32_16x16x32_bf16 v[12:15], v[184:187], v[242:245], v[12:15]
	s_setprio 0
	s_setprio 1
	v_mfma_f32_16x16x32_bf16 v[56:59], v[188:191], v[204:207], v[56:59]
	v_mfma_f32_16x16x32_bf16 v[52:55], v[196:199], v[204:207], v[52:55]
	v_mfma_f32_16x16x32_bf16 v[40:43], v[188:191], v[212:215], v[40:43]
	v_mfma_f32_16x16x32_bf16 v[36:39], v[196:199], v[212:215], v[36:39]
	v_mfma_f32_16x16x32_bf16 v[24:27], v[188:191], v[220:223], v[24:27]
	v_mfma_f32_16x16x32_bf16 v[20:23], v[196:199], v[220:223], v[20:23]
	v_mfma_f32_16x16x32_bf16 v[6:9], v[188:191], v[232:235], v[8:11]
	v_mfma_f32_16x16x32_bf16 v[2:5], v[196:199], v[232:235], v[2:5]
	s_setprio 0
	s_setprio 1
	v_mfma_f32_16x16x32_bf16 v[56:59], v[192:195], v[208:211], v[56:59]
	v_mfma_f32_16x16x32_bf16 v[52:55], v[200:203], v[208:211], v[52:55]
	v_mfma_f32_16x16x32_bf16 v[40:43], v[192:195], v[216:219], v[40:43]
	v_mfma_f32_16x16x32_bf16 v[36:39], v[200:203], v[216:219], v[36:39]
	v_mfma_f32_16x16x32_bf16 v[24:27], v[192:195], v[224:227], v[24:27]
	v_mfma_f32_16x16x32_bf16 v[20:23], v[200:203], v[224:227], v[20:23]
	v_mfma_f32_16x16x32_bf16 v[8:11], v[192:195], v[242:245], v[6:9]
	v_mfma_f32_16x16x32_bf16 v[4:7], v[200:203], v[242:245], v[2:5]
	s_setprio 0
	s_barrier
	s_add_i32 s47, s47, 2
	s_add_u32 s6, s6, 0x100
	s_addc_u32 s7, s7, 0
	s_cmp_gt_u32 s47, 13
	s_cbranch_scc1 .LBB0_1573

.LBB0_1681:
	s_add_u32 s48, s6, s2
	s_addc_u32 s49, s7, s3
	s_add_u32 s10, s48, 0x100
	s_addc_u32 s11, s49, 0
	s_add_u32 s12, s37, s2
	s_addc_u32 s13, s40, s3
	s_add_i32 s47, 0, 0x10000
	s_cmp_eq_u32 s46, 12
	s_cselect_b32 s11, s7, s11
	s_cselect_b32 s10, s6, s10
	v_add_u32_e32 v0, s47, v136
	s_cselect_b32 s13, s9, s13
	s_cselect_b32 s12, s8, s12
	s_add_i32 s50, 0, 0x14000
	ds_read_b128 v[138:141], v0
	ds_read_b128 v[142:145], v0 offset:1024
	ds_read_b128 v[146:149], v0 offset:2048
	ds_read_b128 v[150:153], v0 offset:3072
	ds_read_b128 v[154:157], v0 offset:16384
	ds_read_b128 v[158:161], v0 offset:17408
	ds_read_b128 v[162:165], v0 offset:18432
	ds_read_b128 v[166:169], v0 offset:19456
	ds_read_b128 v[170:173], v137
	ds_read_b128 v[174:177], v137 offset:1024
	ds_read_b128 v[178:181], v137 offset:2048
	ds_read_b128 v[182:185], v137 offset:3072
	ds_read_b128 v[186:189], v137 offset:4096
	ds_read_b128 v[190:193], v137 offset:5120
	ds_read_b128 v[194:197], v137 offset:6144
	ds_read_b128 v[198:201], v137 offset:7168
	s_add_i32 m0, s23, 0xc000
	s_add_u32 s100, s48, s56
	s_addc_u32 s101, s49, s57
	global_load_lds_dwordx4 v130, s[100:101]
	s_add_i32 m0, s23, 0xe000
	s_nop 0
	global_load_lds_dwordx4 v132, s[100:101]
	s_waitcnt vmcnt(8)
	s_waitcnt lgkmcnt(0)
	s_barrier
	s_setprio 1
	s_waitcnt lgkmcnt(0)
	v_mfma_f32_16x16x32_bf16 v[126:129], v[138:141], v[170:173], v[126:129]
	v_mfma_f32_16x16x32_bf16 v[122:125], v[146:149], v[170:173], v[122:125]
	v_mfma_f32_16x16x32_bf16 v[110:113], v[138:141], v[178:181], v[110:113]
	v_mfma_f32_16x16x32_bf16 v[106:109], v[146:149], v[178:181], v[106:109]
	v_mfma_f32_16x16x32_bf16 v[94:97], v[138:141], v[186:189], v[94:97]
	v_mfma_f32_16x16x32_bf16 v[90:93], v[146:149], v[186:189], v[90:93]
	v_mfma_f32_16x16x32_bf16 v[78:81], v[138:141], v[194:197], v[78:81]
	v_mfma_f32_16x16x32_bf16 v[74:77], v[146:149], v[194:197], v[74:77]
	s_setprio 0
	s_setprio 1
	v_mfma_f32_16x16x32_bf16 v[126:129], v[142:145], v[174:177], v[126:129]
	v_mfma_f32_16x16x32_bf16 v[122:125], v[150:153], v[174:177], v[122:125]
	v_mfma_f32_16x16x32_bf16 v[110:113], v[142:145], v[182:185], v[110:113]
	v_mfma_f32_16x16x32_bf16 v[106:109], v[150:153], v[182:185], v[106:109]
	v_mfma_f32_16x16x32_bf16 v[94:97], v[142:145], v[190:193], v[94:97]
	v_mfma_f32_16x16x32_bf16 v[90:93], v[150:153], v[190:193], v[90:93]
	v_mfma_f32_16x16x32_bf16 v[78:81], v[142:145], v[198:201], v[78:81]
	v_mfma_f32_16x16x32_bf16 v[74:77], v[150:153], v[198:201], v[74:77]
	s_setprio 0
	s_setprio 1
	v_mfma_f32_16x16x32_bf16 v[118:121], v[154:157], v[170:173], v[118:121]
	v_mfma_f32_16x16x32_bf16 v[114:117], v[162:165], v[170:173], v[114:117]
	v_mfma_f32_16x16x32_bf16 v[102:105], v[154:157], v[178:181], v[102:105]
	v_mfma_f32_16x16x32_bf16 v[98:101], v[162:165], v[178:181], v[98:101]
	v_mfma_f32_16x16x32_bf16 v[86:89], v[154:157], v[186:189], v[86:89]
	v_mfma_f32_16x16x32_bf16 v[82:85], v[162:165], v[186:189], v[82:85]
	v_mfma_f32_16x16x32_bf16 v[70:73], v[154:157], v[194:197], v[70:73]
	v_mfma_f32_16x16x32_bf16 v[66:69], v[162:165], v[194:197], v[66:69]
	s_setprio 0
	s_setprio 1
	v_mfma_f32_16x16x32_bf16 v[118:121], v[158:161], v[174:177], v[118:121]
	v_mfma_f32_16x16x32_bf16 v[114:117], v[166:169], v[174:177], v[114:117]
	v_mfma_f32_16x16x32_bf16 v[102:105], v[158:161], v[182:185], v[102:105]
	v_mfma_f32_16x16x32_bf16 v[98:101], v[166:169], v[182:185], v[98:101]
	v_mfma_f32_16x16x32_bf16 v[86:89], v[158:161], v[190:193], v[86:89]
	v_mfma_f32_16x16x32_bf16 v[82:85], v[166:169], v[190:193], v[82:85]
	v_mfma_f32_16x16x32_bf16 v[70:73], v[158:161], v[198:201], v[70:73]
	v_mfma_f32_16x16x32_bf16 v[66:69], v[166:169], v[198:201], v[66:69]
	s_setprio 0
	s_barrier
	s_add_i32 s47, s47, s22
	ds_read_b128 v[170:173], v137 offset:16384
	ds_read_b128 v[174:177], v137 offset:17408
	ds_read_b128 v[178:181], v137 offset:18432
	ds_read_b128 v[182:185], v137 offset:19456
	ds_read_b128 v[186:189], v137 offset:20480
	ds_read_b128 v[190:193], v137 offset:21504
	ds_read_b128 v[194:197], v137 offset:22528
	ds_read_b128 v[198:201], v137 offset:23552
	s_mov_b32 m0, s47
	s_nop 0
	global_load_lds_dwordx4 v134, s[12:13]
	s_add_i32 m0, s47, 0x2000
	s_add_u32 s48, s12, 0x40000
	global_load_lds_dwordx4 v135, s[12:13]
	s_addc_u32 s49, s13, 0
	s_add_i32 s47, s50, s22
	s_mov_b32 m0, s47
	s_nop 0
	global_load_lds_dwordx4 v134, s[48:49]
	s_add_i32 m0, s47, 0x2000
	s_nop 0
	global_load_lds_dwordx4 v135, s[48:49]
	s_mov_b32 m0, s23
	s_nop 0
	global_load_lds_dwordx4 v130, s[10:11]
	s_mov_b32 m0, s24
	s_nop 0
	global_load_lds_dwordx4 v132, s[10:11]
	s_waitcnt vmcnt(8)
	s_waitcnt lgkmcnt(0)
	s_barrier
	s_setprio 1
	s_waitcnt lgkmcnt(0)
	v_mfma_f32_16x16x32_bf16 v[62:65], v[138:141], v[170:173], v[62:65]
	v_mfma_f32_16x16x32_bf16 v[58:61], v[146:149], v[170:173], v[58:61]
	v_mfma_f32_16x16x32_bf16 v[46:49], v[138:141], v[178:181], v[46:49]
	v_mfma_f32_16x16x32_bf16 v[42:45], v[146:149], v[178:181], v[42:45]
	v_mfma_f32_16x16x32_bf16 v[30:33], v[138:141], v[186:189], v[30:33]
	v_mfma_f32_16x16x32_bf16 v[26:29], v[146:149], v[186:189], v[26:29]
	v_mfma_f32_16x16x32_bf16 v[14:17], v[138:141], v[194:197], v[14:17]
	v_mfma_f32_16x16x32_bf16 v[10:13], v[146:149], v[194:197], v[10:13]
	s_setprio 0
	s_setprio 1
	v_mfma_f32_16x16x32_bf16 v[62:65], v[142:145], v[174:177], v[62:65]
	v_mfma_f32_16x16x32_bf16 v[58:61], v[150:153], v[174:177], v[58:61]
	v_mfma_f32_16x16x32_bf16 v[46:49], v[142:145], v[182:185], v[46:49]
	v_mfma_f32_16x16x32_bf16 v[42:45], v[150:153], v[182:185], v[42:45]
	v_mfma_f32_16x16x32_bf16 v[30:33], v[142:145], v[190:193], v[30:33]
	v_mfma_f32_16x16x32_bf16 v[26:29], v[150:153], v[190:193], v[26:29]
	v_mfma_f32_16x16x32_bf16 v[14:17], v[142:145], v[198:201], v[14:17]
	v_mfma_f32_16x16x32_bf16 v[10:13], v[150:153], v[198:201], v[10:13]
	s_setprio 0
	s_setprio 1
	v_mfma_f32_16x16x32_bf16 v[54:57], v[154:157], v[170:173], v[54:57]
	v_mfma_f32_16x16x32_bf16 v[50:53], v[162:165], v[170:173], v[50:53]
	v_mfma_f32_16x16x32_bf16 v[38:41], v[154:157], v[178:181], v[38:41]
	v_mfma_f32_16x16x32_bf16 v[34:37], v[162:165], v[178:181], v[34:37]
	v_mfma_f32_16x16x32_bf16 v[22:25], v[154:157], v[186:189], v[22:25]
	v_mfma_f32_16x16x32_bf16 v[18:21], v[162:165], v[186:189], v[18:21]
	v_mfma_f32_16x16x32_bf16 v[6:9], v[154:157], v[194:197], v[6:9]
	v_mfma_f32_16x16x32_bf16 v[2:5], v[162:165], v[194:197], v[2:5]
	s_setprio 0
	s_setprio 1
	v_mfma_f32_16x16x32_bf16 v[54:57], v[158:161], v[174:177], v[54:57]
	v_mfma_f32_16x16x32_bf16 v[50:53], v[166:169], v[174:177], v[50:53]
	v_mfma_f32_16x16x32_bf16 v[38:41], v[158:161], v[182:185], v[38:41]
	v_mfma_f32_16x16x32_bf16 v[34:37], v[166:169], v[182:185], v[34:37]
	v_mfma_f32_16x16x32_bf16 v[22:25], v[158:161], v[190:193], v[22:25]
	v_mfma_f32_16x16x32_bf16 v[18:21], v[166:169], v[190:193], v[18:21]
	v_mfma_f32_16x16x32_bf16 v[6:9], v[158:161], v[198:201], v[6:9]
	v_mfma_f32_16x16x32_bf16 v[2:5], v[166:169], v[198:201], v[2:5]
	s_setprio 0
	s_barrier
	s_add_i32 s47, 0, 0x18000
	s_add_i32 s50, 0, 0x1c000
	ds_read_b128 v[138:141], v0 offset:32768
	ds_read_b128 v[142:145], v0 offset:33792
	ds_read_b128 v[146:149], v0 offset:34816
	ds_read_b128 v[150:153], v0 offset:35840
	ds_read_b128 v[154:157], v0 offset:49152
	ds_read_b128 v[158:161], v0 offset:50176
	ds_read_b128 v[162:165], v0 offset:51200
	ds_read_b128 v[166:169], v0 offset:52224
	s_add_u32 s48, s10, 0x40000
	s_mov_b32 m0, s25
	ds_read_b128 v[170:173], v137 offset:32768
	ds_read_b128 v[174:177], v137 offset:33792
	ds_read_b128 v[178:181], v137 offset:34816
	ds_read_b128 v[182:185], v137 offset:35840
	ds_read_b128 v[186:189], v137 offset:36864
	ds_read_b128 v[190:193], v137 offset:37888
	ds_read_b128 v[194:197], v137 offset:38912
	ds_read_b128 v[198:201], v137 offset:39936
	s_addc_u32 s49, s11, 0
	s_nop 0
	global_load_lds_dwordx4 v130, s[48:49]
	s_mov_b32 m0, s26
	s_nop 0
	global_load_lds_dwordx4 v132, s[48:49]
	s_waitcnt vmcnt(8)
	s_waitcnt lgkmcnt(0)
	s_barrier
	s_setprio 1
	s_waitcnt lgkmcnt(0)
	v_mfma_f32_16x16x32_bf16 v[126:129], v[138:141], v[170:173], v[126:129]
	v_mfma_f32_16x16x32_bf16 v[122:125], v[146:149], v[170:173], v[122:125]
	v_mfma_f32_16x16x32_bf16 v[110:113], v[138:141], v[178:181], v[110:113]
	v_mfma_f32_16x16x32_bf16 v[106:109], v[146:149], v[178:181], v[106:109]
	v_mfma_f32_16x16x32_bf16 v[94:97], v[138:141], v[186:189], v[94:97]
	v_mfma_f32_16x16x32_bf16 v[90:93], v[146:149], v[186:189], v[90:93]
	v_mfma_f32_16x16x32_bf16 v[78:81], v[138:141], v[194:197], v[78:81]
	v_mfma_f32_16x16x32_bf16 v[74:77], v[146:149], v[194:197], v[74:77]
	s_setprio 0
	s_setprio 1
	v_mfma_f32_16x16x32_bf16 v[126:129], v[142:145], v[174:177], v[126:129]
	v_mfma_f32_16x16x32_bf16 v[122:125], v[150:153], v[174:177], v[122:125]
	v_mfma_f32_16x16x32_bf16 v[110:113], v[142:145], v[182:185], v[110:113]
	v_mfma_f32_16x16x32_bf16 v[106:109], v[150:153], v[182:185], v[106:109]
	v_mfma_f32_16x16x32_bf16 v[94:97], v[142:145], v[190:193], v[94:97]
	v_mfma_f32_16x16x32_bf16 v[90:93], v[150:153], v[190:193], v[90:93]
	v_mfma_f32_16x16x32_bf16 v[78:81], v[142:145], v[198:201], v[78:81]
	v_mfma_f32_16x16x32_bf16 v[74:77], v[150:153], v[198:201], v[74:77]
	s_setprio 0
	s_setprio 1
	v_mfma_f32_16x16x32_bf16 v[118:121], v[154:157], v[170:173], v[118:121]
	v_mfma_f32_16x16x32_bf16 v[114:117], v[162:165], v[170:173], v[114:117]
	v_mfma_f32_16x16x32_bf16 v[102:105], v[154:157], v[178:181], v[102:105]
	v_mfma_f32_16x16x32_bf16 v[98:101], v[162:165], v[178:181], v[98:101]
	v_mfma_f32_16x16x32_bf16 v[86:89], v[154:157], v[186:189], v[86:89]
	v_mfma_f32_16x16x32_bf16 v[82:85], v[162:165], v[186:189], v[82:85]
	v_mfma_f32_16x16x32_bf16 v[70:73], v[154:157], v[194:197], v[70:73]
	v_mfma_f32_16x16x32_bf16 v[66:69], v[162:165], v[194:197], v[66:69]
	s_setprio 0
	s_setprio 1
	v_mfma_f32_16x16x32_bf16 v[118:121], v[158:161], v[174:177], v[118:121]
	v_mfma_f32_16x16x32_bf16 v[114:117], v[166:169], v[174:177], v[114:117]
	v_mfma_f32_16x16x32_bf16 v[102:105], v[158:161], v[182:185], v[102:105]
	v_mfma_f32_16x16x32_bf16 v[98:101], v[166:169], v[182:185], v[98:101]
	v_mfma_f32_16x16x32_bf16 v[86:89], v[158:161], v[190:193], v[86:89]
	v_mfma_f32_16x16x32_bf16 v[82:85], v[166:169], v[190:193], v[82:85]
	v_mfma_f32_16x16x32_bf16 v[70:73], v[158:161], v[198:201], v[70:73]
	v_mfma_f32_16x16x32_bf16 v[66:69], v[166:169], v[198:201], v[66:69]
	s_setprio 0
	s_barrier
	ds_read_b128 v[170:173], v137 offset:49152
	ds_read_b128 v[174:177], v137 offset:50176
	ds_read_b128 v[178:181], v137 offset:51200
	ds_read_b128 v[182:185], v137 offset:52224
	ds_read_b128 v[186:189], v137 offset:53248
	ds_read_b128 v[190:193], v137 offset:54272
	ds_read_b128 v[194:197], v137 offset:55296
	ds_read_b128 v[198:201], v137 offset:56320
	s_add_i32 s47, s47, s22
	s_add_u32 s100, s12, s38
	s_addc_u32 s101, s13, s39
	s_mov_b32 m0, s47
	s_nop 0
	global_load_lds_dwordx4 v134, s[100:101]
	s_add_i32 m0, s47, 0x2000
	s_nop 0
	s_add_u32 s12, s12, 0x40080
	s_addc_u32 s13, s13, 0
	s_add_i32 s47, s50, s22
	global_load_lds_dwordx4 v135, s[100:101]
	s_mov_b32 m0, s47
	s_nop 0
	global_load_lds_dwordx4 v134, s[12:13]
	s_add_i32 m0, s47, 0x2000
	s_nop 0
	global_load_lds_dwordx4 v135, s[12:13]
	s_mov_b32 m0, s42
	s_add_u32 s100, s10, s38
	s_addc_u32 s101, s11, s39
	v_mov_b32_e32 v0, v132
	global_load_lds_dwordx4 v130, s[100:101]
	s_mov_b32 m0, s43
	s_nop 0
	global_load_lds_dwordx4 v132, s[100:101]
	s_waitcnt vmcnt(8)
	s_waitcnt lgkmcnt(0)
	s_barrier
	s_setprio 1
	s_waitcnt lgkmcnt(0)
	v_mfma_f32_16x16x32_bf16 v[62:65], v[138:141], v[170:173], v[62:65]
	v_mfma_f32_16x16x32_bf16 v[58:61], v[146:149], v[170:173], v[58:61]
	v_mfma_f32_16x16x32_bf16 v[46:49], v[138:141], v[178:181], v[46:49]
	v_mfma_f32_16x16x32_bf16 v[42:45], v[146:149], v[178:181], v[42:45]
	v_mfma_f32_16x16x32_bf16 v[30:33], v[138:141], v[186:189], v[30:33]
	v_mfma_f32_16x16x32_bf16 v[26:29], v[146:149], v[186:189], v[26:29]
	v_mfma_f32_16x16x32_bf16 v[14:17], v[138:141], v[194:197], v[14:17]
	v_mfma_f32_16x16x32_bf16 v[10:13], v[146:149], v[194:197], v[10:13]
	s_setprio 0
	s_setprio 1
	v_mfma_f32_16x16x32_bf16 v[62:65], v[142:145], v[174:177], v[62:65]
	v_mfma_f32_16x16x32_bf16 v[58:61], v[150:153], v[174:177], v[58:61]
	v_mfma_f32_16x16x32_bf16 v[46:49], v[142:145], v[182:185], v[46:49]
	v_mfma_f32_16x16x32_bf16 v[42:45], v[150:153], v[182:185], v[42:45]
	v_mfma_f32_16x16x32_bf16 v[30:33], v[142:145], v[190:193], v[30:33]
	v_mfma_f32_16x16x32_bf16 v[26:29], v[150:153], v[190:193], v[26:29]
	v_mfma_f32_16x16x32_bf16 v[14:17], v[142:145], v[198:201], v[14:17]
	v_mfma_f32_16x16x32_bf16 v[10:13], v[150:153], v[198:201], v[10:13]
	s_setprio 0
	s_setprio 1
	v_mfma_f32_16x16x32_bf16 v[54:57], v[154:157], v[170:173], v[54:57]
	v_mfma_f32_16x16x32_bf16 v[50:53], v[162:165], v[170:173], v[50:53]
	v_mfma_f32_16x16x32_bf16 v[38:41], v[154:157], v[178:181], v[38:41]
	v_mfma_f32_16x16x32_bf16 v[34:37], v[162:165], v[178:181], v[34:37]
	v_mfma_f32_16x16x32_bf16 v[22:25], v[154:157], v[186:189], v[22:25]
	v_mfma_f32_16x16x32_bf16 v[18:21], v[162:165], v[186:189], v[18:21]
	v_mfma_f32_16x16x32_bf16 v[6:9], v[154:157], v[194:197], v[6:9]
	v_mfma_f32_16x16x32_bf16 v[2:5], v[162:165], v[194:197], v[2:5]
	s_setprio 0
	s_setprio 1
	v_mfma_f32_16x16x32_bf16 v[54:57], v[158:161], v[174:177], v[54:57]
	v_mfma_f32_16x16x32_bf16 v[50:53], v[166:169], v[174:177], v[50:53]
	v_mfma_f32_16x16x32_bf16 v[38:41], v[158:161], v[182:185], v[38:41]
	v_mfma_f32_16x16x32_bf16 v[34:37], v[166:169], v[182:185], v[34:37]
	v_mfma_f32_16x16x32_bf16 v[22:25], v[158:161], v[190:193], v[22:25]
	v_mfma_f32_16x16x32_bf16 v[18:21], v[166:169], v[190:193], v[18:21]
	v_mfma_f32_16x16x32_bf16 v[6:9], v[158:161], v[198:201], v[6:9]
	v_mfma_f32_16x16x32_bf16 v[2:5], v[166:169], v[198:201], v[2:5]
	s_setprio 0
	s_barrier
	s_add_i32 s46, s46, 2
	s_add_u32 s2, s2, 0x100
	s_addc_u32 s3, s3, 0
	s_cmp_gt_u32 s46, 13
	s_cbranch_scc0 .LBB0_1681
	s_cmpk_lt_u32 s17, 0x100
	s_cbranch_scc0 .LBB0_1684
	s_barrier

.LBB0_1807:
	s_add_u32 s68, s4, s14
	s_addc_u32 s69, s5, s15
	s_add_u32 s16, s68, 0x100
	s_addc_u32 s17, s69, 0
	s_add_u32 s22, s50, s14
	s_addc_u32 s23, s51, s15
	s_add_i32 s67, 0, 0x10000
	s_cmp_eq_u32 s66, 12
	s_cselect_b32 s17, s5, s17
	s_cselect_b32 s16, s4, s16
	v_add_u32_e32 v0, s67, v126
	s_cselect_b32 s23, s13, s23
	s_cselect_b32 s22, s12, s22
	s_add_i32 s70, 0, 0x14000
	ds_read_b128 v[128:131], v0
	ds_read_b128 v[142:145], v0 offset:1024
	ds_read_b128 v[146:149], v0 offset:2048
	ds_read_b128 v[150:153], v0 offset:3072
	ds_read_b128 v[154:157], v0 offset:16384
	ds_read_b128 v[160:163], v0 offset:17408
	ds_read_b128 v[164:167], v0 offset:18432
	ds_read_b128 v[168:171], v0 offset:19456
	ds_read_b128 v[172:175], v127
	ds_read_b128 v[176:179], v127 offset:1024
	ds_read_b128 v[180:183], v127 offset:2048
	ds_read_b128 v[184:187], v127 offset:3072
	ds_read_b128 v[188:191], v127 offset:4096
	ds_read_b128 v[192:195], v127 offset:5120
	ds_read_b128 v[196:199], v127 offset:6144
	ds_read_b128 v[200:203], v127 offset:7168
	s_add_i32 m0, s43, 0xc000
	s_add_u32 s100, s68, s56
	s_addc_u32 s101, s69, s57
	global_load_lds_dwordx4 v122, s[100:101]
	s_add_i32 m0, s43, 0xe000
	s_nop 0
	global_load_lds_dwordx4 v123, s[100:101]
	s_waitcnt vmcnt(8)
	s_waitcnt lgkmcnt(0)
	s_barrier
	s_setprio 1
	s_waitcnt lgkmcnt(0)
	v_mfma_f32_16x16x32_bf16 v[138:141], v[128:131], v[172:175], v[138:141]
	v_mfma_f32_16x16x32_bf16 v[132:135], v[146:149], v[172:175], v[134:137]
	v_mfma_f32_16x16x32_bf16 v[110:113], v[128:131], v[180:183], v[110:113]
	v_mfma_f32_16x16x32_bf16 v[106:109], v[146:149], v[180:183], v[106:109]
	v_mfma_f32_16x16x32_bf16 v[94:97], v[128:131], v[188:191], v[94:97]
	v_mfma_f32_16x16x32_bf16 v[90:93], v[146:149], v[188:191], v[90:93]
	v_mfma_f32_16x16x32_bf16 v[78:81], v[128:131], v[196:199], v[78:81]
	v_mfma_f32_16x16x32_bf16 v[74:77], v[146:149], v[196:199], v[74:77]
	s_setprio 0
	s_setprio 1
	v_mfma_f32_16x16x32_bf16 v[138:141], v[142:145], v[176:179], v[138:141]
	v_mfma_f32_16x16x32_bf16 v[132:135], v[150:153], v[176:179], v[132:135]
	v_mfma_f32_16x16x32_bf16 v[110:113], v[142:145], v[184:187], v[110:113]
	v_mfma_f32_16x16x32_bf16 v[106:109], v[150:153], v[184:187], v[106:109]
	v_mfma_f32_16x16x32_bf16 v[94:97], v[142:145], v[192:195], v[94:97]
	v_mfma_f32_16x16x32_bf16 v[90:93], v[150:153], v[192:195], v[90:93]
	v_mfma_f32_16x16x32_bf16 v[78:81], v[142:145], v[200:203], v[78:81]
	v_mfma_f32_16x16x32_bf16 v[74:77], v[150:153], v[200:203], v[74:77]
	s_setprio 0
	s_setprio 1
	v_mfma_f32_16x16x32_bf16 v[118:121], v[154:157], v[172:175], v[118:121]
	v_mfma_f32_16x16x32_bf16 v[114:117], v[164:167], v[172:175], v[114:117]
	v_mfma_f32_16x16x32_bf16 v[102:105], v[154:157], v[180:183], v[102:105]
	v_mfma_f32_16x16x32_bf16 v[98:101], v[164:167], v[180:183], v[98:101]
	v_mfma_f32_16x16x32_bf16 v[86:89], v[154:157], v[188:191], v[86:89]
	v_mfma_f32_16x16x32_bf16 v[82:85], v[164:167], v[188:191], v[82:85]
	v_mfma_f32_16x16x32_bf16 v[70:73], v[154:157], v[196:199], v[70:73]
	v_mfma_f32_16x16x32_bf16 v[66:69], v[164:167], v[196:199], v[66:69]
	s_setprio 0
	s_setprio 1
	v_mfma_f32_16x16x32_bf16 v[118:121], v[160:163], v[176:179], v[118:121]
	v_mfma_f32_16x16x32_bf16 v[114:117], v[168:171], v[176:179], v[114:117]
	v_mfma_f32_16x16x32_bf16 v[102:105], v[160:163], v[184:187], v[102:105]
	v_mfma_f32_16x16x32_bf16 v[98:101], v[168:171], v[184:187], v[98:101]
	v_mfma_f32_16x16x32_bf16 v[86:89], v[160:163], v[192:195], v[86:89]
	v_mfma_f32_16x16x32_bf16 v[82:85], v[168:171], v[192:195], v[82:85]
	v_mfma_f32_16x16x32_bf16 v[70:73], v[160:163], v[200:203], v[70:73]
	v_mfma_f32_16x16x32_bf16 v[66:69], v[168:171], v[200:203], v[66:69]
	s_setprio 0
	s_barrier
	s_add_i32 s67, s67, s42
	ds_read_b128 v[172:175], v127 offset:16384
	ds_read_b128 v[176:179], v127 offset:17408
	ds_read_b128 v[180:183], v127 offset:18432
	ds_read_b128 v[184:187], v127 offset:19456
	ds_read_b128 v[188:191], v127 offset:20480
	ds_read_b128 v[192:195], v127 offset:21504
	ds_read_b128 v[196:199], v127 offset:22528
	ds_read_b128 v[200:203], v127 offset:23552
	s_mov_b32 m0, s67
	s_nop 0
	global_load_lds_dwordx4 v124, s[22:23]
	s_add_i32 m0, s67, 0x2000
	s_add_u32 s68, s22, 0x40000
	global_load_lds_dwordx4 v125, s[22:23]
	s_addc_u32 s69, s23, 0
	s_add_i32 s67, s70, s42
	s_mov_b32 m0, s67
	s_nop 0
	global_load_lds_dwordx4 v124, s[68:69]
	s_add_i32 m0, s67, 0x2000
	s_nop 0
	global_load_lds_dwordx4 v125, s[68:69]
	s_mov_b32 m0, s43
	s_nop 0
	global_load_lds_dwordx4 v122, s[16:17]
	s_mov_b32 m0, s46
	s_nop 0
	global_load_lds_dwordx4 v123, s[16:17]
	s_waitcnt vmcnt(8)
	s_waitcnt lgkmcnt(0)
	s_barrier
	s_setprio 1
	s_waitcnt lgkmcnt(0)
	v_mfma_f32_16x16x32_bf16 v[62:65], v[128:131], v[172:175], v[62:65]
	v_mfma_f32_16x16x32_bf16 v[58:61], v[146:149], v[172:175], v[58:61]
	v_mfma_f32_16x16x32_bf16 v[46:49], v[128:131], v[180:183], v[46:49]
	v_mfma_f32_16x16x32_bf16 v[42:45], v[146:149], v[180:183], v[42:45]
	v_mfma_f32_16x16x32_bf16 v[30:33], v[128:131], v[188:191], v[30:33]
	v_mfma_f32_16x16x32_bf16 v[26:29], v[146:149], v[188:191], v[26:29]
	v_mfma_f32_16x16x32_bf16 v[14:17], v[128:131], v[196:199], v[14:17]
	v_mfma_f32_16x16x32_bf16 v[10:13], v[146:149], v[196:199], v[10:13]
	s_setprio 0
	s_setprio 1
	v_mfma_f32_16x16x32_bf16 v[62:65], v[142:145], v[176:179], v[62:65]
	v_mfma_f32_16x16x32_bf16 v[58:61], v[150:153], v[176:179], v[58:61]
	v_mfma_f32_16x16x32_bf16 v[46:49], v[142:145], v[184:187], v[46:49]
	v_mfma_f32_16x16x32_bf16 v[42:45], v[150:153], v[184:187], v[42:45]
	v_mfma_f32_16x16x32_bf16 v[30:33], v[142:145], v[192:195], v[30:33]
	v_mfma_f32_16x16x32_bf16 v[26:29], v[150:153], v[192:195], v[26:29]
	v_mfma_f32_16x16x32_bf16 v[14:17], v[142:145], v[200:203], v[14:17]
	v_mfma_f32_16x16x32_bf16 v[10:13], v[150:153], v[200:203], v[10:13]
	s_setprio 0
	s_setprio 1
	v_mfma_f32_16x16x32_bf16 v[54:57], v[154:157], v[172:175], v[54:57]
	v_mfma_f32_16x16x32_bf16 v[50:53], v[164:167], v[172:175], v[50:53]
	v_mfma_f32_16x16x32_bf16 v[38:41], v[154:157], v[180:183], v[38:41]
	v_mfma_f32_16x16x32_bf16 v[34:37], v[164:167], v[180:183], v[34:37]
	v_mfma_f32_16x16x32_bf16 v[22:25], v[154:157], v[188:191], v[22:25]
	v_mfma_f32_16x16x32_bf16 v[18:21], v[164:167], v[188:191], v[18:21]
	v_mfma_f32_16x16x32_bf16 v[6:9], v[154:157], v[196:199], v[6:9]
	v_mfma_f32_16x16x32_bf16 v[2:5], v[164:167], v[196:199], v[2:5]
	s_setprio 0
	s_setprio 1
	v_mfma_f32_16x16x32_bf16 v[54:57], v[160:163], v[176:179], v[54:57]
	v_mfma_f32_16x16x32_bf16 v[50:53], v[168:171], v[176:179], v[50:53]
	v_mfma_f32_16x16x32_bf16 v[38:41], v[160:163], v[184:187], v[38:41]
	v_mfma_f32_16x16x32_bf16 v[34:37], v[168:171], v[184:187], v[34:37]
	v_mfma_f32_16x16x32_bf16 v[22:25], v[160:163], v[192:195], v[22:25]
	v_mfma_f32_16x16x32_bf16 v[18:21], v[168:171], v[192:195], v[18:21]
	v_mfma_f32_16x16x32_bf16 v[6:9], v[160:163], v[200:203], v[6:9]
	v_mfma_f32_16x16x32_bf16 v[2:5], v[168:171], v[200:203], v[2:5]
	s_setprio 0
	s_barrier
	s_add_i32 s67, 0, 0x18000
	s_add_i32 s70, 0, 0x1c000
	ds_read_b128 v[128:131], v0 offset:32768
	ds_read_b128 v[142:145], v0 offset:33792
	ds_read_b128 v[146:149], v0 offset:34816
	ds_read_b128 v[150:153], v0 offset:35840
	ds_read_b128 v[154:157], v0 offset:49152
	ds_read_b128 v[160:163], v0 offset:50176
	ds_read_b128 v[164:167], v0 offset:51200
	ds_read_b128 v[168:171], v0 offset:52224
	s_add_u32 s68, s16, 0x40000
	s_mov_b32 m0, s47
	ds_read_b128 v[172:175], v127 offset:32768
	ds_read_b128 v[176:179], v127 offset:33792
	ds_read_b128 v[180:183], v127 offset:34816
	ds_read_b128 v[184:187], v127 offset:35840
	ds_read_b128 v[188:191], v127 offset:36864
	ds_read_b128 v[192:195], v127 offset:37888
	ds_read_b128 v[196:199], v127 offset:38912
	ds_read_b128 v[200:203], v127 offset:39936
	s_addc_u32 s69, s17, 0
	s_nop 0
	global_load_lds_dwordx4 v122, s[68:69]
	s_mov_b32 m0, s48
	s_nop 0
	global_load_lds_dwordx4 v123, s[68:69]
	s_waitcnt vmcnt(8)
	s_waitcnt lgkmcnt(0)
	s_barrier
	s_setprio 1
	s_waitcnt lgkmcnt(0)
	v_mfma_f32_16x16x32_bf16 v[136:139], v[128:131], v[172:175], v[138:141]
	v_mfma_f32_16x16x32_bf16 v[132:135], v[146:149], v[172:175], v[132:135]
	v_mfma_f32_16x16x32_bf16 v[110:113], v[128:131], v[180:183], v[110:113]
	v_mfma_f32_16x16x32_bf16 v[106:109], v[146:149], v[180:183], v[106:109]
	v_mfma_f32_16x16x32_bf16 v[94:97], v[128:131], v[188:191], v[94:97]
	v_mfma_f32_16x16x32_bf16 v[90:93], v[146:149], v[188:191], v[90:93]
	v_mfma_f32_16x16x32_bf16 v[78:81], v[128:131], v[196:199], v[78:81]
	v_mfma_f32_16x16x32_bf16 v[74:77], v[146:149], v[196:199], v[74:77]
	s_setprio 0
	s_setprio 1
	v_mfma_f32_16x16x32_bf16 v[138:141], v[142:145], v[176:179], v[136:139]
	v_mfma_f32_16x16x32_bf16 v[134:137], v[150:153], v[176:179], v[132:135]
	v_mfma_f32_16x16x32_bf16 v[110:113], v[142:145], v[184:187], v[110:113]
	v_mfma_f32_16x16x32_bf16 v[106:109], v[150:153], v[184:187], v[106:109]
	v_mfma_f32_16x16x32_bf16 v[94:97], v[142:145], v[192:195], v[94:97]
	v_mfma_f32_16x16x32_bf16 v[90:93], v[150:153], v[192:195], v[90:93]
	v_mfma_f32_16x16x32_bf16 v[78:81], v[142:145], v[200:203], v[78:81]
	v_mfma_f32_16x16x32_bf16 v[74:77], v[150:153], v[200:203], v[74:77]
	s_setprio 0
	s_setprio 1
	v_mfma_f32_16x16x32_bf16 v[118:121], v[154:157], v[172:175], v[118:121]
	v_mfma_f32_16x16x32_bf16 v[114:117], v[164:167], v[172:175], v[114:117]
	v_mfma_f32_16x16x32_bf16 v[102:105], v[154:157], v[180:183], v[102:105]
	v_mfma_f32_16x16x32_bf16 v[98:101], v[164:167], v[180:183], v[98:101]
	v_mfma_f32_16x16x32_bf16 v[86:89], v[154:157], v[188:191], v[86:89]
	v_mfma_f32_16x16x32_bf16 v[82:85], v[164:167], v[188:191], v[82:85]
	v_mfma_f32_16x16x32_bf16 v[70:73], v[154:157], v[196:199], v[70:73]
	v_mfma_f32_16x16x32_bf16 v[66:69], v[164:167], v[196:199], v[66:69]
	s_setprio 0
	s_setprio 1
	v_mfma_f32_16x16x32_bf16 v[118:121], v[160:163], v[176:179], v[118:121]
	v_mfma_f32_16x16x32_bf16 v[114:117], v[168:171], v[176:179], v[114:117]
	v_mfma_f32_16x16x32_bf16 v[102:105], v[160:163], v[184:187], v[102:105]
	v_mfma_f32_16x16x32_bf16 v[98:101], v[168:171], v[184:187], v[98:101]
	v_mfma_f32_16x16x32_bf16 v[86:89], v[160:163], v[192:195], v[86:89]
	v_mfma_f32_16x16x32_bf16 v[82:85], v[168:171], v[192:195], v[82:85]
	v_mfma_f32_16x16x32_bf16 v[70:73], v[160:163], v[200:203], v[70:73]
	v_mfma_f32_16x16x32_bf16 v[66:69], v[168:171], v[200:203], v[66:69]
	s_setprio 0
	s_barrier
	ds_read_b128 v[172:175], v127 offset:49152
	ds_read_b128 v[176:179], v127 offset:50176
	ds_read_b128 v[180:183], v127 offset:51200
	ds_read_b128 v[184:187], v127 offset:52224
	ds_read_b128 v[188:191], v127 offset:53248
	ds_read_b128 v[192:195], v127 offset:54272
	ds_read_b128 v[196:199], v127 offset:55296
	ds_read_b128 v[200:203], v127 offset:56320
	s_add_i32 s67, s67, s42
	s_add_u32 s100, s22, s38
	s_addc_u32 s101, s23, s39
	s_mov_b32 m0, s67
	s_nop 0
	global_load_lds_dwordx4 v124, s[100:101]
	s_add_i32 m0, s67, 0x2000
	s_nop 0
	s_add_u32 s22, s22, 0x40080
	s_addc_u32 s23, s23, 0
	s_add_i32 s67, s70, s42
	global_load_lds_dwordx4 v125, s[100:101]
	s_mov_b32 m0, s67
	s_nop 0
	global_load_lds_dwordx4 v124, s[22:23]
	s_add_i32 m0, s67, 0x2000
	s_nop 0
	global_load_lds_dwordx4 v125, s[22:23]
	s_mov_b32 m0, s64
	s_add_u32 s100, s16, s38
	s_addc_u32 s101, s17, s39
	v_mov_b32_e32 v0, v123
	global_load_lds_dwordx4 v122, s[100:101]
	s_mov_b32 m0, s65
	s_nop 0
	global_load_lds_dwordx4 v123, s[100:101]
	s_waitcnt vmcnt(8)
	s_waitcnt lgkmcnt(0)
	s_barrier
	s_setprio 1
	s_waitcnt lgkmcnt(0)
	v_mfma_f32_16x16x32_bf16 v[62:65], v[128:131], v[172:175], v[62:65]
	v_mfma_f32_16x16x32_bf16 v[58:61], v[146:149], v[172:175], v[58:61]
	v_mfma_f32_16x16x32_bf16 v[46:49], v[128:131], v[180:183], v[46:49]
	v_mfma_f32_16x16x32_bf16 v[42:45], v[146:149], v[180:183], v[42:45]
	v_mfma_f32_16x16x32_bf16 v[30:33], v[128:131], v[188:191], v[30:33]
	v_mfma_f32_16x16x32_bf16 v[26:29], v[146:149], v[188:191], v[26:29]
	v_mfma_f32_16x16x32_bf16 v[14:17], v[128:131], v[196:199], v[14:17]
	v_mfma_f32_16x16x32_bf16 v[10:13], v[146:149], v[196:199], v[10:13]
	s_setprio 0
	s_setprio 1
	v_mfma_f32_16x16x32_bf16 v[62:65], v[142:145], v[176:179], v[62:65]
	v_mfma_f32_16x16x32_bf16 v[58:61], v[150:153], v[176:179], v[58:61]
	v_mfma_f32_16x16x32_bf16 v[46:49], v[142:145], v[184:187], v[46:49]
	v_mfma_f32_16x16x32_bf16 v[42:45], v[150:153], v[184:187], v[42:45]
	v_mfma_f32_16x16x32_bf16 v[30:33], v[142:145], v[192:195], v[30:33]
	v_mfma_f32_16x16x32_bf16 v[26:29], v[150:153], v[192:195], v[26:29]
	v_mfma_f32_16x16x32_bf16 v[14:17], v[142:145], v[200:203], v[14:17]
	v_mfma_f32_16x16x32_bf16 v[10:13], v[150:153], v[200:203], v[10:13]
	s_setprio 0
	s_setprio 1
	v_mfma_f32_16x16x32_bf16 v[54:57], v[154:157], v[172:175], v[54:57]
	v_mfma_f32_16x16x32_bf16 v[50:53], v[164:167], v[172:175], v[50:53]
	v_mfma_f32_16x16x32_bf16 v[38:41], v[154:157], v[180:183], v[38:41]
	v_mfma_f32_16x16x32_bf16 v[34:37], v[164:167], v[180:183], v[34:37]
	v_mfma_f32_16x16x32_bf16 v[22:25], v[154:157], v[188:191], v[22:25]
	v_mfma_f32_16x16x32_bf16 v[18:21], v[164:167], v[188:191], v[18:21]
	v_mfma_f32_16x16x32_bf16 v[6:9], v[154:157], v[196:199], v[6:9]
	v_mfma_f32_16x16x32_bf16 v[2:5], v[164:167], v[196:199], v[2:5]
	s_setprio 0
	s_setprio 1
	v_mfma_f32_16x16x32_bf16 v[54:57], v[160:163], v[176:179], v[54:57]
	v_mfma_f32_16x16x32_bf16 v[50:53], v[168:171], v[176:179], v[50:53]
	v_mfma_f32_16x16x32_bf16 v[38:41], v[160:163], v[184:187], v[38:41]
	v_mfma_f32_16x16x32_bf16 v[34:37], v[168:171], v[184:187], v[34:37]
	v_mfma_f32_16x16x32_bf16 v[22:25], v[160:163], v[192:195], v[22:25]
	v_mfma_f32_16x16x32_bf16 v[18:21], v[168:171], v[192:195], v[18:21]
	v_mfma_f32_16x16x32_bf16 v[6:9], v[160:163], v[200:203], v[6:9]
	v_mfma_f32_16x16x32_bf16 v[2:5], v[168:171], v[200:203], v[2:5]
	s_setprio 0
	s_barrier
	s_add_i32 s66, s66, 2
	s_add_u32 s14, s14, 0x100
	s_addc_u32 s15, s15, 0
	s_cmp_gt_u32 s66, 13
	s_cbranch_scc0 .LBB0_1807
	s_cmpk_lt_u32 s26, 0x100
	s_cbranch_scc0 .LBB0_1810
	s_barrier

.LBB0_1886:
	s_add_u32 s6, s4, 0xfffc0080
	s_addc_u32 s7, s5, -1
	s_add_i32 s47, 0, 0x10000
	s_cmp_eq_u32 s46, 12
	s_cselect_b32 s7, s3, s7
	s_cselect_b32 s6, s2, s6
	v_add_u32_e32 v0, s47, v127
	s_cselect_b32 s11, s40, s43
	s_cselect_b32 s10, s26, s37
	s_add_i32 s50, 0, 0x14000
	ds_read_b128 v[130:133], v0
	ds_read_b128 v[134:137], v0 offset:1024
	ds_read_b128 v[138:141], v0 offset:2048
	ds_read_b128 v[142:145], v0 offset:3072
	ds_read_b128 v[146:149], v0 offset:16384
	ds_read_b128 v[158:161], v0 offset:17408
	ds_read_b128 v[162:165], v0 offset:18432
	ds_read_b128 v[166:169], v0 offset:19456
	ds_read_b128 v[170:173], v128
	ds_read_b128 v[174:177], v128 offset:1024
	ds_read_b128 v[178:181], v128 offset:2048
	ds_read_b128 v[182:185], v128 offset:3072
	ds_read_b128 v[186:189], v128 offset:4096
	ds_read_b128 v[190:193], v128 offset:5120
	ds_read_b128 v[194:197], v128 offset:6144
	ds_read_b128 v[198:201], v128 offset:7168
	s_add_i32 m0, s17, 0xc000
	s_nop 0
	global_load_lds_dwordx4 v122, s[4:5]
	s_add_i32 m0, s17, 0xe000
	s_nop 0
	global_load_lds_dwordx4 v123, s[4:5]
	s_waitcnt vmcnt(8)
	s_waitcnt lgkmcnt(0)
	s_barrier
	s_setprio 1
	s_waitcnt lgkmcnt(0)
	v_mfma_f32_16x16x32_bf16 v[154:157], v[130:133], v[170:173], v[154:157]
	v_mfma_f32_16x16x32_bf16 v[150:153], v[138:141], v[170:173], v[150:153]
	v_mfma_f32_16x16x32_bf16 v[110:113], v[130:133], v[178:181], v[110:113]
	v_mfma_f32_16x16x32_bf16 v[106:109], v[138:141], v[178:181], v[106:109]
	v_mfma_f32_16x16x32_bf16 v[94:97], v[130:133], v[186:189], v[94:97]
	v_mfma_f32_16x16x32_bf16 v[90:93], v[138:141], v[186:189], v[90:93]
	v_mfma_f32_16x16x32_bf16 v[78:81], v[130:133], v[194:197], v[78:81]
	v_mfma_f32_16x16x32_bf16 v[74:77], v[138:141], v[194:197], v[74:77]
	s_setprio 0
	s_setprio 1
	v_mfma_f32_16x16x32_bf16 v[154:157], v[134:137], v[174:177], v[154:157]
	v_mfma_f32_16x16x32_bf16 v[150:153], v[142:145], v[174:177], v[150:153]
	v_mfma_f32_16x16x32_bf16 v[110:113], v[134:137], v[182:185], v[110:113]
	v_mfma_f32_16x16x32_bf16 v[106:109], v[142:145], v[182:185], v[106:109]
	v_mfma_f32_16x16x32_bf16 v[94:97], v[134:137], v[190:193], v[94:97]
	v_mfma_f32_16x16x32_bf16 v[90:93], v[142:145], v[190:193], v[90:93]
	v_mfma_f32_16x16x32_bf16 v[78:81], v[134:137], v[198:201], v[78:81]
	v_mfma_f32_16x16x32_bf16 v[74:77], v[142:145], v[198:201], v[74:77]
	s_setprio 0
	s_setprio 1
	v_mfma_f32_16x16x32_bf16 v[118:121], v[146:149], v[170:173], v[118:121]
	v_mfma_f32_16x16x32_bf16 v[114:117], v[162:165], v[170:173], v[114:117]
	v_mfma_f32_16x16x32_bf16 v[102:105], v[146:149], v[178:181], v[102:105]
	v_mfma_f32_16x16x32_bf16 v[98:101], v[162:165], v[178:181], v[98:101]
	v_mfma_f32_16x16x32_bf16 v[86:89], v[146:149], v[186:189], v[86:89]
	v_mfma_f32_16x16x32_bf16 v[82:85], v[162:165], v[186:189], v[82:85]
	v_mfma_f32_16x16x32_bf16 v[70:73], v[146:149], v[194:197], v[70:73]
	v_mfma_f32_16x16x32_bf16 v[66:69], v[162:165], v[194:197], v[66:69]
	s_setprio 0
	s_setprio 1
	v_mfma_f32_16x16x32_bf16 v[118:121], v[158:161], v[174:177], v[118:121]
	v_mfma_f32_16x16x32_bf16 v[114:117], v[166:169], v[174:177], v[114:117]
	v_mfma_f32_16x16x32_bf16 v[102:105], v[158:161], v[182:185], v[102:105]
	v_mfma_f32_16x16x32_bf16 v[98:101], v[166:169], v[182:185], v[98:101]
	v_mfma_f32_16x16x32_bf16 v[86:89], v[158:161], v[190:193], v[86:89]
	v_mfma_f32_16x16x32_bf16 v[82:85], v[166:169], v[190:193], v[82:85]
	v_mfma_f32_16x16x32_bf16 v[70:73], v[158:161], v[198:201], v[70:73]
	v_mfma_f32_16x16x32_bf16 v[66:69], v[166:169], v[198:201], v[66:69]
	s_setprio 0
	s_barrier
	s_add_i32 s47, s47, s16
	ds_read_b128 v[170:173], v128 offset:16384
	ds_read_b128 v[174:177], v128 offset:17408
	ds_read_b128 v[178:181], v128 offset:18432
	ds_read_b128 v[182:185], v128 offset:19456
	ds_read_b128 v[186:189], v128 offset:20480
	ds_read_b128 v[190:193], v128 offset:21504
	ds_read_b128 v[194:197], v128 offset:22528
	ds_read_b128 v[198:201], v128 offset:23552
	s_mov_b32 m0, s47
	s_nop 0
	global_load_lds_dwordx4 v125, s[10:11]
	s_add_i32 m0, s47, 0x2000
	s_add_u32 s48, s10, 0x40000
	global_load_lds_dwordx4 v126, s[10:11]
	s_addc_u32 s49, s11, 0
	s_add_i32 s47, s50, s16
	s_mov_b32 m0, s47
	s_nop 0
	global_load_lds_dwordx4 v125, s[48:49]
	s_add_i32 m0, s47, 0x2000
	s_nop 0
	global_load_lds_dwordx4 v126, s[48:49]
	s_mov_b32 m0, s17
	s_nop 0
	global_load_lds_dwordx4 v122, s[6:7]
	s_mov_b32 m0, s22
	s_nop 0
	global_load_lds_dwordx4 v123, s[6:7]
	s_waitcnt vmcnt(8)
	s_waitcnt lgkmcnt(0)
	s_barrier
	s_setprio 1
	s_waitcnt lgkmcnt(0)
	v_mfma_f32_16x16x32_bf16 v[62:65], v[130:133], v[170:173], v[62:65]
	v_mfma_f32_16x16x32_bf16 v[58:61], v[138:141], v[170:173], v[58:61]
	v_mfma_f32_16x16x32_bf16 v[46:49], v[130:133], v[178:181], v[46:49]
	v_mfma_f32_16x16x32_bf16 v[42:45], v[138:141], v[178:181], v[42:45]
	v_mfma_f32_16x16x32_bf16 v[30:33], v[130:133], v[186:189], v[30:33]
	v_mfma_f32_16x16x32_bf16 v[26:29], v[138:141], v[186:189], v[26:29]
	v_mfma_f32_16x16x32_bf16 v[14:17], v[130:133], v[194:197], v[14:17]
	v_mfma_f32_16x16x32_bf16 v[10:13], v[138:141], v[194:197], v[10:13]
	s_setprio 0
	s_setprio 1
	v_mfma_f32_16x16x32_bf16 v[62:65], v[134:137], v[174:177], v[62:65]
	v_mfma_f32_16x16x32_bf16 v[58:61], v[142:145], v[174:177], v[58:61]
	v_mfma_f32_16x16x32_bf16 v[46:49], v[134:137], v[182:185], v[46:49]
	v_mfma_f32_16x16x32_bf16 v[42:45], v[142:145], v[182:185], v[42:45]
	v_mfma_f32_16x16x32_bf16 v[30:33], v[134:137], v[190:193], v[30:33]
	v_mfma_f32_16x16x32_bf16 v[26:29], v[142:145], v[190:193], v[26:29]
	v_mfma_f32_16x16x32_bf16 v[14:17], v[134:137], v[198:201], v[14:17]
	v_mfma_f32_16x16x32_bf16 v[10:13], v[142:145], v[198:201], v[10:13]
	s_setprio 0
	s_setprio 1
	v_mfma_f32_16x16x32_bf16 v[54:57], v[146:149], v[170:173], v[54:57]
	v_mfma_f32_16x16x32_bf16 v[50:53], v[162:165], v[170:173], v[50:53]
	v_mfma_f32_16x16x32_bf16 v[38:41], v[146:149], v[178:181], v[38:41]
	v_mfma_f32_16x16x32_bf16 v[34:37], v[162:165], v[178:181], v[34:37]
	v_mfma_f32_16x16x32_bf16 v[22:25], v[146:149], v[186:189], v[22:25]
	v_mfma_f32_16x16x32_bf16 v[18:21], v[162:165], v[186:189], v[18:21]
	v_mfma_f32_16x16x32_bf16 v[6:9], v[146:149], v[194:197], v[6:9]
	v_mfma_f32_16x16x32_bf16 v[2:5], v[162:165], v[194:197], v[2:5]
	s_setprio 0
	s_setprio 1
	v_mfma_f32_16x16x32_bf16 v[54:57], v[158:161], v[174:177], v[54:57]
	v_mfma_f32_16x16x32_bf16 v[50:53], v[166:169], v[174:177], v[50:53]
	v_mfma_f32_16x16x32_bf16 v[38:41], v[158:161], v[182:185], v[38:41]
	v_mfma_f32_16x16x32_bf16 v[34:37], v[166:169], v[182:185], v[34:37]
	v_mfma_f32_16x16x32_bf16 v[22:25], v[158:161], v[190:193], v[22:25]
	v_mfma_f32_16x16x32_bf16 v[18:21], v[166:169], v[190:193], v[18:21]
	v_mfma_f32_16x16x32_bf16 v[6:9], v[158:161], v[198:201], v[6:9]
	v_mfma_f32_16x16x32_bf16 v[2:5], v[166:169], v[198:201], v[2:5]
	s_setprio 0
	s_barrier
	s_add_i32 s47, 0, 0x18000
	s_add_i32 s50, 0, 0x1c000
	ds_read_b128 v[130:133], v0 offset:32768
	ds_read_b128 v[134:137], v0 offset:33792
	ds_read_b128 v[138:141], v0 offset:34816
	ds_read_b128 v[142:145], v0 offset:35840
	ds_read_b128 v[146:149], v0 offset:49152
	ds_read_b128 v[158:161], v0 offset:50176
	ds_read_b128 v[162:165], v0 offset:51200
	ds_read_b128 v[166:169], v0 offset:52224
	s_add_u32 s48, s6, 0x40000
	s_mov_b32 m0, s23
	ds_read_b128 v[170:173], v128 offset:32768
	ds_read_b128 v[174:177], v128 offset:33792
	ds_read_b128 v[178:181], v128 offset:34816
	ds_read_b128 v[182:185], v128 offset:35840
	ds_read_b128 v[186:189], v128 offset:36864
	ds_read_b128 v[190:193], v128 offset:37888
	ds_read_b128 v[194:197], v128 offset:38912
	ds_read_b128 v[198:201], v128 offset:39936
	s_addc_u32 s49, s7, 0
	s_nop 0
	global_load_lds_dwordx4 v122, s[48:49]
	s_mov_b32 m0, s24
	s_nop 0
	global_load_lds_dwordx4 v123, s[48:49]
	s_waitcnt vmcnt(8)
	s_waitcnt lgkmcnt(0)
	s_barrier
	s_setprio 1
	s_waitcnt lgkmcnt(0)
	v_mfma_f32_16x16x32_bf16 v[154:157], v[130:133], v[170:173], v[154:157]
	v_mfma_f32_16x16x32_bf16 v[150:153], v[138:141], v[170:173], v[150:153]
	v_mfma_f32_16x16x32_bf16 v[110:113], v[130:133], v[178:181], v[110:113]
	v_mfma_f32_16x16x32_bf16 v[106:109], v[138:141], v[178:181], v[106:109]
	v_mfma_f32_16x16x32_bf16 v[94:97], v[130:133], v[186:189], v[94:97]
	v_mfma_f32_16x16x32_bf16 v[90:93], v[138:141], v[186:189], v[90:93]
	v_mfma_f32_16x16x32_bf16 v[78:81], v[130:133], v[194:197], v[78:81]
	v_mfma_f32_16x16x32_bf16 v[74:77], v[138:141], v[194:197], v[74:77]
	s_setprio 0
	s_setprio 1
	v_mfma_f32_16x16x32_bf16 v[154:157], v[134:137], v[174:177], v[154:157]
	v_mfma_f32_16x16x32_bf16 v[150:153], v[142:145], v[174:177], v[150:153]
	v_mfma_f32_16x16x32_bf16 v[110:113], v[134:137], v[182:185], v[110:113]
	v_mfma_f32_16x16x32_bf16 v[106:109], v[142:145], v[182:185], v[106:109]
	v_mfma_f32_16x16x32_bf16 v[94:97], v[134:137], v[190:193], v[94:97]
	v_mfma_f32_16x16x32_bf16 v[90:93], v[142:145], v[190:193], v[90:93]
	v_mfma_f32_16x16x32_bf16 v[78:81], v[134:137], v[198:201], v[78:81]
	v_mfma_f32_16x16x32_bf16 v[74:77], v[142:145], v[198:201], v[74:77]
	s_setprio 0
	s_setprio 1
	v_mfma_f32_16x16x32_bf16 v[118:121], v[146:149], v[170:173], v[118:121]
	v_mfma_f32_16x16x32_bf16 v[114:117], v[162:165], v[170:173], v[114:117]
	v_mfma_f32_16x16x32_bf16 v[102:105], v[146:149], v[178:181], v[102:105]
	v_mfma_f32_16x16x32_bf16 v[98:101], v[162:165], v[178:181], v[98:101]
	v_mfma_f32_16x16x32_bf16 v[86:89], v[146:149], v[186:189], v[86:89]
	v_mfma_f32_16x16x32_bf16 v[82:85], v[162:165], v[186:189], v[82:85]
	v_mfma_f32_16x16x32_bf16 v[70:73], v[146:149], v[194:197], v[70:73]
	v_mfma_f32_16x16x32_bf16 v[66:69], v[162:165], v[194:197], v[66:69]
	s_setprio 0
	s_setprio 1
	v_mfma_f32_16x16x32_bf16 v[118:121], v[158:161], v[174:177], v[118:121]
	v_mfma_f32_16x16x32_bf16 v[114:117], v[166:169], v[174:177], v[114:117]
	v_mfma_f32_16x16x32_bf16 v[102:105], v[158:161], v[182:185], v[102:105]
	v_mfma_f32_16x16x32_bf16 v[98:101], v[166:169], v[182:185], v[98:101]
	v_mfma_f32_16x16x32_bf16 v[86:89], v[158:161], v[190:193], v[86:89]
	v_mfma_f32_16x16x32_bf16 v[82:85], v[166:169], v[190:193], v[82:85]
	v_mfma_f32_16x16x32_bf16 v[70:73], v[158:161], v[198:201], v[70:73]
	v_mfma_f32_16x16x32_bf16 v[66:69], v[166:169], v[198:201], v[66:69]
	s_setprio 0
	s_barrier
	ds_read_b128 v[170:173], v128 offset:49152
	ds_read_b128 v[174:177], v128 offset:50176
	ds_read_b128 v[178:181], v128 offset:51200
	ds_read_b128 v[182:185], v128 offset:52224
	ds_read_b128 v[186:189], v128 offset:53248
	ds_read_b128 v[190:193], v128 offset:54272
	ds_read_b128 v[194:197], v128 offset:55296
	ds_read_b128 v[198:201], v128 offset:56320
	s_add_i32 s47, s47, s16
	s_add_u32 s100, s10, s38
	s_addc_u32 s101, s11, s39
	s_mov_b32 m0, s47
	s_nop 0
	global_load_lds_dwordx4 v125, s[100:101]
	s_add_i32 m0, s47, 0x2000
	s_nop 0
	s_add_u32 s10, s10, 0x40080
	s_addc_u32 s11, s11, 0
	s_add_i32 s47, s50, s16
	global_load_lds_dwordx4 v126, s[100:101]
	s_mov_b32 m0, s47
	s_nop 0
	global_load_lds_dwordx4 v125, s[10:11]
	s_add_i32 m0, s47, 0x2000
	s_nop 0
	global_load_lds_dwordx4 v126, s[10:11]
	s_mov_b32 m0, s41
	s_add_u32 s100, s6, s38
	s_addc_u32 s101, s7, s39
	v_mov_b32_e32 v0, v123
	global_load_lds_dwordx4 v122, s[100:101]
	s_mov_b32 m0, s42
	s_nop 0
	global_load_lds_dwordx4 v123, s[100:101]
	s_waitcnt vmcnt(8)
	s_waitcnt lgkmcnt(0)
	s_barrier
	s_setprio 1
	s_waitcnt lgkmcnt(0)
	v_mfma_f32_16x16x32_bf16 v[62:65], v[130:133], v[170:173], v[62:65]
	v_mfma_f32_16x16x32_bf16 v[58:61], v[138:141], v[170:173], v[58:61]
	v_mfma_f32_16x16x32_bf16 v[46:49], v[130:133], v[178:181], v[46:49]
	v_mfma_f32_16x16x32_bf16 v[42:45], v[138:141], v[178:181], v[42:45]
	v_mfma_f32_16x16x32_bf16 v[30:33], v[130:133], v[186:189], v[30:33]
	v_mfma_f32_16x16x32_bf16 v[26:29], v[138:141], v[186:189], v[26:29]
	v_mfma_f32_16x16x32_bf16 v[14:17], v[130:133], v[194:197], v[14:17]
	v_mfma_f32_16x16x32_bf16 v[10:13], v[138:141], v[194:197], v[10:13]
	s_setprio 0
	s_setprio 1
	v_mfma_f32_16x16x32_bf16 v[62:65], v[134:137], v[174:177], v[62:65]
	v_mfma_f32_16x16x32_bf16 v[58:61], v[142:145], v[174:177], v[58:61]
	v_mfma_f32_16x16x32_bf16 v[46:49], v[134:137], v[182:185], v[46:49]
	v_mfma_f32_16x16x32_bf16 v[42:45], v[142:145], v[182:185], v[42:45]
	v_mfma_f32_16x16x32_bf16 v[30:33], v[134:137], v[190:193], v[30:33]
	v_mfma_f32_16x16x32_bf16 v[26:29], v[142:145], v[190:193], v[26:29]
	v_mfma_f32_16x16x32_bf16 v[14:17], v[134:137], v[198:201], v[14:17]
	v_mfma_f32_16x16x32_bf16 v[10:13], v[142:145], v[198:201], v[10:13]
	s_setprio 0
	s_setprio 1
	v_mfma_f32_16x16x32_bf16 v[54:57], v[146:149], v[170:173], v[54:57]
	v_mfma_f32_16x16x32_bf16 v[50:53], v[162:165], v[170:173], v[50:53]
	v_mfma_f32_16x16x32_bf16 v[38:41], v[146:149], v[178:181], v[38:41]
	v_mfma_f32_16x16x32_bf16 v[34:37], v[162:165], v[178:181], v[34:37]
	v_mfma_f32_16x16x32_bf16 v[22:25], v[146:149], v[186:189], v[22:25]
	v_mfma_f32_16x16x32_bf16 v[18:21], v[162:165], v[186:189], v[18:21]
	v_mfma_f32_16x16x32_bf16 v[6:9], v[146:149], v[194:197], v[6:9]
	v_mfma_f32_16x16x32_bf16 v[2:5], v[162:165], v[194:197], v[2:5]
	s_setprio 0
	s_setprio 1
	v_mfma_f32_16x16x32_bf16 v[54:57], v[158:161], v[174:177], v[54:57]
	v_mfma_f32_16x16x32_bf16 v[50:53], v[166:169], v[174:177], v[50:53]
	v_mfma_f32_16x16x32_bf16 v[38:41], v[158:161], v[182:185], v[38:41]
	v_mfma_f32_16x16x32_bf16 v[34:37], v[166:169], v[182:185], v[34:37]
	v_mfma_f32_16x16x32_bf16 v[22:25], v[158:161], v[190:193], v[22:25]
	v_mfma_f32_16x16x32_bf16 v[18:21], v[166:169], v[190:193], v[18:21]
	v_mfma_f32_16x16x32_bf16 v[6:9], v[158:161], v[198:201], v[6:9]
	v_mfma_f32_16x16x32_bf16 v[2:5], v[166:169], v[198:201], v[2:5]
	s_setprio 0
	s_barrier
	s_add_i32 s46, s46, 2
	s_add_u32 s4, s4, 0x100
	s_addc_u32 s5, s5, 0
	s_add_u32 s37, s37, 0x100
	s_addc_u32 s43, s43, 0
	s_cmp_gt_u32 s46, 13
	s_cbranch_scc0 .LBB0_1886
	s_cmpk_lt_u32 s14, 0x100
	s_cbranch_scc0 .LBB0_1889
	s_barrier
